# mixer phases: f32 division sequences without the two v_div_scale range-rescale steps (operands are in normal range: denominators 1+exp(.), softmax/normaliser sums); same rcp + 3-step fma refinement +
# speedup vs baseline: 1.0065x; 1.0032x over previous
; DI float sigmoidf_(float z) { return 1.f / (1.f + __expf(-z)); }
; DI void rec_setup_lb(const Params& p, int l, int h, unsigned char* smem, int tid) {
;   float* LB = (float*)(smem + L_LB);
;   __syncthreads();
;   if (tid < 64) LB[tid] = (l == 1) ? sigmoidf_(p.hg_lb[256 + h * 64 + tid] - p.hg_lb[h * 64 + tid]) : 0.f;
;   __syncthreads();
; }
.LBB0_509:
	s_and_b64 vcc, exec, s[6:7]
	s_cbranch_vccz .LBB0_566
	v_readlane_b32 s2, v253, 39
	s_waitcnt vmcnt(0)
	v_mbcnt_lo_u32_b32 v68, -1, 0
	v_mbcnt_hi_u32_b32 v68, -1, v68
	s_waitcnt lgkmcnt(0)
	s_barrier
	v_or_b32_e32 v56, s2, v68
	v_cmp_gt_i32_e64 s[4:5], 64, v56
	s_and_saveexec_b64 s[6:7], s[4:5]
	s_cbranch_execz .LBB0_514
	v_readlane_b32 s8, v254, 19
	v_readlane_b32 s9, v254, 20
	v_mov_b32_e32 v0, 0
	s_andn2_b64 vcc, exec, s[8:9]
	s_cbranch_vccnz .LBB0_513
	s_lshl_b32 s2, s50, 6
	v_ashrrev_i32_e32 v57, 31, v56
	v_readlane_b32 s72, v253, 23
	v_lshl_add_u64 v[0:1], s[2:3], 0, v[56:57]
	v_readlane_b32 s78, v253, 29
	v_readlane_b32 s79, v253, 30
	v_readlane_b32 s73, v253, 24
	v_readlane_b32 s72, v254, 15
	v_lshl_add_u64 v[0:1], v[0:1], 2, s[78:79]
	global_load_dword v2, v[0:1], off offset:1024
	v_add_u32_e32 v0, s2, v56
	v_ashrrev_i32_e32 v1, 31, v0
	v_lshl_add_u64 v[0:1], v[0:1], 2, s[78:79]
	global_load_dword v0, v[0:1], off
	v_readlane_b32 s73, v254, 16
	v_readlane_b32 s74, v253, 25
	v_readlane_b32 s75, v253, 26
	v_readlane_b32 s76, v253, 27
	v_readlane_b32 s77, v253, 28
	v_readlane_b32 s80, v253, 31
	v_readlane_b32 s81, v253, 32
	v_readlane_b32 s82, v253, 33
	v_readlane_b32 s83, v253, 34
	v_readlane_b32 s84, v253, 35
	v_readlane_b32 s85, v253, 36
	v_readlane_b32 s86, v253, 37
	v_readlane_b32 s87, v253, 38
	s_waitcnt vmcnt(0)
	v_sub_f32_e32 v0, v2, v0
	v_mul_f32_e32 v0, 0xbfb8aa3b, v0
	v_exp_f32_e32 v0, v0
	s_nop 0
	v_add_f32_e32 v0, 1.0, v0
	v_rcp_f32_e32 v2, v0
	s_nop 0
	v_fma_f32 v3, -v0, v2, 1.0
	v_fmac_f32_e32 v2, v3, v2
	v_mov_b32_e64 v3, 1.0
	v_mul_f32_e32 v4, v3, v2
	v_fma_f32 v5, -v0, v4, v3
	v_fmac_f32_e32 v4, v5, v2
	v_fma_f32 v1, -v0, v4, v3
	v_fma_f32 v1, v1, v2, v4
	v_div_fixup_f32 v0, v1, v0, 1.0

; template <int MX>
; DI RecRaw rec_load(const Params& p, int b, int h, int dir, int T0, int tid) {
;   const bf16_t* P = (const bf16_t*)(p.ws + WS_P);
;   const int tt = tid >> 2, k0 = (tid & 3) * 16;
;   const size_t row = (size_t)b * NTOK + T0 + tt;
;   const bf16_t* rp = P + row * PW;
;   RecRaw w;
;   if (MX == 0) {
;     const int fcol = (dir ? B_FB : B_FF) + h * 64 + k0;
;     w.a0 = *(const uint4*)(rp + fcol); w.a1 = *(const uint4*)(rp + fcol + 8);
;     w.b0 = *(const uint4*)(rp + B_Q + h * 64 + k0); w.b1 = *(const uint4*)(rp + B_Q + h * 64 + k0 + 8);
;     w.c0 = *(const uint4*)(rp + B_I + h * 64 + k0); w.c1 = *(const uint4*)(rp + B_I + h * 64 + k0 + 8);
;     w.ig = 0.f; w.fg = 0.f;
; template <int MX, bool OUT>
; DI void rec_chunk(const Params& p, int l, int b, int h, int dir, int T0, unsigned char* smem, f32x4 (&St)[4], float& nst, float& dtot, int tid, const RecRaw& raw) {
;     ...
;     float lf[16];
;     if (MX == 0) {
; #pragma unroll
;       for (int i = 0; i < 8; ++i) {
; #pragma unroll
;         for (int hh = 0; hh < 2; ++hh) {
;           const int k = 2 * i + hh;
;           float z = __uint_as_float(hh ? (au[i] & 0xffff0000u) : (au[i] << 16));
;           z = fminf(fmaxf(z, -30.f), 30.f);
;           const float e = __expf(-z);
;           const float sg = 1.f / (1.f + e);
;           const float lb = LB[k0 + k];
;           lf[k] = __log2f(lb + (1.f - lb) * sg);
;           kin[k] = (1.f - lb) * (e * sg);
;           qv[k] = __uint_as_float(hh ? (bu[i] & 0xffff0000u) : (bu[i] << 16)) * 0.125f;
;           vv[k] = __uint_as_float(hh ? (cu[i] & 0xffff0000u) : (cu[i] << 16));
;         }
;       }
.LBB0_515:
	s_cmp_eq_u32 s25, -1
	s_cselect_b32 s26, 3, s28
	s_cselect_b32 s27, 0, s25
	s_and_b64 s[22:23], s[0:1], exec
	s_cselect_b32 s22, s26, s27
	s_lshl_b32 s22, s22, 6
	s_add_i32 s22, s22, s24
	s_ashr_i32 s23, s22, 31
	s_waitcnt vmcnt(0) lgkmcnt(0)
	v_mov_b64_e32 v[90:91], v[2:3]
	v_mov_b64_e32 v[92:93], v[0:1]
	v_lshl_add_u64 v[0:1], v[60:61], 0, s[22:23]
	v_mov_b64_e32 v[2:3], s[12:13]
	v_mad_u64_u32 v[20:21], s[22:23], v0, s33, v[2:3]
	v_lshlrev_b32_e32 v0, 16, v92
	v_max_f32_e32 v0, v0, v0
	v_med3_f32 v0, v0, s17, v190
	v_mul_f32_e32 v0, 0xbfb8aa3b, v0
	v_exp_f32_e32 v116, v0
	v_mad_i32_i24 v21, v1, s33, v21
	v_mov_b64_e32 v[66:67], v[4:5]
	v_lshl_add_u64 v[4:5], v[20:21], 0, v[160:161]
	v_add_f32_e32 v40, 1.0, v116
	v_rcp_f32_e32 v42, v40
	v_lshl_add_u64 v[20:21], v[20:21], 0, s[2:3]
	v_mov_b32_e32 v63, v161
	v_lshl_add_u64 v[20:21], v[20:21], 0, v[62:63]
	v_fma_f32 v43, -v40, v42, 1.0
	v_fmac_f32_e32 v42, v43, v42
	v_mov_b32_e64 v43, 1.0
	v_mul_f32_e32 v44, v43, v42
	v_fma_f32 v45, -v40, v44, v43
	v_fmac_f32_e32 v44, v45, v42
	v_fma_f32 v41, -v40, v44, v43
	v_fma_f32 v41, v41, v42, v44
	v_div_fixup_f32 v122, v41, v40, 1.0
	v_and_b32_e32 v40, 0xffff0000, v92
	v_max_f32_e32 v40, v40, v40
	v_med3_f32 v40, v40, s17, v190
	v_mul_f32_e32 v40, 0xbfb8aa3b, v40
	v_exp_f32_e32 v109, v40
	v_mov_b64_e32 v[64:65], v[6:7]
	global_load_dwordx4 v[0:3], v[4:5], off
	s_nop 0
	global_load_dwordx4 v[4:7], v[4:5], off offset:16
	s_nop 0
	global_load_dwordx4 v[24:27], v[20:21], off offset:3072
	s_nop 0
	global_load_dwordx4 v[20:23], v[20:21], off offset:3088
	v_add_f32_e32 v63, 1.0, v109
	v_rcp_f32_e32 v94, v63
	ds_read_b128 v[44:47], v69
	ds_read_b128 v[52:55], v69 offset:16
	ds_read_b128 v[48:51], v69 offset:32
	ds_read_b128 v[40:43], v69 offset:48
	s_waitcnt lgkmcnt(0)
	v_sub_f32_e32 v125, 1.0, v44
	v_fma_f32 v95, -v63, v94, 1.0
	v_fmac_f32_e32 v94, v95, v94
	v_mov_b32_e64 v95, 1.0
	v_mul_f32_e32 v96, v95, v94
	v_fma_f32 v97, -v63, v96, v95
	v_fmac_f32_e32 v96, v97, v94
	v_fma_f32 v92, -v63, v96, v95
	v_lshlrev_b32_e32 v95, 16, v93
	v_max_f32_e32 v95, v95, v95
	v_med3_f32 v95, v95, s17, v190
	v_mul_f32_e32 v95, 0xbfb8aa3b, v95
	v_exp_f32_e32 v117, v95
	v_fma_f32 v92, v92, v94, v96
	v_div_fixup_f32 v118, v92, v63, 1.0
	v_and_b32_e32 v93, 0xffff0000, v93
	v_add_f32_e32 v63, 1.0, v117
	v_rcp_f32_e32 v94, v63
	v_max_f32_e32 v93, v93, v93
	v_med3_f32 v93, v93, s17, v190
	v_mul_f32_e32 v93, 0xbfb8aa3b, v93
	v_fma_f32 v95, -v63, v94, 1.0
	v_fmac_f32_e32 v94, v95, v94
	v_mov_b32_e64 v95, 1.0
	v_mul_f32_e32 v96, v95, v94
	v_fma_f32 v97, -v63, v96, v95
	v_exp_f32_e32 v103, v93
	v_fmac_f32_e32 v96, v97, v94
	v_fma_f32 v92, -v63, v96, v95
	v_fma_f32 v92, v92, v94, v96
	v_div_fixup_f32 v124, v92, v63, 1.0
	v_add_f32_e32 v63, 1.0, v103
	v_rcp_f32_e32 v93, v63
	v_sub_f32_e32 v107, 1.0, v48
	v_sub_f32_e32 v101, 1.0, v50
	v_sub_f32_e32 v120, 1.0, v45
	v_fma_f32 v94, -v63, v93, 1.0
	v_fmac_f32_e32 v93, v94, v93
	v_mov_b32_e64 v94, 1.0
	v_mul_f32_e32 v95, v94, v93
	v_fma_f32 v96, -v63, v95, v94
	v_fmac_f32_e32 v95, v96, v93
	v_fma_f32 v92, -v63, v95, v94
	v_lshlrev_b32_e32 v94, 16, v90
	v_max_f32_e32 v94, v94, v94
	v_med3_f32 v94, v94, s17, v190
	v_mul_f32_e32 v94, 0xbfb8aa3b, v94
	v_exp_f32_e32 v111, v94
	v_fma_f32 v92, v92, v93, v95
	v_div_fixup_f32 v112, v92, v63, 1.0
	v_and_b32_e32 v90, 0xffff0000, v90
	v_add_f32_e32 v63, 1.0, v111
	v_rcp_f32_e32 v93, v63
	v_max_f32_e32 v90, v90, v90
	v_med3_f32 v90, v90, s17, v190
	v_mul_f32_e32 v90, 0xbfb8aa3b, v90
	v_fma_f32 v94, -v63, v93, 1.0
	v_fmac_f32_e32 v93, v94, v93
	v_mov_b32_e64 v94, 1.0
	v_mul_f32_e32 v95, v94, v93
	v_fma_f32 v96, -v63, v95, v94
	v_exp_f32_e32 v97, v90
	v_fmac_f32_e32 v95, v96, v93
	v_fma_f32 v92, -v63, v95, v94
	v_fma_f32 v90, v92, v93, v95
	v_div_fixup_f32 v121, v90, v63, 1.0
	v_add_f32_e32 v63, 1.0, v97
	v_rcp_f32_e32 v92, v63
	v_sub_f32_e32 v96, 1.0, v49
	v_sub_f32_e32 v123, 1.0, v46
	v_sub_f32_e32 v114, 1.0, v47
	v_fma_f32 v93, -v63, v92, 1.0
	v_fmac_f32_e32 v92, v93, v92
	v_mov_b32_e64 v93, 1.0
	v_mul_f32_e32 v94, v93, v92
	v_fma_f32 v95, -v63, v94, v93
	v_fmac_f32_e32 v94, v95, v92
	v_fma_f32 v90, -v63, v94, v93
	v_lshlrev_b32_e32 v93, 16, v91
	v_max_f32_e32 v93, v93, v93
	v_med3_f32 v93, v93, s17, v190
	v_mul_f32_e32 v93, 0xbfb8aa3b, v93
	v_exp_f32_e32 v105, v93
	v_fma_f32 v90, v90, v92, v94
	v_div_fixup_f32 v106, v90, v63, 1.0
	v_and_b32_e32 v91, 0xffff0000, v91
	v_add_f32_e32 v63, 1.0, v105
	v_rcp_f32_e32 v93, v63
	v_max_f32_e32 v91, v91, v91
	v_med3_f32 v91, v91, s17, v190
	v_mul_f32_e32 v91, 0xbfb8aa3b, v91
	v_fma_f32 v92, -v63, v93, 1.0
	v_fmac_f32_e32 v93, v92, v93
	v_mov_b32_e64 v92, 1.0
	v_mul_f32_e32 v94, v92, v93
	v_fma_f32 v95, -v63, v94, v92
	v_fmac_f32_e32 v94, v95, v93
	v_fma_f32 v90, -v63, v94, v92
	v_exp_f32_e32 v92, v91
	v_fma_f32 v90, v90, v93, v94
	v_div_fixup_f32 v115, v90, v63, 1.0
	v_fma_f32 v44, v122, v125, v44
	v_add_f32_e32 v63, 1.0, v92
	v_rcp_f32_e32 v91, v63
	v_fma_f32 v45, v118, v120, v45
	v_fma_f32 v46, v124, v123, v46
	v_fmac_f32_e32 v47, v112, v114
	v_fma_f32 v93, -v63, v91, 1.0
	v_fmac_f32_e32 v91, v93, v91
	v_mov_b32_e64 v93, 1.0
	v_mul_f32_e32 v94, v93, v91
	v_fma_f32 v95, -v63, v94, v93
	v_fmac_f32_e32 v94, v95, v91
	v_fma_f32 v90, -v63, v94, v93
	v_lshlrev_b32_e32 v93, 16, v66
	v_max_f32_e32 v93, v93, v93
	v_med3_f32 v93, v93, s17, v190
	v_mul_f32_e32 v93, 0xbfb8aa3b, v93
	v_exp_f32_e32 v99, v93
	v_fma_f32 v90, v90, v91, v94
	v_div_fixup_f32 v100, v90, v63, 1.0
	v_and_b32_e32 v66, 0xffff0000, v66
	v_add_f32_e32 v63, 1.0, v99
	v_rcp_f32_e32 v91, v63
	v_max_f32_e32 v66, v66, v66
	v_med3_f32 v66, v66, s17, v190
	v_mul_f32_e32 v66, 0xbfb8aa3b, v66
; template <int MX, bool OUT>
; DI void rec_chunk(const Params& p, int l, int b, int h, int dir, int T0, unsigned char* smem, f32x4 (&St)[4], float& nst, float& dtot, int tid, const RecRaw& raw) {
;     ...
;     float lf[16];
;     if (MX == 0) {
; #pragma unroll
;       for (int i = 0; i < 8; ++i) {
; #pragma unroll
;         for (int hh = 0; hh < 2; ++hh) {
;           const int k = 2 * i + hh;
;           float z = __uint_as_float(hh ? (au[i] & 0xffff0000u) : (au[i] << 16));
;           z = fminf(fmaxf(z, -30.f), 30.f);
;           const float e = __expf(-z);
;           const float sg = 1.f / (1.f + e);
;           const float lb = LB[k0 + k];
;           lf[k] = __log2f(lb + (1.f - lb) * sg);
;           kin[k] = (1.f - lb) * (e * sg);
;           qv[k] = __uint_as_float(hh ? (bu[i] & 0xffff0000u) : (bu[i] << 16)) * 0.125f;
;           vv[k] = __uint_as_float(hh ? (cu[i] & 0xffff0000u) : (cu[i] << 16));
;         }
;       }
;     ...
;   } else {
;     const int k = tid & 63, part = tid >> 6;
;     float x[16];
;     float acc = 0.f;
;     if (dir == 0) {
; #pragma unroll
;       for (int i = 0; i < 16; ++i) { acc += CUM[(part * 16 + i) * 64 + k]; x[i] = acc; }
;     } else {
; #pragma unroll
;       for (int i = 15; i >= 0; --i) { acc += CUM[(part * 16 + i) * 64 + k]; x[i] = acc; }
;     }
;     TOT[part * 64 + k] = acc;
	v_fma_f32 v93, -v63, v91, 1.0
	v_fmac_f32_e32 v91, v93, v91
	v_mov_b32_e64 v93, 1.0
	v_mul_f32_e32 v94, v93, v91
	v_fma_f32 v95, -v63, v94, v93
	v_exp_f32_e32 v66, v66
	v_fmac_f32_e32 v94, v95, v91
	v_fma_f32 v90, -v63, v94, v93
	v_fma_f32 v90, v90, v91, v94
	v_div_fixup_f32 v110, v90, v63, 1.0
	v_add_f32_e32 v63, 1.0, v66
	v_rcp_f32_e32 v91, v63
	v_fma_f32 v48, v110, v107, v48
	v_log_f32_e32 v126, v48
	v_sub_f32_e32 v119, 1.0, v52
	v_fma_f32 v48, -v63, v91, 1.0
	v_fmac_f32_e32 v91, v48, v91
	v_mov_b32_e64 v48, 1.0
	v_mul_f32_e32 v94, v48, v91
	v_fma_f32 v93, -v63, v94, v48
	v_fmac_f32_e32 v94, v93, v91
	v_fma_f32 v48, -v63, v94, v48
	v_lshlrev_b32_e32 v90, 16, v67
	v_max_f32_e32 v90, v90, v90
	v_med3_f32 v90, v90, s17, v190
	v_mul_f32_e32 v90, 0xbfb8aa3b, v90
	v_exp_f32_e32 v93, v90
	v_fma_f32 v48, v48, v91, v94
	v_div_fixup_f32 v94, v48, v63, 1.0
	v_fma_f32 v49, v94, v96, v49
	v_add_f32_e32 v48, 1.0, v93
	v_rcp_f32_e32 v90, v48
	v_log_f32_e32 v127, v49
	v_sub_f32_e32 v108, 1.0, v53
	v_sub_f32_e32 v113, 1.0, v54
	v_fma_f32 v49, -v48, v90, 1.0
	v_fmac_f32_e32 v90, v49, v90
	v_mov_b32_e64 v49, 1.0
	v_mul_f32_e32 v91, v49, v90
	v_fma_f32 v95, -v48, v91, v49
	v_fmac_f32_e32 v91, v95, v90
	v_fma_f32 v63, -v48, v91, v49
	v_and_b32_e32 v49, 0xffff0000, v67
	v_max_f32_e32 v49, v49, v49
	v_med3_f32 v49, v49, s17, v190
	v_mul_f32_e32 v49, 0xbfb8aa3b, v49
	v_exp_f32_e32 v49, v49
	v_fma_f32 v63, v63, v90, v91
	v_div_fixup_f32 v104, v63, v48, 1.0
	v_fma_f32 v50, v104, v101, v50
	v_add_f32_e32 v48, 1.0, v49
	v_rcp_f32_e32 v90, v48
	v_log_f32_e32 v128, v50
	v_sub_f32_e32 v102, 1.0, v55
	v_log_f32_e32 v44, v44
	v_fma_f32 v50, -v48, v90, 1.0
	v_fmac_f32_e32 v90, v50, v90
	v_mov_b32_e64 v50, 1.0
	v_mul_f32_e32 v91, v50, v90
	v_fma_f32 v67, -v48, v91, v50
	v_fmac_f32_e32 v91, v67, v90
	v_fma_f32 v50, -v48, v91, v50
	v_lshlrev_b32_e32 v63, 16, v64
	v_max_f32_e32 v63, v63, v63
	v_med3_f32 v63, v63, s17, v190
	v_mul_f32_e32 v63, 0xbfb8aa3b, v63
	v_exp_f32_e32 v67, v63
	v_fma_f32 v50, v50, v90, v91
	v_div_fixup_f32 v90, v50, v48, 1.0
	v_sub_f32_e32 v91, 1.0, v51
	v_add_f32_e32 v50, 1.0, v67
	v_rcp_f32_e32 v63, v50
	v_fmac_f32_e32 v51, v90, v91
	v_log_f32_e32 v129, v51
	v_log_f32_e32 v45, v45
	v_fma_f32 v51, -v50, v63, 1.0
	v_fmac_f32_e32 v63, v51, v63
	v_mov_b32_e64 v51, 1.0
	v_mul_f32_e32 v95, v51, v63
	v_fma_f32 v98, -v50, v95, v51
	v_fmac_f32_e32 v95, v98, v63
	v_fma_f32 v51, -v50, v95, v51
	v_and_b32_e32 v48, 0xffff0000, v64
	v_max_f32_e32 v48, v48, v48
	v_med3_f32 v48, v48, s17, v190
	v_mul_f32_e32 v48, 0xbfb8aa3b, v48
	v_exp_f32_e32 v48, v48
	v_fma_f32 v51, v51, v63, v95
	v_div_fixup_f32 v98, v51, v50, 1.0
	v_sub_f32_e32 v95, 1.0, v40
	v_add_f32_e32 v51, 1.0, v48
	v_rcp_f32_e32 v63, v51
	v_fma_f32 v40, v98, v95, v40
	v_log_f32_e32 v130, v40
	v_log_f32_e32 v46, v46
	v_fma_f32 v40, -v51, v63, 1.0
	v_fmac_f32_e32 v63, v40, v63
	v_mov_b32_e64 v40, 1.0
	v_mul_f32_e32 v64, v40, v63
	v_fma_f32 v131, -v51, v64, v40
	v_fmac_f32_e32 v64, v131, v63
	v_fma_f32 v40, -v51, v64, v40
	v_lshlrev_b32_e32 v50, 16, v65
	v_max_f32_e32 v50, v50, v50
	v_med3_f32 v50, v50, s17, v190
	v_mul_f32_e32 v50, 0xbfb8aa3b, v50
	v_exp_f32_e32 v50, v50
	v_fma_f32 v40, v40, v63, v64
	v_div_fixup_f32 v51, v40, v51, 1.0
	v_sub_f32_e32 v63, 1.0, v41
	v_add_f32_e32 v64, 1.0, v50
	v_rcp_f32_e32 v132, v64
	v_fma_f32 v41, v51, v63, v41
	v_log_f32_e32 v131, v41
	v_log_f32_e32 v47, v47
	v_fma_f32 v41, -v64, v132, 1.0
	v_fmac_f32_e32 v132, v41, v132
	v_mov_b32_e64 v41, 1.0
	v_mul_f32_e32 v133, v41, v132
	v_fma_f32 v134, -v64, v133, v41
	v_fmac_f32_e32 v133, v134, v132
	v_fma_f32 v41, -v64, v133, v41
	v_and_b32_e32 v40, 0xffff0000, v65
	v_max_f32_e32 v40, v40, v40
	v_med3_f32 v40, v40, s17, v190
	v_mul_f32_e32 v40, 0xbfb8aa3b, v40
	v_exp_f32_e32 v40, v40
	v_fma_f32 v41, v41, v132, v133
	v_div_fixup_f32 v65, v41, v64, 1.0
	v_sub_f32_e32 v64, 1.0, v42
	v_add_f32_e32 v41, 1.0, v40
	v_rcp_f32_e32 v134, v41
	v_fma_f32 v42, v65, v64, v42
	v_log_f32_e32 v132, v42
	v_fma_f32 v52, v121, v119, v52
	v_fma_f32 v42, -v41, v134, 1.0
	v_fmac_f32_e32 v134, v42, v134
	v_mov_b32_e64 v42, 1.0
	v_mul_f32_e32 v135, v42, v134
	v_fma_f32 v136, -v41, v135, v42
	v_fmac_f32_e32 v135, v136, v134
	v_fma_f32 v42, -v41, v135, v42
	v_fma_f32 v53, v106, v108, v53
	v_fma_f32 v54, v115, v113, v54
	v_fmac_f32_e32 v55, v100, v102
	v_fma_f32 v42, v42, v134, v135
	v_log_f32_e32 v52, v52
	v_log_f32_e32 v53, v53
	v_log_f32_e32 v54, v54
	v_log_f32_e32 v55, v55
	v_div_fixup_f32 v41, v42, v41, 1.0
	v_sub_f32_e32 v42, 1.0, v43
	v_fmac_f32_e32 v43, v41, v42
	v_log_f32_e32 v133, v43
	s_andn2_b64 vcc, exec, s[20:21]
	s_mov_b64 s[22:23], -1
	ds_write_b128 v70, v[44:47]
	ds_write_b128 v70, v[52:55] offset:16
	ds_write_b128 v70, v[126:129] offset:32
	ds_write_b128 v70, v[130:133] offset:48
	s_waitcnt lgkmcnt(0)
	s_barrier
	s_cbranch_vccnz .LBB0_517
	ds_read2st64_b32 v[44:45], v71 offset0:14 offset1:15
	s_mov_b64 s[22:23], 0
	ds_read2st64_b32 v[126:127], v71 offset0:6 offset1:7
	ds_read2st64_b32 v[132:133], v71 offset0:2 offset1:3
	s_waitcnt lgkmcnt(0)
	v_add_f32_e32 v129, 0, v45
	v_add_f32_e32 v130, v129, v44
	ds_read2st64_b32 v[44:45], v71 offset0:12 offset1:13
	s_waitcnt lgkmcnt(0)
	v_add_f32_e32 v47, v130, v45
	v_add_f32_e32 v52, v47, v44
	ds_read2st64_b32 v[44:45], v71 offset0:10 offset1:11
	s_waitcnt lgkmcnt(0)
	v_add_f32_e32 v53, v52, v45
	v_add_f32_e32 v54, v53, v44
	ds_read2st64_b32 v[44:45], v71 offset0:8 offset1:9
	s_waitcnt lgkmcnt(0)
	v_add_f32_e32 v43, v54, v45
	v_add_f32_e32 v44, v43, v44
	v_add_f32_e32 v45, v44, v127
	v_add_f32_e32 v46, v45, v126
	ds_read2st64_b32 v[126:127], v71 offset0:4 offset1:5
	s_waitcnt lgkmcnt(0)
	v_add_f32_e32 v55, v46, v127
	v_add_f32_e32 v126, v55, v126
	v_add_f32_e32 v127, v126, v133
	v_add_f32_e32 v128, v127, v132
	ds_read2st64_b32 v[132:133], v71 offset1:1
	s_waitcnt lgkmcnt(0)
	v_add_f32_e32 v131, v128, v133
	v_add_f32_e32 v132, v131, v132

; template <int MODE>
; DI void attn_mfma(const Params& p, int l, int b, int hd, int qb, unsigned char* smem) {
;     ...
;   const float ltot = lsum + __shfl_xor(lsum, 32);
;   if (MODE == 0) {
;     const float lam_init = 0.8f - 0.6f * __expf(-0.3f * (float)l);
;     float s01 = 0.f, s23 = 0.f;
;     for (int i = 0; i < 32; ++i) {
;       s01 += p.diff_lam[l * 128 + i] * p.diff_lam[l * 128 + 32 + i];
;       s23 += p.diff_lam[l * 128 + 64 + i] * p.diff_lam[l * 128 + 96 + i];
;     }
;     const float lam = expf(s01) - expf(s23) + lam_init;
;     float* sO = (float*)smem;
;     const int ql = (wv & 1) * 32 + r;
;     __syncthreads();
;     if (mp == 1) {
;       const float i1 = lam / ltot;
; #pragma unroll
.LBB0_586:
	v_readlane_b32 s0, v254, 25
	v_readlane_b32 s1, v254, 26
	s_nop 4
	global_load_dwordx4 v[44:47], v161, s[0:1] offset:48
	global_load_dwordx4 v[64:67], v161, s[0:1] offset:32
	global_load_dwordx4 v[80:83], v161, s[0:1] offset:16
	global_load_dwordx4 v[88:91], v161, s[0:1]
	global_load_dwordx4 v[56:59], v161, s[0:1] offset:176
	global_load_dwordx4 v[72:75], v161, s[0:1] offset:160
	global_load_dwordx4 v[84:87], v161, s[0:1] offset:144
	global_load_dwordx4 v[92:95], v161, s[0:1] offset:128
	global_load_dwordx4 v[108:111], v161, s[0:1] offset:304
	global_load_dwordx4 v[128:131], v161, s[0:1] offset:288
	global_load_dwordx4 v[144:147], v161, s[0:1] offset:272
	global_load_dwordx4 v[152:155], v161, s[0:1] offset:256
	global_load_dwordx4 v[120:123], v161, s[0:1] offset:432
	global_load_dwordx4 v[136:139], v161, s[0:1] offset:416
	global_load_dwordx4 v[148:151], v161, s[0:1] offset:400
	global_load_dwordx4 v[156:159], v161, s[0:1] offset:384
	global_load_dwordx4 v[32:35], v161, s[0:1] offset:112
	global_load_dwordx4 v[40:43], v161, s[0:1] offset:96
	global_load_dwordx4 v[52:55], v161, s[0:1] offset:80
	global_load_dwordx4 v[68:71], v161, s[0:1] offset:64
	global_load_dwordx4 v[36:39], v161, s[0:1] offset:240
	global_load_dwordx4 v[48:51], v161, s[0:1] offset:224
	global_load_dwordx4 v[60:63], v161, s[0:1] offset:208
	global_load_dwordx4 v[76:79], v161, s[0:1] offset:192
	global_load_dwordx4 v[96:99], v161, s[0:1] offset:368
	global_load_dwordx4 v[104:107], v161, s[0:1] offset:352
	global_load_dwordx4 v[116:119], v161, s[0:1] offset:336
	global_load_dwordx4 v[132:135], v161, s[0:1] offset:320
	global_load_dwordx4 v[100:103], v161, s[0:1] offset:496
	global_load_dwordx4 v[112:115], v161, s[0:1] offset:480
	global_load_dwordx4 v[124:127], v161, s[0:1] offset:464
	global_load_dwordx4 v[140:143], v161, s[0:1] offset:448
	ds_bpermute_b32 v160, v170, v200
	v_or_b32_e32 v198, v199, v198
	v_lshlrev_b32_e32 v171, 4, v171
	s_movk_i32 s0, 0x104
	v_cmp_eq_u32_e32 vcc, 1, v197
	s_waitcnt lgkmcnt(0)
	v_add_f32_e32 v160, v200, v160
	v_mad_u32_u24 v197, v198, s0, v171
	s_barrier
	s_and_saveexec_b64 s[0:1], vcc
	s_cbranch_execz .LBB0_588
	s_waitcnt vmcnt(0)
	v_fma_f32 v152, v152, v156, 0
	v_fmac_f32_e32 v152, v153, v157
	v_fmac_f32_e32 v152, v154, v158
	v_fmac_f32_e32 v152, v155, v159
	v_fma_f32 v88, v88, v92, 0
	v_fmac_f32_e32 v152, v144, v148
	v_fmac_f32_e32 v88, v89, v93
	v_fmac_f32_e32 v152, v145, v149
	v_fmac_f32_e32 v88, v90, v94
	v_fmac_f32_e32 v152, v146, v150
	v_fmac_f32_e32 v88, v91, v95
	v_fmac_f32_e32 v152, v147, v151
	v_fmac_f32_e32 v88, v80, v84
	v_fmac_f32_e32 v152, v128, v136
	v_fmac_f32_e32 v88, v81, v85
	v_fmac_f32_e32 v152, v129, v137
	v_fmac_f32_e32 v88, v82, v86
	v_fmac_f32_e32 v152, v130, v138
	v_fmac_f32_e32 v88, v83, v87
	v_fmac_f32_e32 v152, v131, v139
	v_fmac_f32_e32 v88, v64, v72
	v_fmac_f32_e32 v152, v108, v120
	v_fmac_f32_e32 v88, v65, v73
	v_fmac_f32_e32 v152, v109, v121
	v_fmac_f32_e32 v88, v66, v74
	v_fmac_f32_e32 v152, v110, v122
	v_fmac_f32_e32 v88, v67, v75
	v_fmac_f32_e32 v152, v111, v123
	v_fmac_f32_e32 v88, v44, v56
	v_fmac_f32_e32 v152, v132, v140
	v_fmac_f32_e32 v88, v45, v57
	v_fmac_f32_e32 v152, v133, v141
	v_fmac_f32_e32 v88, v46, v58
	v_fmac_f32_e32 v152, v134, v142
	v_fmac_f32_e32 v88, v47, v59
	v_fmac_f32_e32 v152, v135, v143
	v_fmac_f32_e32 v88, v68, v76
	v_fmac_f32_e32 v152, v116, v124
	v_fmac_f32_e32 v88, v69, v77
	v_fmac_f32_e32 v152, v117, v125
	v_fmac_f32_e32 v88, v70, v78
	v_fmac_f32_e32 v152, v118, v126
	v_fmac_f32_e32 v88, v71, v79
	v_fmac_f32_e32 v152, v119, v127
	v_pk_mul_f32 v[104:105], v[104:105], v[112:113]
	v_fmac_f32_e32 v88, v52, v60
	v_add_f32_e32 v104, v152, v104
	v_fmac_f32_e32 v88, v53, v61
	v_add_f32_e32 v108, v104, v105
	v_pk_mul_f32 v[104:105], v[106:107], v[114:115]
	v_fmac_f32_e32 v88, v54, v62
	v_add_f32_e32 v104, v108, v104
	v_fmac_f32_e32 v88, v55, v63
	v_pk_mul_f32 v[40:41], v[40:41], v[48:49]
	v_add_f32_e32 v104, v104, v105
	v_pk_mul_f32 v[96:97], v[96:97], v[100:101]
	v_add_f32_e32 v40, v88, v40
	v_add_f32_e32 v96, v104, v96
	v_add_f32_e32 v44, v40, v41
	v_pk_mul_f32 v[40:41], v[42:43], v[50:51]
	v_add_f32_e32 v100, v96, v97
	v_pk_mul_f32 v[96:97], v[98:99], v[102:103]
	v_add_f32_e32 v40, v44, v40
	v_add_f32_e32 v96, v100, v96
	v_add_f32_e32 v40, v40, v41
	v_pk_mul_f32 v[32:33], v[32:33], v[36:37]
	v_add_f32_e32 v96, v96, v97
	v_add_f32_e32 v32, v40, v32
	v_add_f32_e32 v36, v32, v33
	v_mul_f32_e32 v32, 0x3fb8aa3b, v96
	s_mov_b32 s2, 0x3fb8aa3b
	v_fma_f32 v33, v96, s2, -v32
	v_rndne_f32_e32 v37, v32
	v_fmac_f32_e32 v33, 0x32a5705f, v96
	v_sub_f32_e32 v32, v32, v37
	v_add_f32_e32 v32, v32, v33
	v_exp_f32_e32 v40, v32
	v_pk_mul_f32 v[32:33], v[34:35], v[38:39]
	v_cvt_i32_f32_e32 v37, v37
	v_add_f32_e32 v32, v36, v32
	v_add_f32_e32 v32, v32, v33
	v_mul_f32_e32 v34, 0x3fb8aa3b, v32
	v_fma_f32 v35, v32, s2, -v34
	v_rndne_f32_e32 v36, v34
	v_fmac_f32_e32 v35, 0x32a5705f, v32
	v_sub_f32_e32 v34, v34, v36
	v_add_f32_e32 v34, v34, v35
	v_exp_f32_e32 v34, v34
	v_cvt_i32_f32_e32 v35, v36
	s_mov_b32 s2, 0xc2ce8ed0
	v_ldexp_f32 v33, v40, v37
	v_cmp_ngt_f32_e32 vcc, s2, v96
	s_mov_b32 s4, 0x42b17218
	v_ldexp_f32 v34, v34, v35
	v_cndmask_b32_e32 v33, 0, v33, vcc
	v_cmp_nlt_f32_e32 vcc, s4, v96
	s_nop 1
	v_cndmask_b32_e32 v33, v191, v33, vcc
	v_cmp_ngt_f32_e32 vcc, s2, v32
	s_nop 1
	v_cndmask_b32_e32 v34, 0, v34, vcc
	v_cmp_nlt_f32_e32 vcc, s4, v32
	s_nop 1
	v_cndmask_b32_e32 v32, v191, v34, vcc
	v_sub_f32_e32 v32, v32, v33
	v_add_f32_e32 v32, v168, v32
	v_rcp_f32_e32 v34, v160
	s_nop 0
	v_fma_f32 v35, -v160, v34, 1.0
	v_fmac_f32_e32 v34, v35, v34
	v_mul_f32_e32 v36, v32, v34
; DI int crow(int reg, int h) { return (reg & 3) + 8 * (reg >> 2) + 4 * h; }
; template <int MODE>
; DI void attn_mfma(const Params& p, int l, int b, int hd, int qb, unsigned char* smem) {
;     ...
;     if (mp == 1) {
;       const float i1 = lam / ltot;
; #pragma unroll
;       for (int vt = 0; vt < 2; ++vt)
; #pragma unroll
;         for (int i = 0; i < 16; ++i) sO[ql * 65 + vt * 32 + crow(i, h2)] = O[vt][i] * i1;
;     }
;     __syncthreads();
;     if (mp == 0) {
;       const float i0 = 1.f / ltot;
;       float ss = 0.f;
; #pragma unroll
;       for (int vt = 0; vt < 2; ++vt)
; #pragma unroll
;         for (int i = 0; i < 16; ++i) { const float o = O[vt][i] * i0 - sO[ql * 65 + vt * 32 + crow(i, h2)]; O[vt][i] = o; ss += o * o; }
;       ss += __shfl_xor(ss, 32);
;       const float rstd = rsqrtf(ss * (1.f / 64.f) + EPS) * (1.f - lam_init);
; #pragma unroll
;       for (int vt = 0; vt < 2; ++vt)
; #pragma unroll
;         for (int g4 = 0; g4 < 4; ++g4) {
;           const int v0 = vt * 32 + 8 * g4 + 4 * h2;
;           const ushort4 gt = *(const ushort4*)(P + qrow * PW + GATE + hd * 64 + v0);
;           const float4 gg = *(const float4*)(p.diff_g + l * 64 + v0);
	v_fma_f32 v37, -v160, v36, v32
	v_fmac_f32_e32 v36, v37, v34
	v_fma_f32 v33, -v160, v36, v32
	v_fma_f32 v33, v33, v34, v36
	v_div_fixup_f32 v32, v33, v160, v32
	v_pk_mul_f32 v[34:35], v[16:17], v[32:33] op_sel_hi:[1,0]
	ds_write2_b32 v197, v34, v35 offset1:1
	v_pk_mul_f32 v[34:35], v[18:19], v[32:33] op_sel_hi:[1,0]
	ds_write2_b32 v197, v34, v35 offset0:2 offset1:3
	v_pk_mul_f32 v[34:35], v[20:21], v[32:33] op_sel_hi:[1,0]
	ds_write2_b32 v197, v34, v35 offset0:8 offset1:9
	v_pk_mul_f32 v[34:35], v[22:23], v[32:33] op_sel_hi:[1,0]
	ds_write2_b32 v197, v34, v35 offset0:10 offset1:11
	v_pk_mul_f32 v[34:35], v[24:25], v[32:33] op_sel_hi:[1,0]
	ds_write2_b32 v197, v34, v35 offset0:16 offset1:17
	v_pk_mul_f32 v[34:35], v[26:27], v[32:33] op_sel_hi:[1,0]
	ds_write2_b32 v197, v34, v35 offset0:18 offset1:19
	v_pk_mul_f32 v[34:35], v[28:29], v[32:33] op_sel_hi:[1,0]
	ds_write2_b32 v197, v34, v35 offset0:24 offset1:25
	v_pk_mul_f32 v[34:35], v[30:31], v[32:33] op_sel_hi:[1,0]
	ds_write2_b32 v197, v34, v35 offset0:26 offset1:27
	v_pk_mul_f32 v[34:35], v[0:1], v[32:33] op_sel_hi:[1,0]
	ds_write2_b32 v197, v34, v35 offset0:32 offset1:33
	v_pk_mul_f32 v[34:35], v[2:3], v[32:33] op_sel_hi:[1,0]
	ds_write2_b32 v197, v34, v35 offset0:34 offset1:35
	v_pk_mul_f32 v[34:35], v[4:5], v[32:33] op_sel_hi:[1,0]
	ds_write2_b32 v197, v34, v35 offset0:40 offset1:41
	v_pk_mul_f32 v[34:35], v[6:7], v[32:33] op_sel_hi:[1,0]
	ds_write2_b32 v197, v34, v35 offset0:42 offset1:43
	v_pk_mul_f32 v[34:35], v[8:9], v[32:33] op_sel_hi:[1,0]
	ds_write2_b32 v197, v34, v35 offset0:48 offset1:49
	v_pk_mul_f32 v[34:35], v[10:11], v[32:33] op_sel_hi:[1,0]
	ds_write2_b32 v197, v34, v35 offset0:50 offset1:51
	v_pk_mul_f32 v[34:35], v[12:13], v[32:33] op_sel_hi:[1,0]
	v_pk_mul_f32 v[32:33], v[14:15], v[32:33] op_sel_hi:[1,0]
	ds_write2_b32 v197, v34, v35 offset0:56 offset1:57
	ds_write2_b32 v197, v32, v33 offset0:58 offset1:59
.LBB0_588:
	s_or_b64 exec, exec, s[0:1]
	s_movk_i32 s0, 0x80
	v_cmp_gt_u32_e32 vcc, s0, v196
	s_waitcnt lgkmcnt(0)
	s_barrier
	s_and_saveexec_b64 s[0:1], vcc
	s_xor_b64 s[0:1], exec, s[0:1]
	s_cbranch_execz .LBB0_590
	s_waitcnt vmcnt(0)
	v_rcp_f32_e32 v33, v160
	s_add_u32 s4, s40, 0x1dc6000
	s_addc_u32 s5, s41, 0
	s_lshl_b32 s2, s7, 1
	v_fma_f32 v34, -v160, v33, 1.0
	v_fmac_f32_e32 v33, v34, v33
	v_mov_b32_e64 v34, 1.0
	v_mul_f32_e32 v35, v34, v33
	v_fma_f32 v36, -v160, v35, v34
	v_fmac_f32_e32 v35, v36, v33
	v_fma_f32 v32, -v160, v35, v34
	v_fma_f32 v32, v32, v33, v35
	v_div_fixup_f32 v44, v32, v160, 1.0
	ds_read2_b32 v[32:33], v197 offset0:56 offset1:57
	s_mul_i32 s6, s6, 0x9000
	v_add_lshl_u32 v160, v165, s6, 6
	v_mov_b32_e32 v165, v161
	s_mov_b64 s[6:7], 0x1a20
	s_waitcnt lgkmcnt(0)
	v_pk_fma_f32 v[34:35], v[12:13], v[44:45], v[32:33] op_sel_hi:[1,0,1] neg_lo:[0,0,1] neg_hi:[0,0,1]
	ds_read2_b32 v[12:13], v197 offset0:58 offset1:59
	ds_read2_b32 v[82:83], v197 offset0:48 offset1:49
	ds_read2_b32 v[48:49], v197 offset1:1
	v_readlane_b32 s8, v254, 27
	v_readlane_b32 s9, v254, 28
	s_waitcnt lgkmcnt(2)
	v_pk_fma_f32 v[32:33], v[14:15], v[44:45], v[12:13] op_sel_hi:[1,0,1] neg_lo:[0,0,1] neg_hi:[0,0,1]
	ds_read2_b32 v[14:15], v197 offset0:2 offset1:3
	v_lshl_add_u64 v[12:13], v[166:167], 0, s[2:3]
	v_lshl_add_u64 v[12:13], v[12:13], 0, v[164:165]
	v_lshl_add_u64 v[36:37], v[12:13], 0, s[6:7]
	global_load_dwordx2 v[204:205], v[36:37], off
	global_load_dwordx2 v[206:207], v[36:37], off offset:16
	global_load_dwordx2 v[208:209], v[36:37], off offset:32
	global_load_dwordx2 v[210:211], v[36:37], off offset:48
	global_load_dwordx2 v[212:213], v[36:37], off offset:64
	global_load_dwordx2 v[214:215], v[36:37], off offset:80
	global_load_dwordx2 v[216:217], v[36:37], off offset:96
	global_load_dwordx2 v[218:219], v[36:37], off offset:112
	global_load_dwordx4 v[220:223], v171, s[8:9]
	global_load_dwordx4 v[224:227], v171, s[8:9] offset:32
	global_load_dwordx4 v[228:231], v171, s[8:9] offset:64
	global_load_dwordx4 v[232:235], v171, s[8:9] offset:96
	global_load_dwordx4 v[236:239], v171, s[8:9] offset:128
	global_load_dwordx4 v[240:243], v171, s[8:9] offset:160
	global_load_dwordx4 v[244:247], v171, s[8:9] offset:192
	global_load_dwordx4 v[248:251], v171, s[8:9] offset:224
	v_add_co_u32_e32 v12, vcc, s16, v12
	s_waitcnt lgkmcnt(0)
	v_pk_fma_f32 v[46:47], v[18:19], v[44:45], v[14:15] op_sel_hi:[1,0,1] neg_lo:[0,0,1] neg_hi:[0,0,1]
	v_addc_co_u32_e32 v13, vcc, 0, v13, vcc
	s_nop 0
	v_pk_fma_f32 v[48:49], v[16:17], v[44:45], v[48:49] op_sel_hi:[1,0,1] neg_lo:[0,0,1] neg_hi:[0,0,1]
	s_nop 0
	v_pk_mul_f32 v[56:57], v[48:49], v[48:49]
	v_pk_mul_f32 v[52:53], v[46:47], v[46:47]
	v_add_f32_e32 v56, v56, v57
	v_add_f32_e32 v52, v56, v52
	v_add_f32_e32 v52, v52, v53
	v_lshl_add_u64 v[38:39], s[4:5], 0, v[160:161]
	v_add_u32_e32 v160, 0x120000, v160
	v_pk_mul_f32 v[40:41], v[34:35], v[34:35]
	v_pk_mul_f32 v[42:43], v[32:33], v[32:33]
	v_lshl_add_u64 v[38:39], v[38:39], 0, v[164:165]
	s_waitcnt vmcnt(0) lgkmcnt(0)
; DI float bf2f(bf16_t v) { return __uint_as_float(((unsigned)v) << 16); }
; DI unsigned pk2(float a, float b) { hwf32x2 f = {a, b}; hwbf16x2 r = __builtin_convertvector(f, hwbf16x2); return __builtin_bit_cast(unsigned, r); }
; DI float siluf_(float z) { return z / (1.f + __expf(-z)); }
; DI int crow(int reg, int h) { return (reg & 3) + 8 * (reg >> 2) + 4 * h; }
; template <int MODE>
; DI void attn_mfma(const Params& p, int l, int b, int hd, int qb, unsigned char* smem) {
;     ...
;         for (int i = 0; i < 16; ++i) { const float o = O[vt][i] * i0 - sO[ql * 65 + vt * 32 + crow(i, h2)]; O[vt][i] = o; ss += o * o; }
;       ss += __shfl_xor(ss, 32);
;       const float rstd = rsqrtf(ss * (1.f / 64.f) + EPS) * (1.f - lam_init);
; #pragma unroll
;       for (int vt = 0; vt < 2; ++vt)
; #pragma unroll
;         for (int g4 = 0; g4 < 4; ++g4) {
;           const int v0 = vt * 32 + 8 * g4 + 4 * h2;
;           const ushort4 gt = *(const ushort4*)(P + qrow * PW + GATE + hd * 64 + v0);
;           const float4 gg = *(const float4*)(p.diff_g + l * 64 + v0);
;           uint2 o;
;           o.x = pk2(O[vt][4 * g4 + 0] * rstd * gg.x * siluf_(bf2f(gt.x)), O[vt][4 * g4 + 1] * rstd * gg.y * siluf_(bf2f(gt.y)));
;           o.y = pk2(O[vt][4 * g4 + 2] * rstd * gg.z * siluf_(bf2f(gt.z)), O[vt][4 * g4 + 3] * rstd * gg.w * siluf_(bf2f(gt.w)));
	v_mov_b32_e32 v18, v204
	v_mov_b32_e32 v19, v205
	v_mov_b32_e32 v12, v220
	v_mov_b32_e32 v13, v221
	v_mov_b32_e32 v14, v222
	v_mov_b32_e32 v15, v223
	v_and_b32_e32 v45, 0xffff0000, v18
	v_lshlrev_b32_e32 v18, 16, v18
	v_mul_f32_e32 v16, 0xbfb8aa3b, v18
	v_mul_f32_e32 v17, 0xbfb8aa3b, v45
	v_exp_f32_e32 v16, v16
	v_exp_f32_e32 v17, v17
	s_nop 0
	v_pk_add_f32 v[16:17], v[16:17], 1.0 op_sel_hi:[1,0]
	s_nop 0
	v_rcp_f32_e32 v51, v17
	s_nop 0
	v_fma_f32 v54, -v17, v51, 1.0
	v_fmac_f32_e32 v51, v54, v51
	v_mul_f32_e32 v55, v45, v51
	v_fma_f32 v58, -v17, v55, v45
	v_fmac_f32_e32 v55, v58, v51
	v_fma_f32 v50, -v17, v55, v45
	v_fma_f32 v50, v50, v51, v55
	v_div_fixup_f32 v51, v50, v17, v45
	v_rcp_f32_e32 v45, v16
	s_nop 0
	v_fma_f32 v50, -v16, v45, 1.0
	v_fmac_f32_e32 v45, v50, v45
	v_mul_f32_e32 v54, v18, v45
	v_fma_f32 v55, -v16, v54, v18
	v_fmac_f32_e32 v54, v55, v45
	v_fma_f32 v17, -v16, v54, v18
	v_fma_f32 v17, v17, v45, v54
	v_div_fixup_f32 v50, v17, v16, v18
	v_and_b32_e32 v18, 0xffff0000, v19
	v_lshlrev_b32_e32 v19, 16, v19
	v_mul_f32_e32 v16, 0xbfb8aa3b, v19
	v_mul_f32_e32 v17, 0xbfb8aa3b, v18
	v_exp_f32_e32 v16, v16
	v_exp_f32_e32 v17, v17
	s_nop 0
	v_pk_add_f32 v[16:17], v[16:17], 1.0 op_sel_hi:[1,0]
	s_nop 0
	v_rcp_f32_e32 v54, v17
	s_nop 0
	v_fma_f32 v55, -v17, v54, 1.0
	v_fmac_f32_e32 v54, v55, v54
	v_mul_f32_e32 v58, v18, v54
	v_fma_f32 v59, -v17, v58, v18
	v_fmac_f32_e32 v58, v59, v54
	v_fma_f32 v45, -v17, v58, v18
	v_fma_f32 v45, v45, v54, v58
	v_div_fixup_f32 v55, v45, v17, v18
	v_rcp_f32_e32 v18, v16
	s_nop 0
	v_fma_f32 v45, -v16, v18, 1.0
	v_fmac_f32_e32 v18, v45, v18
	v_mul_f32_e32 v54, v19, v18
	v_fma_f32 v58, -v16, v54, v19
	v_fmac_f32_e32 v54, v58, v18
	v_fma_f32 v17, -v16, v54, v19
	v_fma_f32 v17, v17, v18, v54
	v_div_fixup_f32 v54, v17, v16, v19
	ds_read2_b32 v[16:17], v197 offset0:10 offset1:11
	ds_read2_b32 v[18:19], v197 offset0:8 offset1:9
	s_waitcnt lgkmcnt(1)
	v_pk_fma_f32 v[60:61], v[22:23], v[44:45], v[16:17] op_sel_hi:[1,0,1] neg_lo:[0,0,1] neg_hi:[0,0,1]
	s_nop 0
	s_waitcnt lgkmcnt(0)
	v_pk_fma_f32 v[62:63], v[20:21], v[44:45], v[18:19] op_sel_hi:[1,0,1] neg_lo:[0,0,1] neg_hi:[0,0,1]
	v_pk_mul_f32 v[68:69], v[60:61], v[60:61]
	v_pk_mul_f32 v[70:71], v[62:63], v[62:63]
	s_nop 0
	v_mov_b32_e32 v16, v206
	v_mov_b32_e32 v17, v207
	v_and_b32_e32 v20, 0xffff0000, v16
	v_lshlrev_b32_e32 v16, 16, v16
	v_mul_f32_e32 v18, 0xbfb8aa3b, v16
	v_mul_f32_e32 v19, 0xbfb8aa3b, v20
	v_exp_f32_e32 v18, v18
	v_exp_f32_e32 v19, v19
	v_add_f32_e32 v52, v52, v70
	v_add_f32_e32 v52, v52, v71
	v_add_f32_e32 v52, v52, v68
	v_pk_add_f32 v[18:19], v[18:19], 1.0 op_sel_hi:[1,0]
	v_add_f32_e32 v52, v52, v69
	v_rcp_f32_e32 v22, v19
	s_nop 0
	v_fma_f32 v23, -v19, v22, 1.0
	v_fmac_f32_e32 v22, v23, v22
	v_mul_f32_e32 v45, v20, v22
	v_fma_f32 v58, -v19, v45, v20
	v_fmac_f32_e32 v45, v58, v22
	v_fma_f32 v21, -v19, v45, v20
	v_fma_f32 v21, v21, v22, v45
	v_div_fixup_f32 v65, v21, v19, v20
	v_rcp_f32_e32 v20, v18
	s_nop 0
	v_fma_f32 v21, -v18, v20, 1.0
	v_fmac_f32_e32 v20, v21, v20
	v_mul_f32_e32 v22, v16, v20
	v_fma_f32 v23, -v18, v22, v16
	v_fmac_f32_e32 v22, v23, v20
	v_fma_f32 v19, -v18, v22, v16
	v_fma_f32 v19, v19, v20, v22
	v_div_fixup_f32 v64, v19, v18, v16
	v_and_b32_e32 v18, 0xffff0000, v17
	v_lshlrev_b32_e32 v19, 16, v17
	v_mul_f32_e32 v16, 0xbfb8aa3b, v19
	v_mul_f32_e32 v17, 0xbfb8aa3b, v18
	v_exp_f32_e32 v16, v16
	v_exp_f32_e32 v17, v17
	s_nop 0
	v_pk_add_f32 v[16:17], v[16:17], 1.0 op_sel_hi:[1,0]
	s_nop 0
	v_rcp_f32_e32 v21, v17
	s_nop 0
	v_fma_f32 v22, -v17, v21, 1.0
	v_fmac_f32_e32 v21, v22, v21
	v_mul_f32_e32 v23, v18, v21
	v_fma_f32 v45, -v17, v23, v18
	v_fmac_f32_e32 v23, v45, v21
	v_fma_f32 v20, -v17, v23, v18
	v_fma_f32 v20, v20, v21, v23
	v_div_fixup_f32 v67, v20, v17, v18
	v_rcp_f32_e32 v18, v16
	v_pk_fma_f32 v[8:9], v[8:9], v[44:45], v[82:83] op_sel_hi:[1,0,1] neg_lo:[0,0,1] neg_hi:[0,0,1]
	v_fma_f32 v20, -v16, v18, 1.0
	v_fmac_f32_e32 v18, v20, v18
	v_mul_f32_e32 v21, v19, v18
	v_fma_f32 v22, -v16, v21, v19
	v_fmac_f32_e32 v21, v22, v18
	v_fma_f32 v17, -v16, v21, v19
	v_fma_f32 v17, v17, v18, v21
	v_div_fixup_f32 v66, v17, v16, v19
	ds_read2_b32 v[16:17], v197 offset0:18 offset1:19
	ds_read2_b32 v[18:19], v197 offset0:34 offset1:35
	s_waitcnt lgkmcnt(1)
	v_pk_fma_f32 v[26:27], v[26:27], v[44:45], v[16:17] op_sel_hi:[1,0,1] neg_lo:[0,0,1] neg_hi:[0,0,1]
	ds_read2_b32 v[16:17], v197 offset0:16 offset1:17
	s_waitcnt lgkmcnt(1)
	v_pk_fma_f32 v[18:19], v[2:3], v[44:45], v[18:19] op_sel_hi:[1,0,1] neg_lo:[0,0,1] neg_hi:[0,0,1]
	ds_read2_b32 v[2:3], v197 offset0:32 offset1:33
	v_pk_mul_f32 v[72:73], v[26:27], v[26:27]
	s_waitcnt lgkmcnt(1)
	v_pk_fma_f32 v[58:59], v[24:25], v[44:45], v[16:17] op_sel_hi:[1,0,1] neg_lo:[0,0,1] neg_hi:[0,0,1]
	ds_read2_b32 v[16:17], v197 offset0:26 offset1:27
	s_waitcnt lgkmcnt(1)
	v_pk_fma_f32 v[20:21], v[0:1], v[44:45], v[2:3] op_sel_hi:[1,0,1] neg_lo:[0,0,1] neg_hi:[0,0,1]
	ds_read2_b32 v[2:3], v197 offset0:42 offset1:43
	v_pk_mul_f32 v[74:75], v[58:59], v[58:59]
	v_pk_mul_f32 v[80:81], v[20:21], v[20:21]
	s_waitcnt lgkmcnt(1)
	v_pk_fma_f32 v[22:23], v[30:31], v[44:45], v[16:17] op_sel_hi:[1,0,1] neg_lo:[0,0,1] neg_hi:[0,0,1]
	ds_read2_b32 v[16:17], v197 offset0:24 offset1:25
	v_add_f32_e32 v52, v52, v74
	v_add_f32_e32 v52, v52, v75
	s_waitcnt lgkmcnt(1)
	v_pk_fma_f32 v[6:7], v[6:7], v[44:45], v[2:3] op_sel_hi:[1,0,1] neg_lo:[0,0,1] neg_hi:[0,0,1]
	ds_read2_b32 v[2:3], v197 offset0:40 offset1:41
	s_waitcnt lgkmcnt(1)
; DI size_t kblk(int row, int col, int nrows) { return ((size_t)(col >> 5) * nrows + row) * 32 + (col & 31); }
; DI float bf2f(bf16_t v) { return __uint_as_float(((unsigned)v) << 16); }
; DI unsigned pk2(float a, float b) { hwf32x2 f = {a, b}; hwbf16x2 r = __builtin_convertvector(f, hwbf16x2); return __builtin_bit_cast(unsigned, r); }
; DI float siluf_(float z) { return z / (1.f + __expf(-z)); }
; template <int MODE>
; DI void attn_mfma(const Params& p, int l, int b, int hd, int qb, unsigned char* smem) {
;     ...
;       ss += __shfl_xor(ss, 32);
;       const float rstd = rsqrtf(ss * (1.f / 64.f) + EPS) * (1.f - lam_init);
; #pragma unroll
;       for (int vt = 0; vt < 2; ++vt)
; #pragma unroll
;         for (int g4 = 0; g4 < 4; ++g4) {
;           const int v0 = vt * 32 + 8 * g4 + 4 * h2;
;           const ushort4 gt = *(const ushort4*)(P + qrow * PW + GATE + hd * 64 + v0);
;           const float4 gg = *(const float4*)(p.diff_g + l * 64 + v0);
;           uint2 o;
;           o.x = pk2(O[vt][4 * g4 + 0] * rstd * gg.x * siluf_(bf2f(gt.x)), O[vt][4 * g4 + 1] * rstd * gg.y * siluf_(bf2f(gt.y)));
;           o.y = pk2(O[vt][4 * g4 + 2] * rstd * gg.z * siluf_(bf2f(gt.z)), O[vt][4 * g4 + 3] * rstd * gg.w * siluf_(bf2f(gt.w)));
;           *(uint2*)(MIX + kblk((int)qrow, hd * 64 + v0, ROWS)) = o;
;         }
	v_pk_fma_f32 v[24:25], v[28:29], v[44:45], v[16:17] op_sel_hi:[1,0,1] neg_lo:[0,0,1] neg_hi:[0,0,1]
	v_add_f32_e32 v52, v52, v72
	v_pk_mul_f32 v[76:77], v[24:25], v[24:25]
	v_add_f32_e32 v52, v52, v73
	v_add_f32_e32 v52, v52, v76
	v_pk_mul_f32 v[30:31], v[22:23], v[22:23]
	v_add_f32_e32 v52, v52, v77
	v_add_f32_e32 v30, v52, v30
	v_add_f32_e32 v30, v30, v31
	v_add_f32_e32 v30, v30, v80
	v_lshl_add_u64 v[16:17], s[4:5], 0, v[160:161]
	v_pk_mul_f32 v[28:29], v[18:19], v[18:19]
	v_add_f32_e32 v30, v30, v81
	v_lshl_add_u64 v[0:1], v[16:17], 0, v[164:165]
	s_waitcnt lgkmcnt(0)
	v_pk_fma_f32 v[16:17], v[4:5], v[44:45], v[2:3] op_sel_hi:[1,0,1] neg_lo:[0,0,1] neg_hi:[0,0,1]
	ds_read2_b32 v[2:3], v197 offset0:50 offset1:51
	v_add_f32_e32 v28, v30, v28
	v_pk_mul_f32 v[4:5], v[16:17], v[16:17]
	v_add_f32_e32 v28, v28, v29
	v_add_f32_e32 v4, v28, v4
	v_pk_mul_f32 v[78:79], v[6:7], v[6:7]
	v_add_f32_e32 v4, v4, v5
	v_add_f32_e32 v4, v4, v78
	s_waitcnt lgkmcnt(0)
	v_pk_fma_f32 v[2:3], v[10:11], v[44:45], v[2:3] op_sel_hi:[1,0,1] neg_lo:[0,0,1] neg_hi:[0,0,1]
	v_pk_mul_f32 v[44:45], v[8:9], v[8:9]
	v_add_f32_e32 v4, v4, v79
	v_add_f32_e32 v4, v4, v44
	v_pk_mul_f32 v[10:11], v[2:3], v[2:3]
	v_add_f32_e32 v4, v4, v45
	v_add_f32_e32 v4, v4, v10
	v_add_f32_e32 v4, v4, v11
	v_add_f32_e32 v4, v4, v40
	v_add_f32_e32 v4, v4, v41
	v_add_f32_e32 v4, v4, v42
	v_add_f32_e32 v4, v4, v43
	ds_bpermute_b32 v5, v170, v4
	s_waitcnt lgkmcnt(0)
	v_add_f32_e32 v4, v4, v5
	v_fmamk_f32 v4, v4, 0x3c800000, v162
	v_cmp_gt_f32_e32 vcc, s38, v4
	v_mul_f32_e32 v5, 0x4b800000, v4
	s_nop 0
	v_cndmask_b32_e32 v4, v4, v5, vcc
	v_rsq_f32_e32 v4, v4
	s_nop 0
	v_mul_f32_e32 v5, 0x45800000, v4
	v_cndmask_b32_e32 v4, v4, v5, vcc
	v_mul_f32_e32 v4, v169, v4
	v_pk_mul_f32 v[10:11], v[48:49], v[4:5] op_sel_hi:[1,0]
	s_nop 0
	v_pk_mul_f32 v[10:11], v[12:13], v[10:11]
	v_pk_mul_f32 v[12:13], v[46:47], v[4:5] op_sel_hi:[1,0]
	v_pk_mul_f32 v[10:11], v[50:51], v[10:11]
	v_pk_mul_f32 v[12:13], v[14:15], v[12:13]
	v_cvt_pk_bf16_f32 v10, v10, v11
	v_pk_mul_f32 v[12:13], v[54:55], v[12:13]
	v_pk_mul_f32 v[14:15], v[62:63], v[4:5] op_sel_hi:[1,0]
	v_cvt_pk_bf16_f32 v11, v12, v13
	global_store_dwordx2 v[38:39], v[10:11], off
	s_nop 0
	s_nop 0
	v_mov_b32_e32 v10, v224
	v_mov_b32_e32 v11, v225
	v_mov_b32_e32 v12, v226
	v_mov_b32_e32 v13, v227
	v_pk_mul_f32 v[10:11], v[14:15], v[10:11]
	v_pk_mul_f32 v[14:15], v[60:61], v[4:5] op_sel_hi:[1,0]
	v_pk_mul_f32 v[10:11], v[10:11], v[64:65]
	v_pk_mul_f32 v[12:13], v[14:15], v[12:13]
	v_cvt_pk_bf16_f32 v10, v10, v11
	v_pk_mul_f32 v[12:13], v[12:13], v[66:67]
	s_nop 0
	v_cvt_pk_bf16_f32 v11, v12, v13
	global_store_dwordx2 v[38:39], v[10:11], off offset:16
	s_nop 0
	s_nop 0
	s_nop 0
	s_waitcnt lgkmcnt(0)
	v_mov_b32_e32 v14, v208
	v_mov_b32_e32 v15, v209
	v_mov_b32_e32 v10, v228
	v_mov_b32_e32 v11, v229
	v_mov_b32_e32 v12, v230
	v_mov_b32_e32 v13, v231
	v_and_b32_e32 v5, 0xffff0000, v14
	v_lshlrev_b32_e32 v14, 16, v14
	v_mul_f32_e32 v28, 0xbfb8aa3b, v14
	v_mul_f32_e32 v29, 0xbfb8aa3b, v5
	v_exp_f32_e32 v28, v28
	v_exp_f32_e32 v29, v29
	v_pk_mul_f32 v[30:31], v[58:59], v[4:5] op_sel_hi:[1,0]
	v_pk_add_f32 v[28:29], v[28:29], 1.0 op_sel_hi:[1,0]
	v_pk_mul_f32 v[10:11], v[30:31], v[10:11]
	v_rcp_f32_e32 v31, v29
	s_nop 0
	v_fma_f32 v40, -v29, v31, 1.0
	v_fmac_f32_e32 v31, v40, v31
	v_mul_f32_e32 v41, v5, v31
	v_fma_f32 v42, -v29, v41, v5
	v_fmac_f32_e32 v41, v42, v31
	v_fma_f32 v30, -v29, v41, v5
	v_fma_f32 v30, v30, v31, v41
	v_div_fixup_f32 v29, v30, v29, v5
	v_rcp_f32_e32 v30, v28
	s_nop 0
	v_fma_f32 v31, -v28, v30, 1.0
	v_fmac_f32_e32 v30, v31, v30
	v_mul_f32_e32 v40, v14, v30
	v_fma_f32 v41, -v28, v40, v14
	v_fmac_f32_e32 v40, v41, v30
	v_fma_f32 v5, -v28, v40, v14
	v_fma_f32 v5, v5, v30, v40
	v_div_fixup_f32 v28, v5, v28, v14
	v_pk_mul_f32 v[10:11], v[10:11], v[28:29]
	v_and_b32_e32 v5, 0xffff0000, v15
	v_cvt_pk_bf16_f32 v10, v10, v11
	v_lshlrev_b32_e32 v11, 16, v15
	v_mul_f32_e32 v14, 0xbfb8aa3b, v11
	v_mul_f32_e32 v15, 0xbfb8aa3b, v5
	v_exp_f32_e32 v14, v14
	v_exp_f32_e32 v15, v15
	v_pk_mul_f32 v[26:27], v[26:27], v[4:5] op_sel_hi:[1,0]
	v_pk_add_f32 v[14:15], v[14:15], 1.0 op_sel_hi:[1,0]
	v_pk_mul_f32 v[12:13], v[26:27], v[12:13]
	v_rcp_f32_e32 v27, v15
	s_nop 0
	v_fma_f32 v28, -v15, v27, 1.0
	v_fmac_f32_e32 v27, v28, v27
	v_mul_f32_e32 v29, v5, v27
	v_fma_f32 v30, -v15, v29, v5
	v_fmac_f32_e32 v29, v30, v27
	v_fma_f32 v26, -v15, v29, v5
	v_fma_f32 v26, v26, v27, v29
	v_div_fixup_f32 v15, v26, v15, v5
	v_rcp_f32_e32 v26, v14
	s_nop 0
	v_fma_f32 v27, -v14, v26, 1.0
	v_fmac_f32_e32 v26, v27, v26
	v_mul_f32_e32 v28, v11, v26
	v_fma_f32 v29, -v14, v28, v11
	v_fmac_f32_e32 v28, v29, v26
	v_fma_f32 v5, -v14, v28, v11
	v_fma_f32 v5, v5, v26, v28
	v_div_fixup_f32 v14, v5, v14, v11
	v_pk_mul_f32 v[12:13], v[12:13], v[14:15]
	s_nop 0
	v_cvt_pk_bf16_f32 v11, v12, v13
	global_store_dwordx2 v[38:39], v[10:11], off offset:32
	s_nop 0
	s_nop 0
	s_nop 0
	s_waitcnt lgkmcnt(0)
; DI size_t kblk(int row, int col, int nrows) { return ((size_t)(col >> 5) * nrows + row) * 32 + (col & 31); }
; DI float bf2f(bf16_t v) { return __uint_as_float(((unsigned)v) << 16); }
; DI unsigned pk2(float a, float b) { hwf32x2 f = {a, b}; hwbf16x2 r = __builtin_convertvector(f, hwbf16x2); return __builtin_bit_cast(unsigned, r); }
; DI float siluf_(float z) { return z / (1.f + __expf(-z)); }
; template <int MODE>
; DI void attn_mfma(const Params& p, int l, int b, int hd, int qb, unsigned char* smem) {
;     ...
; #pragma unroll
;       for (int vt = 0; vt < 2; ++vt)
; #pragma unroll
;         for (int g4 = 0; g4 < 4; ++g4) {
;           const int v0 = vt * 32 + 8 * g4 + 4 * h2;
;           const ushort4 gt = *(const ushort4*)(P + qrow * PW + GATE + hd * 64 + v0);
;           const float4 gg = *(const float4*)(p.diff_g + l * 64 + v0);
;           uint2 o;
;           o.x = pk2(O[vt][4 * g4 + 0] * rstd * gg.x * siluf_(bf2f(gt.x)), O[vt][4 * g4 + 1] * rstd * gg.y * siluf_(bf2f(gt.y)));
;           o.y = pk2(O[vt][4 * g4 + 2] * rstd * gg.z * siluf_(bf2f(gt.z)), O[vt][4 * g4 + 3] * rstd * gg.w * siluf_(bf2f(gt.w)));
;           *(uint2*)(MIX + kblk((int)qrow, hd * 64 + v0, ROWS)) = o;
;         }
	v_mov_b32_e32 v14, v210
	v_mov_b32_e32 v15, v211
	v_mov_b32_e32 v10, v232
	v_mov_b32_e32 v11, v233
	v_mov_b32_e32 v12, v234
	v_mov_b32_e32 v13, v235
	v_and_b32_e32 v5, 0xffff0000, v14
	v_lshlrev_b32_e32 v14, 16, v14
	v_pk_mul_f32 v[24:25], v[24:25], v[4:5] op_sel_hi:[1,0]
	v_mul_f32_e32 v26, 0xbfb8aa3b, v14
	v_pk_mul_f32 v[10:11], v[24:25], v[10:11]
	v_mul_f32_e32 v24, 0xbfb8aa3b, v5
	v_exp_f32_e32 v26, v26
	v_exp_f32_e32 v27, v24
	s_nop 0
	v_pk_add_f32 v[24:25], v[26:27], 1.0 op_sel_hi:[1,0]
	s_nop 0
	v_rcp_f32_e32 v27, v25
	s_nop 0
	v_fma_f32 v28, -v25, v27, 1.0
	v_fmac_f32_e32 v27, v28, v27
	v_mul_f32_e32 v29, v5, v27
	v_fma_f32 v30, -v25, v29, v5
	v_fmac_f32_e32 v29, v30, v27
	v_fma_f32 v26, -v25, v29, v5
	v_fma_f32 v26, v26, v27, v29
	v_div_fixup_f32 v25, v26, v25, v5
	v_rcp_f32_e32 v26, v24
	s_nop 0
	v_fma_f32 v27, -v24, v26, 1.0
	v_fmac_f32_e32 v26, v27, v26
	v_mul_f32_e32 v28, v14, v26
	v_fma_f32 v29, -v24, v28, v14
	v_fmac_f32_e32 v28, v29, v26
	v_fma_f32 v5, -v24, v28, v14
	v_fma_f32 v5, v5, v26, v28
	v_div_fixup_f32 v24, v5, v24, v14
	v_pk_mul_f32 v[10:11], v[10:11], v[24:25]
	v_and_b32_e32 v5, 0xffff0000, v15
	v_cvt_pk_bf16_f32 v10, v10, v11
	v_lshlrev_b32_e32 v11, 16, v15
	v_mul_f32_e32 v14, 0xbfb8aa3b, v11
	v_mul_f32_e32 v15, 0xbfb8aa3b, v5
	v_exp_f32_e32 v14, v14
	v_exp_f32_e32 v15, v15
	v_pk_mul_f32 v[22:23], v[22:23], v[4:5] op_sel_hi:[1,0]
	v_pk_add_f32 v[14:15], v[14:15], 1.0 op_sel_hi:[1,0]
	v_pk_mul_f32 v[12:13], v[22:23], v[12:13]
	v_rcp_f32_e32 v23, v15
	s_nop 0
	v_fma_f32 v24, -v15, v23, 1.0
	v_fmac_f32_e32 v23, v24, v23
	v_mul_f32_e32 v25, v5, v23
	v_fma_f32 v26, -v15, v25, v5
	v_fmac_f32_e32 v25, v26, v23
	v_fma_f32 v22, -v15, v25, v5
	v_fma_f32 v22, v22, v23, v25
	v_div_fixup_f32 v15, v22, v15, v5
	v_rcp_f32_e32 v22, v14
	s_nop 0
	v_fma_f32 v23, -v14, v22, 1.0
	v_fmac_f32_e32 v22, v23, v22
	v_mul_f32_e32 v24, v11, v22
	v_fma_f32 v25, -v14, v24, v11
	v_fmac_f32_e32 v24, v25, v22
	v_fma_f32 v5, -v14, v24, v11
	v_fma_f32 v5, v5, v22, v24
	v_div_fixup_f32 v14, v5, v14, v11
	v_pk_mul_f32 v[12:13], v[12:13], v[14:15]
	s_nop 0
	v_cvt_pk_bf16_f32 v11, v12, v13
	global_store_dwordx2 v[38:39], v[10:11], off offset:48
	s_nop 0
	s_nop 0
	s_nop 0
	s_waitcnt lgkmcnt(0)
	v_mov_b32_e32 v10, v212
	v_mov_b32_e32 v11, v213
	v_mov_b32_e32 v12, v236
	v_mov_b32_e32 v13, v237
	v_mov_b32_e32 v14, v238
	v_mov_b32_e32 v15, v239
	v_and_b32_e32 v5, 0xffff0000, v10
	v_lshlrev_b32_e32 v10, 16, v10
	v_pk_mul_f32 v[20:21], v[20:21], v[4:5] op_sel_hi:[1,0]
	v_mul_f32_e32 v22, 0xbfb8aa3b, v10
	v_pk_mul_f32 v[12:13], v[20:21], v[12:13]
	v_mul_f32_e32 v20, 0xbfb8aa3b, v5
	v_exp_f32_e32 v22, v22
	v_exp_f32_e32 v23, v20
	s_nop 0
	v_pk_add_f32 v[20:21], v[22:23], 1.0 op_sel_hi:[1,0]
	s_nop 0
	v_rcp_f32_e32 v23, v21
	s_nop 0
	v_fma_f32 v24, -v21, v23, 1.0
	v_fmac_f32_e32 v23, v24, v23
	v_mul_f32_e32 v25, v5, v23
	v_fma_f32 v26, -v21, v25, v5
	v_fmac_f32_e32 v25, v26, v23
	v_fma_f32 v22, -v21, v25, v5
	v_fma_f32 v22, v22, v23, v25
	v_div_fixup_f32 v21, v22, v21, v5
	v_rcp_f32_e32 v22, v20
	s_nop 0
	v_fma_f32 v23, -v20, v22, 1.0
	v_fmac_f32_e32 v22, v23, v22
	v_mul_f32_e32 v24, v10, v22
	v_fma_f32 v25, -v20, v24, v10
	v_fmac_f32_e32 v24, v25, v22
	v_fma_f32 v5, -v20, v24, v10
	v_fma_f32 v5, v5, v22, v24
	v_div_fixup_f32 v20, v5, v20, v10
	v_pk_mul_f32 v[12:13], v[12:13], v[20:21]
	v_and_b32_e32 v5, 0xffff0000, v11
	v_lshlrev_b32_e32 v11, 16, v11
	v_cvt_pk_bf16_f32 v10, v12, v13
	v_mul_f32_e32 v12, 0xbfb8aa3b, v11
	v_mul_f32_e32 v13, 0xbfb8aa3b, v5
	v_exp_f32_e32 v12, v12
	v_exp_f32_e32 v13, v13
	v_pk_mul_f32 v[18:19], v[18:19], v[4:5] op_sel_hi:[1,0]
	v_pk_add_f32 v[12:13], v[12:13], 1.0 op_sel_hi:[1,0]
	v_pk_mul_f32 v[14:15], v[18:19], v[14:15]
	v_rcp_f32_e32 v19, v13
	s_nop 0
	v_fma_f32 v20, -v13, v19, 1.0
	v_fmac_f32_e32 v19, v20, v19
	v_mul_f32_e32 v21, v5, v19
	v_fma_f32 v22, -v13, v21, v5
	v_fmac_f32_e32 v21, v22, v19
	v_fma_f32 v18, -v13, v21, v5
	v_fma_f32 v18, v18, v19, v21
	v_div_fixup_f32 v13, v18, v13, v5
	v_rcp_f32_e32 v18, v12
	s_nop 0
	v_fma_f32 v19, -v12, v18, 1.0
	v_fmac_f32_e32 v18, v19, v18
	v_mul_f32_e32 v20, v11, v18
	v_fma_f32 v21, -v12, v20, v11
	v_fmac_f32_e32 v20, v21, v18
	v_fma_f32 v5, -v12, v20, v11
	v_fma_f32 v5, v5, v18, v20
	v_div_fixup_f32 v12, v5, v12, v11
	v_pk_mul_f32 v[12:13], v[14:15], v[12:13]
	s_nop 0
	v_cvt_pk_bf16_f32 v11, v12, v13
	global_store_dwordx2 v[0:1], v[10:11], off
	s_nop 0
	s_nop 0
	s_nop 0
	s_waitcnt lgkmcnt(0)
; DI size_t kblk(int row, int col, int nrows) { return ((size_t)(col >> 5) * nrows + row) * 32 + (col & 31); }
; DI float bf2f(bf16_t v) { return __uint_as_float(((unsigned)v) << 16); }
; DI unsigned pk2(float a, float b) { hwf32x2 f = {a, b}; hwbf16x2 r = __builtin_convertvector(f, hwbf16x2); return __builtin_bit_cast(unsigned, r); }
; DI float siluf_(float z) { return z / (1.f + __expf(-z)); }
; template <int MODE>
; DI void attn_mfma(const Params& p, int l, int b, int hd, int qb, unsigned char* smem) {
;     ...
; #pragma unroll
;       for (int vt = 0; vt < 2; ++vt)
; #pragma unroll
;         for (int g4 = 0; g4 < 4; ++g4) {
;           const int v0 = vt * 32 + 8 * g4 + 4 * h2;
;           const ushort4 gt = *(const ushort4*)(P + qrow * PW + GATE + hd * 64 + v0);
;           const float4 gg = *(const float4*)(p.diff_g + l * 64 + v0);
;           uint2 o;
;           o.x = pk2(O[vt][4 * g4 + 0] * rstd * gg.x * siluf_(bf2f(gt.x)), O[vt][4 * g4 + 1] * rstd * gg.y * siluf_(bf2f(gt.y)));
;           o.y = pk2(O[vt][4 * g4 + 2] * rstd * gg.z * siluf_(bf2f(gt.z)), O[vt][4 * g4 + 3] * rstd * gg.w * siluf_(bf2f(gt.w)));
;           *(uint2*)(MIX + kblk((int)qrow, hd * 64 + v0, ROWS)) = o;
;         }
	v_mov_b32_e32 v14, v214
	v_mov_b32_e32 v15, v215
	v_mov_b32_e32 v10, v240
	v_mov_b32_e32 v11, v241
	v_mov_b32_e32 v12, v242
	v_mov_b32_e32 v13, v243
	v_and_b32_e32 v5, 0xffff0000, v14
	v_lshlrev_b32_e32 v14, 16, v14
	v_pk_mul_f32 v[16:17], v[16:17], v[4:5] op_sel_hi:[1,0]
	v_mul_f32_e32 v18, 0xbfb8aa3b, v14
	v_pk_mul_f32 v[10:11], v[16:17], v[10:11]
	v_mul_f32_e32 v16, 0xbfb8aa3b, v5
	v_exp_f32_e32 v18, v18
	v_exp_f32_e32 v19, v16
	s_nop 0
	v_pk_add_f32 v[16:17], v[18:19], 1.0 op_sel_hi:[1,0]
	s_nop 0
	v_rcp_f32_e32 v19, v17
	s_nop 0
	v_fma_f32 v20, -v17, v19, 1.0
	v_fmac_f32_e32 v19, v20, v19
	v_mul_f32_e32 v21, v5, v19
	v_fma_f32 v22, -v17, v21, v5
	v_fmac_f32_e32 v21, v22, v19
	v_fma_f32 v18, -v17, v21, v5
	v_fma_f32 v18, v18, v19, v21
	v_div_fixup_f32 v17, v18, v17, v5
	v_rcp_f32_e32 v18, v16
	s_nop 0
	v_fma_f32 v19, -v16, v18, 1.0
	v_fmac_f32_e32 v18, v19, v18
	v_mul_f32_e32 v20, v14, v18
	v_fma_f32 v21, -v16, v20, v14
	v_fmac_f32_e32 v20, v21, v18
	v_fma_f32 v5, -v16, v20, v14
	v_fma_f32 v5, v5, v18, v20
	v_div_fixup_f32 v16, v5, v16, v14
	v_pk_mul_f32 v[10:11], v[10:11], v[16:17]
	v_and_b32_e32 v5, 0xffff0000, v15
	v_cvt_pk_bf16_f32 v10, v10, v11
	v_lshlrev_b32_e32 v11, 16, v15
	v_pk_mul_f32 v[6:7], v[6:7], v[4:5] op_sel_hi:[1,0]
	v_mul_f32_e32 v14, 0xbfb8aa3b, v11
	v_pk_mul_f32 v[6:7], v[6:7], v[12:13]
	v_mul_f32_e32 v12, 0xbfb8aa3b, v5
	v_exp_f32_e32 v14, v14
	v_exp_f32_e32 v15, v12
	s_nop 0
	v_pk_add_f32 v[12:13], v[14:15], 1.0 op_sel_hi:[1,0]
	s_nop 0
	v_rcp_f32_e32 v15, v13
	s_nop 0
	v_fma_f32 v16, -v13, v15, 1.0
	v_fmac_f32_e32 v15, v16, v15
	v_mul_f32_e32 v17, v5, v15
	v_fma_f32 v18, -v13, v17, v5
	v_fmac_f32_e32 v17, v18, v15
	v_fma_f32 v14, -v13, v17, v5
	v_fma_f32 v14, v14, v15, v17
	v_div_fixup_f32 v13, v14, v13, v5
	v_rcp_f32_e32 v14, v12
	s_nop 0
	v_fma_f32 v15, -v12, v14, 1.0
	v_fmac_f32_e32 v14, v15, v14
	v_mul_f32_e32 v16, v11, v14
	v_fma_f32 v17, -v12, v16, v11
	v_fmac_f32_e32 v16, v17, v14
	v_fma_f32 v5, -v12, v16, v11
	v_fma_f32 v5, v5, v14, v16
	v_div_fixup_f32 v12, v5, v12, v11
	v_pk_mul_f32 v[6:7], v[6:7], v[12:13]
	s_nop 0
	v_cvt_pk_bf16_f32 v11, v6, v7
	global_store_dwordx2 v[0:1], v[10:11], off offset:16
	s_nop 0
	s_nop 0
	s_nop 0
	s_waitcnt lgkmcnt(0)
	v_mov_b32_e32 v6, v216
	v_mov_b32_e32 v7, v217
	v_mov_b32_e32 v10, v244
	v_mov_b32_e32 v11, v245
	v_mov_b32_e32 v12, v246
	v_mov_b32_e32 v13, v247
	v_and_b32_e32 v5, 0xffff0000, v6
	v_lshlrev_b32_e32 v6, 16, v6
	v_pk_mul_f32 v[8:9], v[8:9], v[4:5] op_sel_hi:[1,0]
	v_mul_f32_e32 v14, 0xbfb8aa3b, v6
	v_pk_mul_f32 v[8:9], v[8:9], v[10:11]
	v_mul_f32_e32 v10, 0xbfb8aa3b, v5
	v_exp_f32_e32 v14, v14
	v_exp_f32_e32 v15, v10
	s_nop 0
	v_pk_add_f32 v[10:11], v[14:15], 1.0 op_sel_hi:[1,0]
	s_nop 0
	v_rcp_f32_e32 v15, v11
	s_nop 0
	v_fma_f32 v16, -v11, v15, 1.0
	v_fmac_f32_e32 v15, v16, v15
	v_mul_f32_e32 v17, v5, v15
	v_fma_f32 v18, -v11, v17, v5
	v_fmac_f32_e32 v17, v18, v15
	v_fma_f32 v14, -v11, v17, v5
	v_fma_f32 v14, v14, v15, v17
	v_div_fixup_f32 v11, v14, v11, v5
	v_rcp_f32_e32 v14, v10
	s_nop 0
	v_fma_f32 v15, -v10, v14, 1.0
	v_fmac_f32_e32 v14, v15, v14
	v_mul_f32_e32 v16, v6, v14
	v_fma_f32 v17, -v10, v16, v6
	v_fmac_f32_e32 v16, v17, v14
	v_fma_f32 v5, -v10, v16, v6
	v_fma_f32 v5, v5, v14, v16
	v_div_fixup_f32 v10, v5, v10, v6
	v_pk_mul_f32 v[8:9], v[8:9], v[10:11]
	v_and_b32_e32 v5, 0xffff0000, v7
	v_lshlrev_b32_e32 v7, 16, v7
	v_cvt_pk_bf16_f32 v6, v8, v9
	v_mul_f32_e32 v8, 0xbfb8aa3b, v7
	v_mul_f32_e32 v9, 0xbfb8aa3b, v5
	v_exp_f32_e32 v8, v8
	v_exp_f32_e32 v9, v9
	v_pk_mul_f32 v[2:3], v[2:3], v[4:5] op_sel_hi:[1,0]
	v_pk_add_f32 v[8:9], v[8:9], 1.0 op_sel_hi:[1,0]
	s_nop 0
	v_rcp_f32_e32 v11, v9
	v_pk_mul_f32 v[2:3], v[2:3], v[12:13]
	v_fma_f32 v12, -v9, v11, 1.0
	v_fmac_f32_e32 v11, v12, v11
	v_mul_f32_e32 v13, v5, v11
	v_fma_f32 v14, -v9, v13, v5
	v_fmac_f32_e32 v13, v14, v11
	v_fma_f32 v10, -v9, v13, v5
	v_fma_f32 v10, v10, v11, v13
	v_div_fixup_f32 v9, v10, v9, v5
	v_rcp_f32_e32 v10, v8
	s_nop 0
	v_fma_f32 v11, -v8, v10, 1.0
	v_fmac_f32_e32 v10, v11, v10
	v_mul_f32_e32 v12, v7, v10
	v_fma_f32 v13, -v8, v12, v7
	v_fmac_f32_e32 v12, v13, v10
	v_fma_f32 v5, -v8, v12, v7
	v_fma_f32 v5, v5, v10, v12
	v_div_fixup_f32 v8, v5, v8, v7
	v_pk_mul_f32 v[2:3], v[2:3], v[8:9]
	s_nop 0
	v_cvt_pk_bf16_f32 v7, v2, v3
	global_store_dwordx2 v[0:1], v[6:7], off offset:32
	s_nop 0
	s_nop 0
	s_nop 0
	s_waitcnt lgkmcnt(0)
	v_mov_b32_e32 v2, v218
	v_mov_b32_e32 v3, v219
	v_mov_b32_e32 v6, v248
	v_mov_b32_e32 v7, v249
	v_mov_b32_e32 v8, v250
	v_mov_b32_e32 v9, v251
	v_and_b32_e32 v5, 0xffff0000, v2
	v_lshlrev_b32_e32 v2, 16, v2
	v_mul_f32_e32 v10, 0xbfb8aa3b, v2
	v_mul_f32_e32 v11, 0xbfb8aa3b, v5
	v_exp_f32_e32 v10, v10
	v_exp_f32_e32 v11, v11
	v_pk_mul_f32 v[12:13], v[34:35], v[4:5] op_sel_hi:[1,0]
	v_pk_add_f32 v[10:11], v[10:11], 1.0 op_sel_hi:[1,0]
	v_pk_mul_f32 v[6:7], v[12:13], v[6:7]
	v_rcp_f32_e32 v13, v11
	s_nop 0
	v_fma_f32 v14, -v11, v13, 1.0
	v_fmac_f32_e32 v13, v14, v13
	v_mul_f32_e32 v15, v5, v13
	v_fma_f32 v16, -v11, v15, v5
	v_fmac_f32_e32 v15, v16, v13
	v_fma_f32 v12, -v11, v15, v5
	v_fma_f32 v12, v12, v13, v15
	v_div_fixup_f32 v11, v12, v11, v5
	v_rcp_f32_e32 v12, v10
	s_nop 0
	v_fma_f32 v13, -v10, v12, 1.0
	v_fmac_f32_e32 v12, v13, v12
	v_mul_f32_e32 v14, v2, v12
	v_fma_f32 v15, -v10, v14, v2
	v_fmac_f32_e32 v14, v15, v12
	v_fma_f32 v5, -v10, v14, v2
	v_fma_f32 v5, v5, v12, v14
	v_div_fixup_f32 v10, v5, v10, v2
	v_pk_mul_f32 v[6:7], v[6:7], v[10:11]
	v_and_b32_e32 v10, 0xffff0000, v3
	v_lshlrev_b32_e32 v3, 16, v3
	v_cvt_pk_bf16_f32 v2, v6, v7
	v_mul_f32_e32 v5, 0xbfb8aa3b, v3
	v_mul_f32_e32 v7, 0xbfb8aa3b, v10
	v_exp_f32_e32 v6, v5
	v_exp_f32_e32 v7, v7
	v_pk_mul_f32 v[4:5], v[32:33], v[4:5] op_sel_hi:[1,0]
	v_pk_add_f32 v[6:7], v[6:7], 1.0 op_sel_hi:[1,0]
	v_pk_mul_f32 v[4:5], v[4:5], v[8:9]
	v_rcp_f32_e32 v9, v7
	s_nop 0
	v_fma_f32 v11, -v7, v9, 1.0
	v_fmac_f32_e32 v9, v11, v9
	v_mul_f32_e32 v12, v10, v9
	v_fma_f32 v13, -v7, v12, v10
	v_fmac_f32_e32 v12, v13, v9
	v_fma_f32 v8, -v7, v12, v10
	v_fma_f32 v8, v8, v9, v12
	v_div_fixup_f32 v7, v8, v7, v10
	v_rcp_f32_e32 v9, v6
	s_nop 0
	v_fma_f32 v10, -v6, v9, 1.0
	v_fmac_f32_e32 v9, v10, v9
	v_mul_f32_e32 v11, v3, v9
	v_fma_f32 v12, -v6, v11, v3
	v_fmac_f32_e32 v11, v12, v9
	v_fma_f32 v8, -v6, v11, v3
	v_fma_f32 v8, v8, v9, v11
	v_div_fixup_f32 v6, v8, v6, v3
	v_pk_mul_f32 v[4:5], v[4:5], v[6:7]
	s_nop 0
	v_cvt_pk_bf16_f32 v3, v4, v5
	global_store_dwordx2 v[0:1], v[2:3], off offset:48

; DI size_t kblk(int row, int col, int nrows) { return ((size_t)(col >> 5) * nrows + row) * 32 + (col & 31); }
; DI unsigned pk2(float a, float b) { hwf32x2 f = {a, b}; hwbf16x2 r = __builtin_convertvector(f, hwbf16x2); return __builtin_bit_cast(unsigned, r); }
; #define MFMA16(a, b, c) __builtin_amdgcn_mfma_f32_16x16x32_bf16((a), (b), (c), 0, 0, 0)
; template <int MX, bool OUT>
; DI void rec_chunk(const Params& p, int l, int b, int h, int dir, int T0, unsigned char* smem, f32x4 (&St)[4], float& nst, float& dtot, int tid, const RecRaw& raw) {
;     ...
; #pragma unroll
;     for (int ks = 0; ks < 2; ++ks) {
;       const bf16x8 fb = *(const bf16x8*)(smem + L_QS + swz(t, ks * 4 + g));
; #pragma unroll
;       for (int a = 0; a < 4; ++a) {
;         const bf16x8 fa = *(const bf16x8*)(smem + L_STT + swz(16 * a + col, ks * 4 + g));
;         O[a] = MFMA16(fa, fb, O[a]);
;       }
;     }
;     if (MX == 1) {
;       const float inv = 1.f / fmaxf(fabsf(den), 1.f);
; #pragma unroll
;       for (int a = 0; a < 4; ++a)
; #pragma unroll
;         for (int j = 0; j < 4; ++j) O[a][j] *= inv;
;     }
;     if (dir == 0) {
; #pragma unroll
;       for (int a = 0; a < 4; ++a) *(uint2*)(MIX + kblk((int)orow, cb + 16 * a + 4 * g, ROWS)) = make_uint2(pk2(O[a][0], O[a][1]), pk2(O[a][2], O[a][3]));
;     } else {
;       float ss = 0.f;
; #pragma unroll
;       for (int a = 0; a < 4; ++a) {
;         const uint2 u = *(const uint2*)(MIX + kblk((int)orow, cb + 16 * a + 4 * g, ROWS));
;         O[a][0] += __uint_as_float(u.x << 16); O[a][1] += __uint_as_float(u.x & 0xffff0000u);
;         O[a][2] += __uint_as_float(u.y << 16); O[a][3] += __uint_as_float(u.y & 0xffff0000u);
; #pragma unroll
;         for (int j = 0; j < 4; ++j) ss += O[a][j] * O[a][j];
.LBB0_683:
	s_or_b64 exec, exec, s[0:1]
	ds_read_b128 v[42:45], v240 offset:32768
	ds_read_b128 v[46:49], v238 offset:57344
	ds_read_b128 v[50:53], v238 offset:59392
	s_add_i32 s0, s13, -1
	v_mov_b32_e32 v40, s0
	v_cndmask_b32_e64 v40, v91, v40, s[24:25]
	s_waitcnt lgkmcnt(1)
	v_mfma_f32_16x16x32_bf16 v[46:49], v[46:49], v[42:45], v[56:59]
	v_lshlrev_b32_e32 v40, 6, v40
	v_add_u32_e32 v160, s12, v40
	v_lshl_add_u64 v[40:41], v[160:161], 0, v[82:83]
	ds_read_b128 v[54:57], v238 offset:61440
	s_waitcnt lgkmcnt(1)
	v_mfma_f32_16x16x32_bf16 v[50:53], v[50:53], v[42:45], v[60:63]
	s_nop 2
	ds_read_b128 v[58:61], v238 offset:63488
	s_waitcnt lgkmcnt(1)
	v_mfma_f32_16x16x32_bf16 v[54:57], v[54:57], v[42:45], v[64:67]
	s_waitcnt lgkmcnt(0)
	v_mfma_f32_16x16x32_bf16 v[42:45], v[58:61], v[42:45], v[72:75]
	ds_read_b128 v[58:61], v239 offset:32768
	ds_read_b128 v[62:65], v237 offset:57344
	s_waitcnt lgkmcnt(0)
	v_mfma_f32_16x16x32_bf16 v[46:49], v[62:65], v[58:61], v[46:49]
	ds_read_b128 v[62:65], v237 offset:59392
	s_waitcnt lgkmcnt(0)
	v_mfma_f32_16x16x32_bf16 v[50:53], v[62:65], v[58:61], v[50:53]
	ds_read_b128 v[62:65], v237 offset:61440
	s_waitcnt lgkmcnt(0)
	v_mfma_f32_16x16x32_bf16 v[62:65], v[62:65], v[58:61], v[54:57]
	s_nop 2
	ds_read_b128 v[54:57], v237 offset:63488
	s_waitcnt lgkmcnt(0)
	v_mfma_f32_16x16x32_bf16 v[42:45], v[54:57], v[58:61], v[42:45]
	v_add_f32_e32 v54, v93, v96
	v_max_f32_e64 v54, |v54|, 1.0
	v_rcp_f32_e32 v56, v54
	s_mov_b64 s[0:1], -1
	v_fma_f32 v57, -v54, v56, 1.0
	v_fmac_f32_e32 v56, v57, v56
	v_mov_b32_e64 v57, 1.0
	v_mul_f32_e32 v58, v57, v56
	v_fma_f32 v59, -v54, v58, v57
	v_fmac_f32_e32 v58, v59, v56
	v_fma_f32 v55, -v54, v58, v57
	v_fma_f32 v55, v55, v56, v58
	v_div_fixup_f32 v60, v55, v54, 1.0
	v_pk_mul_f32 v[54:55], v[60:61], v[46:47] op_sel_hi:[0,1]
	v_pk_mul_f32 v[46:47], v[60:61], v[42:43] op_sel_hi:[0,1]
	v_ashrrev_i32_e32 v43, 31, v40
	v_mov_b32_e32 v42, v40
	v_pk_mul_f32 v[58:59], v[60:61], v[48:49] op_sel_hi:[0,1]
	v_pk_mul_f32 v[50:51], v[60:61], v[50:51] op_sel_hi:[0,1]
	v_pk_mul_f32 v[56:57], v[60:61], v[52:53] op_sel_hi:[0,1]
	v_pk_mul_f32 v[48:49], v[60:61], v[62:63] op_sel_hi:[0,1]
	v_pk_mul_f32 v[52:53], v[60:61], v[64:65] op_sel_hi:[0,1]
	v_pk_mul_f32 v[44:45], v[60:61], v[44:45] op_sel_hi:[0,1]
	v_lshl_add_u64 v[60:61], v[42:43], 0, s[28:29]
	v_lshl_add_u64 v[62:63], v[42:43], 0, s[30:31]
	v_lshl_add_u64 v[42:43], v[42:43], 0, s[42:43]
	s_andn2_b64 vcc, exec, s[44:45]
	v_lshlrev_b64 v[64:65], 6, v[60:61]
	v_lshlrev_b64 v[62:63], 6, v[62:63]
	v_lshlrev_b64 v[60:61], 6, v[42:43]
	s_cbranch_vccnz .LBB0_685
	v_lshl_add_u64 v[98:99], v[88:89], 0, v[62:63]
	global_load_dwordx2 v[66:67], v[98:99], off
	v_mov_b64_e32 v[42:43], s[18:19]
	v_mad_u64_u32 v[42:43], s[0:1], v40, s33, v[42:43]
	v_mad_i32_i24 v43, v41, s33, v43
	s_mov_b64 s[0:1], 0x1a20
	v_mov_b32_e32 v91, v161
	v_lshl_add_u64 v[74:75], v[42:43], 0, s[0:1]
	v_lshl_add_u64 v[100:101], v[74:75], 0, s[2:3]
	v_lshl_add_u64 v[74:75], v[74:75], 0, v[90:91]
	v_lshl_add_u64 v[102:103], v[84:85], 0, v[64:65]
	v_lshl_add_u64 v[74:75], v[74:75], 0, s[2:3]
	global_load_dwordx2 v[40:41], v[102:103], off
	s_mov_b32 s21, s3
	v_lshl_add_u64 v[42:43], v[42:43], 0, s[20:21]
	v_lshl_add_u64 v[42:43], v[42:43], 0, v[90:91]
	s_mov_b64 s[0:1], 0x1820
	v_lshl_add_u64 v[100:101], v[100:101], 0, v[90:91]
	global_load_dwordx2 v[74:75], v[74:75], off
	s_waitcnt vmcnt(0) lgkmcnt(0)
	v_lshlrev_b32_e32 v96, 16, v66
	v_and_b32_e32 v97, 0xffff0000, v66
	v_lshlrev_b32_e32 v104, 16, v67
	v_and_b32_e32 v105, 0xffff0000, v67
	v_lshl_add_u64 v[66:67], s[22:23], 0, v[60:61]
	v_lshl_add_u64 v[72:73], v[66:67], 0, v[90:91]
	global_load_dwordx2 v[68:69], v[72:73], off
	v_pk_add_f32 v[246:247], v[50:51], v[96:97]
	v_lshlrev_b32_e32 v124, 16, v40
	v_and_b32_e32 v125, 0xffff0000, v40
	v_lshlrev_b32_e32 v40, 16, v41
	v_and_b32_e32 v41, 0xffff0000, v41
	v_pk_add_f32 v[124:125], v[54:55], v[124:125]
	v_pk_mul_f32 v[96:97], v[246:247], v[246:247]
	v_lshlrev_b32_e32 v93, 16, v74
	v_and_b32_e32 v160, 0xffff0000, v74
	v_lshlrev_b32_e32 v126, 16, v75
	v_and_b32_e32 v127, 0xffff0000, v75
	v_lshl_add_u64 v[74:75], v[42:43], 0, s[0:1]
	v_add_co_u32_e32 v42, vcc, s16, v42
	v_mul_f32_e32 v116, 0xbfb8aa3b, v126
	s_nop 0
	v_addc_co_u32_e32 v43, vcc, 0, v43, vcc
	v_mul_f32_e32 v117, 0xbfb8aa3b, v127
	global_load_dwordx2 v[42:43], v[42:43], off offset:2080
	v_exp_f32_e32 v116, v116
	v_exp_f32_e32 v117, v117
	s_waitcnt vmcnt(0) lgkmcnt(0)
; DI size_t kblk(int row, int col, int nrows) { return ((size_t)(col >> 5) * nrows + row) * 32 + (col & 31); }
; DI unsigned pk2(float a, float b) { hwf32x2 f = {a, b}; hwbf16x2 r = __builtin_convertvector(f, hwbf16x2); return __builtin_bit_cast(unsigned, r); }
; DI float sigmoidf_(float z) { return 1.f / (1.f + __expf(-z)); }
; DI float siluf_(float z) { return z / (1.f + __expf(-z)); }
; template <int MX, bool OUT>
; DI void rec_chunk(const Params& p, int l, int b, int h, int dir, int T0, unsigned char* smem, f32x4 (&St)[4], float& nst, float& dtot, int tid, const RecRaw& raw) {
;     ...
;       float ss = 0.f;
; #pragma unroll
;       for (int a = 0; a < 4; ++a) {
;         const uint2 u = *(const uint2*)(MIX + kblk((int)orow, cb + 16 * a + 4 * g, ROWS));
;         O[a][0] += __uint_as_float(u.x << 16); O[a][1] += __uint_as_float(u.x & 0xffff0000u);
;         O[a][2] += __uint_as_float(u.y << 16); O[a][3] += __uint_as_float(u.y & 0xffff0000u);
; #pragma unroll
;         for (int j = 0; j < 4; ++j) ss += O[a][j] * O[a][j];
;       }
;       ss += __shfl_xor(ss, 16);
;       ss += __shfl_xor(ss, 32);
;       const float rstd = rsqrtf(ss * (1.f / 64.f) + EPS);
;       const float* gvec = (MX ? p.ml_g : p.hg_g) + l * 64;
; #pragma unroll
;       for (int a = 0; a < 4; ++a) {
;         const int v0 = 16 * a + 4 * g;
;         const uint2 gt = *(const uint2*)(prow + GATE + cb + v0);
;         const float4 gg = *(const float4*)(gvec + v0);
;         float y0 = O[a][0] * rstd * gg.x * siluf_(__uint_as_float(gt.x << 16));
;         float y1 = O[a][1] * rstd * gg.y * siluf_(__uint_as_float(gt.x & 0xffff0000u));
;         float y2 = O[a][2] * rstd * gg.z * siluf_(__uint_as_float(gt.y << 16));
;         float y3 = O[a][3] * rstd * gg.w * siluf_(__uint_as_float(gt.y & 0xffff0000u));
;         if (MX == 1) {
;           const uint2 og = *(const uint2*)(prow + D_OG + h * 64 + v0);
;           y0 *= sigmoidf_(__uint_as_float(og.x << 16)); y1 *= sigmoidf_(__uint_as_float(og.x & 0xffff0000u));
;           y2 *= sigmoidf_(__uint_as_float(og.y << 16)); y3 *= sigmoidf_(__uint_as_float(og.y & 0xffff0000u));
;         }
;         *(uint2*)(MIX + kblk((int)orow, cb + v0, ROWS)) = make_uint2(pk2(y0, y1), pk2(y2, y3));
	v_lshlrev_b32_e32 v106, 16, v68
	v_and_b32_e32 v107, 0xffff0000, v68
	v_pk_add_f32 v[116:117], v[116:117], 1.0 op_sel_hi:[1,0]
	v_lshlrev_b32_e32 v108, 16, v69
	v_rcp_f32_e32 v129, v117
	v_and_b32_e32 v109, 0xffff0000, v69
	global_load_dwordx2 v[68:69], v[72:73], off offset:32
	v_pk_add_f32 v[106:107], v[48:49], v[106:107]
	v_fma_f32 v241, -v117, v129, 1.0
	v_fmac_f32_e32 v129, v241, v129
	v_mul_f32_e32 v242, v127, v129
	v_fma_f32 v243, -v117, v242, v127
	v_fmac_f32_e32 v242, v243, v129
	v_fma_f32 v128, -v117, v242, v127
	v_fma_f32 v128, v128, v129, v242
	v_div_fixup_f32 v117, v128, v117, v127
	v_rcp_f32_e32 v128, v116
	v_pk_mul_f32 v[248:249], v[106:107], v[106:107]
	v_lshlrev_b32_e32 v114, 16, v42
	v_and_b32_e32 v42, 0xffff0000, v42
	v_fma_f32 v129, -v116, v128, 1.0
	v_fmac_f32_e32 v128, v129, v128
	v_mul_f32_e32 v241, v126, v128
	v_fma_f32 v242, -v116, v241, v126
	v_fmac_f32_e32 v241, v242, v128
	v_fma_f32 v127, -v116, v241, v126
	v_fma_f32 v127, v127, v128, v241
	v_mul_f32_e32 v128, 0xbfb8aa3b, v93
	v_mul_f32_e32 v129, 0xbfb8aa3b, v160
	v_exp_f32_e32 v128, v128
	v_exp_f32_e32 v129, v129
	v_div_fixup_f32 v116, v127, v116, v126
	v_pk_mul_f32 v[126:127], v[124:125], v[124:125]
	v_mul_f32_e32 v114, 0xbfb8aa3b, v114
	v_pk_add_f32 v[128:129], v[128:129], 1.0 op_sel_hi:[1,0]
	v_mul_f32_e32 v42, 0xbfb8aa3b, v42
	v_rcp_f32_e32 v242, v129
	v_add_f32_e32 v91, v126, v127
	v_exp_f32_e32 v122, v114
	v_exp_f32_e32 v123, v42
	v_fma_f32 v243, -v129, v242, 1.0
	v_fmac_f32_e32 v242, v243, v242
	v_mul_f32_e32 v244, v160, v242
	v_fma_f32 v245, -v129, v244, v160
	v_fmac_f32_e32 v244, v245, v242
	v_fma_f32 v241, -v129, v244, v160
	v_fma_f32 v241, v241, v242, v244
	v_div_fixup_f32 v129, v241, v129, v160
	v_rcp_f32_e32 v241, v128
	v_lshlrev_b32_e32 v42, 16, v43
	v_pk_add_f32 v[114:115], v[58:59], v[40:41]
	v_mul_f32_e32 v42, 0xbfb8aa3b, v42
	v_fma_f32 v242, -v128, v241, 1.0
	v_fmac_f32_e32 v241, v242, v241
	v_mul_f32_e32 v243, v93, v241
	v_fma_f32 v244, -v128, v243, v93
	v_fmac_f32_e32 v243, v244, v241
	v_fma_f32 v160, -v128, v243, v93
	v_fma_f32 v160, v160, v241, v243
	v_div_fixup_f32 v128, v160, v128, v93
	v_pk_mul_f32 v[118:119], v[114:115], v[114:115]
	v_exp_f32_e32 v120, v42
	v_and_b32_e32 v42, 0xffff0000, v43
	v_add_f32_e32 v91, v91, v118
	v_mul_f32_e32 v42, 0xbfb8aa3b, v42
	v_add_f32_e32 v91, v119, v91
	v_pk_add_f32 v[122:123], v[122:123], 1.0 op_sel_hi:[1,0]
	v_exp_f32_e32 v121, v42
	global_load_dwordx4 v[40:43], v[86:87], off
	v_rcp_f32_e32 v160, v123
	v_pk_add_f32 v[120:121], v[120:121], 1.0 op_sel_hi:[1,0]
	v_add_f32_e32 v91, v96, v91
	v_add_f32_e32 v91, v97, v91
	v_fma_f32 v241, -v123, v160, 1.0
	v_fmac_f32_e32 v160, v241, v160
	v_mov_b32_e64 v241, 1.0
	v_mul_f32_e32 v242, v241, v160
	v_fma_f32 v243, -v123, v242, v241
	v_fmac_f32_e32 v242, v243, v160
	v_fma_f32 v93, -v123, v242, v241
	v_fma_f32 v93, v93, v160, v242
	v_div_fixup_f32 v123, v93, v123, 1.0
	v_rcp_f32_e32 v160, v122
	s_waitcnt vmcnt(0) lgkmcnt(0)
	v_lshlrev_b32_e32 v70, 16, v68
	v_and_b32_e32 v71, 0xffff0000, v68
	v_pk_add_f32 v[70:71], v[46:47], v[70:71]
	v_fma_f32 v241, -v122, v160, 1.0
	v_fmac_f32_e32 v160, v241, v160
	v_mov_b32_e64 v241, 1.0
	v_mul_f32_e32 v242, v241, v160
	v_fma_f32 v243, -v122, v242, v241
	v_fmac_f32_e32 v242, v243, v160
	v_fma_f32 v93, -v122, v242, v241
	v_fma_f32 v93, v93, v160, v242
	v_div_fixup_f32 v122, v93, v122, 1.0
	v_rcp_f32_e32 v160, v121
	v_lshlrev_b32_e32 v68, 16, v69
	v_and_b32_e32 v69, 0xffff0000, v69
	v_pk_mul_f32 v[110:111], v[70:71], v[70:71]
	v_fma_f32 v241, -v121, v160, 1.0
	v_fmac_f32_e32 v160, v241, v160
	v_mov_b32_e64 v241, 1.0
	v_mul_f32_e32 v242, v241, v160
	v_fma_f32 v243, -v121, v242, v241
	v_fmac_f32_e32 v242, v243, v160
	v_fma_f32 v93, -v121, v242, v241
	v_fma_f32 v93, v93, v160, v242
	v_div_fixup_f32 v121, v93, v121, 1.0
	v_rcp_f32_e32 v160, v120
	v_pk_add_f32 v[68:69], v[44:45], v[68:69]
	v_fma_f32 v241, -v120, v160, 1.0
	v_fmac_f32_e32 v160, v241, v160
	v_mov_b32_e64 v241, 1.0
	v_mul_f32_e32 v242, v241, v160
	v_fma_f32 v243, -v120, v242, v241
	v_fmac_f32_e32 v242, v243, v160
	v_fma_f32 v93, -v120, v242, v241
	v_fma_f32 v93, v93, v160, v242
	v_pk_add_f32 v[242:243], v[56:57], v[104:105]
	v_pk_add_f32 v[104:105], v[52:53], v[108:109]
	v_pk_mul_f32 v[244:245], v[242:243], v[242:243]
	v_pk_mul_f32 v[108:109], v[104:105], v[104:105]
	v_add_f32_e32 v91, v244, v91
	v_add_f32_e32 v91, v245, v91
	v_add_f32_e32 v91, v248, v91
	v_add_f32_e32 v91, v249, v91
	v_add_f32_e32 v91, v108, v91
	v_add_f32_e32 v91, v109, v91
	v_add_f32_e32 v91, v110, v91
	v_pk_mul_f32 v[112:113], v[68:69], v[68:69]
	v_add_f32_e32 v91, v111, v91
	v_add_f32_e32 v91, v112, v91
	v_add_f32_e32 v91, v113, v91
	v_div_fixup_f32 v120, v93, v120, 1.0
	ds_bpermute_b32 v93, v145, v91
	s_waitcnt lgkmcnt(0)
	v_add_f32_e32 v91, v91, v93
	ds_bpermute_b32 v93, v146, v91
	s_waitcnt lgkmcnt(0)
	v_add_f32_e32 v91, v91, v93
	v_fmamk_f32 v91, v91, 0x3c800000, v162
	v_cmp_gt_f32_e32 vcc, s38, v91
	v_mul_f32_e32 v93, 0x4b800000, v91
	s_nop 0
	v_cndmask_b32_e32 v91, v91, v93, vcc
	v_rsq_f32_e32 v91, v91
	s_nop 0
	v_mul_f32_e32 v93, 0x45800000, v91
	v_cndmask_b32_e32 v96, v91, v93, vcc
	v_pk_mul_f32 v[108:109], v[124:125], v[96:97] op_sel_hi:[1,0]
	s_nop 0
	v_pk_mul_f32 v[40:41], v[40:41], v[108:109]
	v_pk_mul_f32 v[108:109], v[114:115], v[96:97] op_sel_hi:[1,0]
	v_pk_mul_f32 v[40:41], v[128:129], v[40:41]
	v_pk_mul_f32 v[42:43], v[42:43], v[108:109]
	v_pk_mul_f32 v[40:41], v[122:123], v[40:41]
	v_pk_mul_f32 v[42:43], v[116:117], v[42:43]
	v_cvt_pk_bf16_f32 v40, v40, v41
	v_pk_mul_f32 v[42:43], v[120:121], v[42:43]
	s_nop 0
	v_cvt_pk_bf16_f32 v41, v42, v43
	global_store_dwordx2 v[102:103], v[40:41], off
	global_load_dwordx2 v[40:41], v[100:101], off offset:32
	s_nop 0
	global_load_dwordx4 v[108:111], v[86:87], off offset:64
	v_pk_mul_f32 v[102:103], v[246:247], v[96:97] op_sel_hi:[1,0]
	s_waitcnt vmcnt(0) lgkmcnt(0)
; DI size_t kblk(int row, int col, int nrows) { return ((size_t)(col >> 5) * nrows + row) * 32 + (col & 31); }
; DI unsigned pk2(float a, float b) { hwf32x2 f = {a, b}; hwbf16x2 r = __builtin_convertvector(f, hwbf16x2); return __builtin_bit_cast(unsigned, r); }
; DI float sigmoidf_(float z) { return 1.f / (1.f + __expf(-z)); }
; DI float siluf_(float z) { return z / (1.f + __expf(-z)); }
; template <int MX, bool OUT>
; DI void rec_chunk(const Params& p, int l, int b, int h, int dir, int T0, unsigned char* smem, f32x4 (&St)[4], float& nst, float& dtot, int tid, const RecRaw& raw) {
;     ...
;       for (int a = 0; a < 4; ++a) {
;         const int v0 = 16 * a + 4 * g;
;         const uint2 gt = *(const uint2*)(prow + GATE + cb + v0);
;         const float4 gg = *(const float4*)(gvec + v0);
;         float y0 = O[a][0] * rstd * gg.x * siluf_(__uint_as_float(gt.x << 16));
;         float y1 = O[a][1] * rstd * gg.y * siluf_(__uint_as_float(gt.x & 0xffff0000u));
;         float y2 = O[a][2] * rstd * gg.z * siluf_(__uint_as_float(gt.y << 16));
;         float y3 = O[a][3] * rstd * gg.w * siluf_(__uint_as_float(gt.y & 0xffff0000u));
;         if (MX == 1) {
;           const uint2 og = *(const uint2*)(prow + D_OG + h * 64 + v0);
;           y0 *= sigmoidf_(__uint_as_float(og.x << 16)); y1 *= sigmoidf_(__uint_as_float(og.x & 0xffff0000u));
;           y2 *= sigmoidf_(__uint_as_float(og.y << 16)); y3 *= sigmoidf_(__uint_as_float(og.y & 0xffff0000u));
;         }
;         *(uint2*)(MIX + kblk((int)orow, cb + v0, ROWS)) = make_uint2(pk2(y0, y1), pk2(y2, y3));
	v_lshlrev_b32_e32 v91, 16, v40
	v_and_b32_e32 v40, 0xffff0000, v40
	v_mul_f32_e32 v42, 0xbfb8aa3b, v91
	v_mul_f32_e32 v43, 0xbfb8aa3b, v40
	v_exp_f32_e32 v42, v42
	v_exp_f32_e32 v43, v43
	v_pk_mul_f32 v[102:103], v[108:109], v[102:103]
	v_pk_add_f32 v[42:43], v[42:43], 1.0 op_sel_hi:[1,0]
	s_nop 0
	v_rcp_f32_e32 v97, v43
	s_nop 0
	v_fma_f32 v108, -v43, v97, 1.0
	v_fmac_f32_e32 v97, v108, v97
	v_mul_f32_e32 v109, v40, v97
	v_fma_f32 v112, -v43, v109, v40
	v_fmac_f32_e32 v109, v112, v97
	v_fma_f32 v93, -v43, v109, v40
	v_fma_f32 v93, v93, v97, v109
	v_div_fixup_f32 v43, v93, v43, v40
	v_rcp_f32_e32 v93, v42
	s_nop 0
	v_fma_f32 v97, -v42, v93, 1.0
	v_fmac_f32_e32 v93, v97, v93
	v_mul_f32_e32 v108, v91, v93
	v_fma_f32 v109, -v42, v108, v91
	v_fmac_f32_e32 v108, v109, v93
	v_fma_f32 v40, -v42, v108, v91
	v_fma_f32 v40, v40, v93, v108
	v_div_fixup_f32 v42, v40, v42, v91
	v_lshlrev_b32_e32 v91, 16, v41
	v_and_b32_e32 v93, 0xffff0000, v41
	v_mul_f32_e32 v40, 0xbfb8aa3b, v91
	v_mul_f32_e32 v41, 0xbfb8aa3b, v93
	v_exp_f32_e32 v40, v40
	v_exp_f32_e32 v41, v41
	v_pk_mul_f32 v[42:43], v[42:43], v[102:103]
	v_pk_mul_f32 v[102:103], v[242:243], v[96:97] op_sel_hi:[1,0]
	v_pk_add_f32 v[40:41], v[40:41], 1.0 op_sel_hi:[1,0]
	s_nop 0
	v_rcp_f32_e32 v108, v41
	v_pk_mul_f32 v[102:103], v[110:111], v[102:103]
	v_fma_f32 v109, -v41, v108, 1.0
	v_fmac_f32_e32 v108, v109, v108
	v_mul_f32_e32 v110, v93, v108
	v_fma_f32 v111, -v41, v110, v93
	v_fmac_f32_e32 v110, v111, v108
	v_fma_f32 v97, -v41, v110, v93
	v_fma_f32 v97, v97, v108, v110
	v_div_fixup_f32 v41, v97, v41, v93
	v_rcp_f32_e32 v97, v40
	s_nop 0
	v_fma_f32 v108, -v40, v97, 1.0
	v_fmac_f32_e32 v97, v108, v97
	v_mul_f32_e32 v109, v91, v97
	v_fma_f32 v110, -v40, v109, v91
	v_fmac_f32_e32 v109, v110, v97
	v_fma_f32 v93, -v40, v109, v91
	v_fma_f32 v93, v93, v97, v109
	v_div_fixup_f32 v40, v93, v40, v91
	v_pk_mul_f32 v[40:41], v[40:41], v[102:103]
	global_load_dwordx2 v[102:103], v[74:75], off offset:32
	s_waitcnt vmcnt(0) lgkmcnt(0)
	v_lshlrev_b32_e32 v91, 16, v102
	v_mul_f32_e32 v91, 0xbfb8aa3b, v91
	v_exp_f32_e32 v108, v91
	v_and_b32_e32 v91, 0xffff0000, v102
	v_mul_f32_e32 v91, 0xbfb8aa3b, v91
	v_exp_f32_e32 v109, v91
	s_nop 0
	v_pk_add_f32 v[108:109], v[108:109], 1.0 op_sel_hi:[1,0]
	s_nop 0
	v_rcp_f32_e32 v93, v109
	s_nop 0
	v_fma_f32 v97, -v109, v93, 1.0
	v_fmac_f32_e32 v93, v97, v93
	v_mov_b32_e64 v97, 1.0
	v_mul_f32_e32 v102, v97, v93
	v_fma_f32 v110, -v109, v102, v97
	v_fmac_f32_e32 v102, v110, v93
	v_fma_f32 v91, -v109, v102, v97
	v_fma_f32 v91, v91, v93, v102
	v_div_fixup_f32 v109, v91, v109, 1.0
	v_rcp_f32_e32 v93, v108
	s_nop 0
	v_fma_f32 v97, -v108, v93, 1.0
	v_fmac_f32_e32 v93, v97, v93
	v_mov_b32_e64 v97, 1.0
	v_mul_f32_e32 v102, v97, v93
	v_fma_f32 v110, -v108, v102, v97
	v_fmac_f32_e32 v102, v110, v93
	v_fma_f32 v91, -v108, v102, v97
	v_fma_f32 v91, v91, v93, v102
	v_div_fixup_f32 v108, v91, v108, 1.0
	v_lshlrev_b32_e32 v91, 16, v103
	v_mul_f32_e32 v91, 0xbfb8aa3b, v91
	v_exp_f32_e32 v102, v91
	v_and_b32_e32 v91, 0xffff0000, v103
	v_mul_f32_e32 v91, 0xbfb8aa3b, v91
	v_exp_f32_e32 v103, v91
	v_pk_mul_f32 v[42:43], v[42:43], v[108:109]
	v_pk_add_f32 v[102:103], v[102:103], 1.0 op_sel_hi:[1,0]
	s_nop 0
	v_rcp_f32_e32 v93, v103
	v_cvt_pk_bf16_f32 v42, v42, v43
	v_fma_f32 v97, -v103, v93, 1.0
	v_fmac_f32_e32 v93, v97, v93
	v_mov_b32_e64 v97, 1.0
	v_mul_f32_e32 v108, v97, v93
	v_fma_f32 v109, -v103, v108, v97
	v_fmac_f32_e32 v108, v109, v93
	v_fma_f32 v91, -v103, v108, v97
	v_fma_f32 v91, v91, v93, v108
	v_div_fixup_f32 v103, v91, v103, 1.0
	v_rcp_f32_e32 v93, v102
	s_nop 0
	v_fma_f32 v97, -v102, v93, 1.0
	v_fmac_f32_e32 v93, v97, v93
	v_mov_b32_e64 v97, 1.0
	v_mul_f32_e32 v108, v97, v93
	v_fma_f32 v109, -v102, v108, v97
	v_fmac_f32_e32 v108, v109, v93
	v_fma_f32 v91, -v102, v108, v97
	v_fma_f32 v91, v91, v93, v108
	v_div_fixup_f32 v102, v91, v102, 1.0
	v_pk_mul_f32 v[40:41], v[40:41], v[102:103]
	s_nop 0
	v_cvt_pk_bf16_f32 v43, v40, v41
	global_store_dwordx2 v[98:99], v[42:43], off
	global_load_dwordx2 v[40:41], v[100:101], off offset:64
	global_load_dwordx4 v[108:111], v[86:87], off offset:128
	v_pk_mul_f32 v[98:99], v[106:107], v[96:97] op_sel_hi:[1,0]
	s_waitcnt vmcnt(0) lgkmcnt(0)
	v_lshlrev_b32_e32 v91, 16, v40
	v_and_b32_e32 v40, 0xffff0000, v40
	v_mul_f32_e32 v42, 0xbfb8aa3b, v91
	v_mul_f32_e32 v43, 0xbfb8aa3b, v40
	v_exp_f32_e32 v42, v42
	v_exp_f32_e32 v43, v43
	v_pk_mul_f32 v[98:99], v[98:99], v[108:109]
	v_pk_add_f32 v[42:43], v[42:43], 1.0 op_sel_hi:[1,0]
	s_nop 0
	v_rcp_f32_e32 v97, v43
	s_nop 0
	v_fma_f32 v102, -v43, v97, 1.0
	v_fmac_f32_e32 v97, v102, v97
	v_mul_f32_e32 v103, v40, v97
	v_fma_f32 v106, -v43, v103, v40
	v_fmac_f32_e32 v103, v106, v97
	v_fma_f32 v93, -v43, v103, v40
	v_fma_f32 v93, v93, v97, v103
	v_div_fixup_f32 v43, v93, v43, v40
	v_rcp_f32_e32 v93, v42
	s_nop 0
	v_fma_f32 v97, -v42, v93, 1.0
	v_fmac_f32_e32 v93, v97, v93
	v_mul_f32_e32 v102, v91, v93
	v_fma_f32 v103, -v42, v102, v91
	v_fmac_f32_e32 v102, v103, v93
	v_fma_f32 v40, -v42, v102, v91
	v_fma_f32 v40, v40, v93, v102
	v_div_fixup_f32 v42, v40, v42, v91
	v_lshlrev_b32_e32 v91, 16, v41
	v_and_b32_e32 v93, 0xffff0000, v41
	v_mul_f32_e32 v40, 0xbfb8aa3b, v91
	v_mul_f32_e32 v41, 0xbfb8aa3b, v93
	v_exp_f32_e32 v40, v40
	v_exp_f32_e32 v41, v41
	v_pk_mul_f32 v[42:43], v[98:99], v[42:43]
	v_pk_mul_f32 v[98:99], v[104:105], v[96:97] op_sel_hi:[1,0]
	v_pk_add_f32 v[40:41], v[40:41], 1.0 op_sel_hi:[1,0]
	s_nop 0
	v_rcp_f32_e32 v102, v41
	v_pk_mul_f32 v[98:99], v[98:99], v[110:111]
	v_fma_f32 v103, -v41, v102, 1.0
	v_fmac_f32_e32 v102, v103, v102
	v_mul_f32_e32 v104, v93, v102
	v_fma_f32 v105, -v41, v104, v93
	v_fmac_f32_e32 v104, v105, v102
	v_fma_f32 v97, -v41, v104, v93
	v_fma_f32 v97, v97, v102, v104
	v_div_fixup_f32 v41, v97, v41, v93
	v_rcp_f32_e32 v97, v40
	s_nop 0
	v_fma_f32 v102, -v40, v97, 1.0
	v_fmac_f32_e32 v97, v102, v97
	v_mul_f32_e32 v103, v91, v97
	v_fma_f32 v104, -v40, v103, v91
	v_fmac_f32_e32 v103, v104, v97
	v_fma_f32 v93, -v40, v103, v91
	v_fma_f32 v93, v93, v97, v103
	v_div_fixup_f32 v40, v93, v40, v91
	v_pk_mul_f32 v[40:41], v[98:99], v[40:41]
	global_load_dwordx2 v[98:99], v[74:75], off offset:64
	s_waitcnt vmcnt(0) lgkmcnt(0)
; DI size_t kblk(int row, int col, int nrows) { return ((size_t)(col >> 5) * nrows + row) * 32 + (col & 31); }
; DI unsigned pk2(float a, float b) { hwf32x2 f = {a, b}; hwbf16x2 r = __builtin_convertvector(f, hwbf16x2); return __builtin_bit_cast(unsigned, r); }
; DI float sigmoidf_(float z) { return 1.f / (1.f + __expf(-z)); }
; DI float siluf_(float z) { return z / (1.f + __expf(-z)); }
; template <int MX, bool OUT>
; DI void rec_chunk(const Params& p, int l, int b, int h, int dir, int T0, unsigned char* smem, f32x4 (&St)[4], float& nst, float& dtot, int tid, const RecRaw& raw) {
;     ...
;       for (int a = 0; a < 4; ++a) {
;         const int v0 = 16 * a + 4 * g;
;         const uint2 gt = *(const uint2*)(prow + GATE + cb + v0);
;         const float4 gg = *(const float4*)(gvec + v0);
;         float y0 = O[a][0] * rstd * gg.x * siluf_(__uint_as_float(gt.x << 16));
;         float y1 = O[a][1] * rstd * gg.y * siluf_(__uint_as_float(gt.x & 0xffff0000u));
;         float y2 = O[a][2] * rstd * gg.z * siluf_(__uint_as_float(gt.y << 16));
;         float y3 = O[a][3] * rstd * gg.w * siluf_(__uint_as_float(gt.y & 0xffff0000u));
;         if (MX == 1) {
;           const uint2 og = *(const uint2*)(prow + D_OG + h * 64 + v0);
;           y0 *= sigmoidf_(__uint_as_float(og.x << 16)); y1 *= sigmoidf_(__uint_as_float(og.x & 0xffff0000u));
;           y2 *= sigmoidf_(__uint_as_float(og.y << 16)); y3 *= sigmoidf_(__uint_as_float(og.y & 0xffff0000u));
;         }
;         *(uint2*)(MIX + kblk((int)orow, cb + v0, ROWS)) = make_uint2(pk2(y0, y1), pk2(y2, y3));
	v_lshlrev_b32_e32 v91, 16, v98
	v_mul_f32_e32 v91, 0xbfb8aa3b, v91
	v_exp_f32_e32 v102, v91
	v_and_b32_e32 v91, 0xffff0000, v98
	v_mul_f32_e32 v91, 0xbfb8aa3b, v91
	v_exp_f32_e32 v103, v91
	s_nop 0
	v_pk_add_f32 v[102:103], v[102:103], 1.0 op_sel_hi:[1,0]
	s_nop 0
	v_rcp_f32_e32 v93, v103
	s_nop 0
	v_fma_f32 v97, -v103, v93, 1.0
	v_fmac_f32_e32 v93, v97, v93
	v_mov_b32_e64 v97, 1.0
	v_mul_f32_e32 v98, v97, v93
	v_fma_f32 v104, -v103, v98, v97
	v_fmac_f32_e32 v98, v104, v93
	v_fma_f32 v91, -v103, v98, v97
	v_fma_f32 v91, v91, v93, v98
	v_div_fixup_f32 v103, v91, v103, 1.0
	v_rcp_f32_e32 v93, v102
	s_nop 0
	v_fma_f32 v97, -v102, v93, 1.0
	v_fmac_f32_e32 v93, v97, v93
	v_mov_b32_e64 v97, 1.0
	v_mul_f32_e32 v98, v97, v93
	v_fma_f32 v104, -v102, v98, v97
	v_fmac_f32_e32 v98, v104, v93
	v_fma_f32 v91, -v102, v98, v97
	v_fma_f32 v91, v91, v93, v98
	v_div_fixup_f32 v102, v91, v102, 1.0
	v_lshlrev_b32_e32 v91, 16, v99
	v_mul_f32_e32 v91, 0xbfb8aa3b, v91
	v_exp_f32_e32 v98, v91
	v_and_b32_e32 v91, 0xffff0000, v99
	v_mul_f32_e32 v91, 0xbfb8aa3b, v91
	v_exp_f32_e32 v99, v91
	v_pk_mul_f32 v[42:43], v[42:43], v[102:103]
	v_pk_add_f32 v[98:99], v[98:99], 1.0 op_sel_hi:[1,0]
	s_nop 0
	v_rcp_f32_e32 v93, v99
	v_cvt_pk_bf16_f32 v42, v42, v43
	v_fma_f32 v97, -v99, v93, 1.0
	v_fmac_f32_e32 v93, v97, v93
	v_mov_b32_e64 v97, 1.0
	v_mul_f32_e32 v102, v97, v93
	v_fma_f32 v103, -v99, v102, v97
	v_fmac_f32_e32 v102, v103, v93
	v_fma_f32 v91, -v99, v102, v97
	v_fma_f32 v91, v91, v93, v102
	v_div_fixup_f32 v99, v91, v99, 1.0
	v_rcp_f32_e32 v93, v98
	s_nop 0
	v_fma_f32 v97, -v98, v93, 1.0
	v_fmac_f32_e32 v93, v97, v93
	v_mov_b32_e64 v97, 1.0
	v_mul_f32_e32 v102, v97, v93
	v_fma_f32 v103, -v98, v102, v97
	v_fmac_f32_e32 v102, v103, v93
	v_fma_f32 v91, -v98, v102, v97
	v_fma_f32 v91, v91, v93, v102
	v_div_fixup_f32 v98, v91, v98, 1.0
	v_pk_mul_f32 v[40:41], v[40:41], v[98:99]
	s_nop 0
	v_cvt_pk_bf16_f32 v43, v40, v41
	global_store_dwordx2 v[72:73], v[42:43], off
	global_load_dwordx2 v[40:41], v[100:101], off offset:96
	s_nop 0
	global_load_dwordx2 v[74:75], v[74:75], off offset:96
	s_waitcnt vmcnt(0) lgkmcnt(0)
	v_lshlrev_b32_e32 v73, 16, v40
	v_and_b32_e32 v91, 0xffff0000, v40
	v_lshlrev_b32_e32 v40, 16, v41
	v_mul_f32_e32 v42, 0xbfb8aa3b, v40
	v_exp_f32_e32 v42, v42
	s_nop 0
	v_add_f32_e32 v42, 1.0, v42
	v_rcp_f32_e32 v72, v42
	s_nop 0
	v_fma_f32 v93, -v42, v72, 1.0
	v_fmac_f32_e32 v72, v93, v72
	v_mul_f32_e32 v97, v40, v72
	v_fma_f32 v98, -v42, v97, v40
	v_fmac_f32_e32 v97, v98, v72
	v_fma_f32 v43, -v42, v97, v40
	v_fma_f32 v43, v43, v72, v97
	v_and_b32_e32 v93, 0xffff0000, v41
	v_div_fixup_f32 v72, v43, v42, v40
	v_mul_f32_e32 v40, 0xbfb8aa3b, v93
	v_exp_f32_e32 v98, v40
	v_lshlrev_b32_e32 v40, 16, v74
	v_mul_f32_e32 v40, 0xbfb8aa3b, v40
	v_exp_f32_e32 v100, v40
	v_and_b32_e32 v40, 0xffff0000, v74
	v_mul_f32_e32 v40, 0xbfb8aa3b, v40
	v_exp_f32_e32 v101, v40
	global_load_dwordx4 v[40:43], v[86:87], off offset:192
	v_pk_mul_f32 v[70:71], v[70:71], v[96:97] op_sel_hi:[1,0]
	v_mul_f32_e32 v74, 0xbfb8aa3b, v73
	v_exp_f32_e32 v102, v74
	s_waitcnt vmcnt(0)
	v_pk_mul_f32 v[40:41], v[70:71], v[40:41]
	v_mul_f32_e32 v70, 0xbfb8aa3b, v91
	v_exp_f32_e32 v103, v70
	s_nop 0
	v_pk_add_f32 v[70:71], v[102:103], 1.0 op_sel_hi:[1,0]
	s_nop 0
	v_rcp_f32_e32 v97, v71
	s_nop 0
	v_fma_f32 v99, -v71, v97, 1.0
	v_fmac_f32_e32 v97, v99, v97
	v_mul_f32_e32 v102, v91, v97
	v_fma_f32 v103, -v71, v102, v91
	v_fmac_f32_e32 v102, v103, v97
	v_fma_f32 v74, -v71, v102, v91
	v_fma_f32 v74, v74, v97, v102
	v_div_fixup_f32 v71, v74, v71, v91
	v_rcp_f32_e32 v91, v70
	s_nop 0
	v_fma_f32 v97, -v70, v91, 1.0
	v_fmac_f32_e32 v91, v97, v91
	v_mul_f32_e32 v99, v73, v91
	v_fma_f32 v102, -v70, v99, v73
	v_fmac_f32_e32 v99, v102, v91
	v_fma_f32 v74, -v70, v99, v73
	v_fma_f32 v74, v74, v91, v99
	v_div_fixup_f32 v70, v74, v70, v73
	v_pk_mul_f32 v[40:41], v[40:41], v[70:71]
	v_pk_add_f32 v[70:71], v[100:101], 1.0 op_sel_hi:[1,0]
	s_nop 0
	v_rcp_f32_e32 v74, v71
	s_nop 0
	v_fma_f32 v91, -v71, v74, 1.0
	v_fmac_f32_e32 v74, v91, v74
	v_mov_b32_e64 v91, 1.0
	v_mul_f32_e32 v97, v91, v74
	v_fma_f32 v99, -v71, v97, v91
	v_fmac_f32_e32 v97, v99, v74
	v_fma_f32 v73, -v71, v97, v91
	v_fma_f32 v73, v73, v74, v97
	v_div_fixup_f32 v71, v73, v71, 1.0
	v_rcp_f32_e32 v74, v70
	s_nop 0
	v_fma_f32 v91, -v70, v74, 1.0
	v_fmac_f32_e32 v74, v91, v74
	v_mov_b32_e64 v91, 1.0
	v_mul_f32_e32 v97, v91, v74
	v_fma_f32 v99, -v70, v97, v91
	v_fmac_f32_e32 v97, v99, v74
	v_fma_f32 v73, -v70, v97, v91
	v_fma_f32 v73, v73, v74, v97
	v_div_fixup_f32 v70, v73, v70, 1.0
	v_pk_mul_f32 v[40:41], v[40:41], v[70:71]
	v_lshlrev_b32_e32 v70, 16, v75
	v_mul_f32_e32 v70, 0xbfb8aa3b, v70
	v_exp_f32_e32 v70, v70
	v_cvt_pk_bf16_f32 v40, v40, v41
	v_add_f32_e32 v70, 1.0, v70
	v_rcp_f32_e32 v73, v70
	s_nop 0
	v_fma_f32 v74, -v70, v73, 1.0
	v_fmac_f32_e32 v73, v74, v73
	v_mov_b32_e64 v74, 1.0
	v_mul_f32_e32 v91, v74, v73
	v_fma_f32 v97, -v70, v91, v74
	v_fmac_f32_e32 v91, v97, v73
	v_fma_f32 v71, -v70, v91, v74
	v_fma_f32 v71, v71, v73, v91
	v_div_fixup_f32 v70, v71, v70, 1.0
	v_and_b32_e32 v71, 0xffff0000, v75
	v_mul_f32_e32 v71, 0xbfb8aa3b, v71
	v_exp_f32_e32 v99, v71
	s_nop 0
	v_pk_add_f32 v[74:75], v[98:99], 1.0 op_sel_hi:[1,0]
	s_nop 0
	v_rcp_f32_e32 v73, v75
	s_nop 0
	v_fma_f32 v91, -v75, v73, 1.0
	v_fmac_f32_e32 v73, v91, v73
	v_mov_b32_e64 v91, 1.0
	v_mul_f32_e32 v97, v91, v73
	v_fma_f32 v98, -v75, v97, v91
	v_fmac_f32_e32 v97, v98, v73
	v_fma_f32 v71, -v75, v97, v91
	v_fma_f32 v71, v71, v73, v97
	v_div_fixup_f32 v71, v71, v75, 1.0
	v_rcp_f32_e32 v75, v74
	s_mov_b64 s[0:1], 0
	v_fma_f32 v91, -v74, v75, 1.0
	v_fmac_f32_e32 v75, v91, v75
	v_mul_f32_e32 v97, v93, v75
	v_fma_f32 v98, -v74, v97, v93
	v_fmac_f32_e32 v97, v98, v75
	v_fma_f32 v73, -v74, v97, v93
	v_fma_f32 v73, v73, v75, v97
	v_pk_mul_f32 v[68:69], v[68:69], v[96:97] op_sel_hi:[1,0]
	v_div_fixup_f32 v73, v73, v74, v93
	v_pk_mul_f32 v[42:43], v[68:69], v[42:43]
	v_mov_b32_e32 v93, v161
	v_pk_mul_f32 v[42:43], v[42:43], v[72:73]
	v_lshl_add_u64 v[66:67], v[66:67], 0, v[92:93]
	v_pk_mul_f32 v[42:43], v[42:43], v[70:71]
	global_store_dword v[66:67], v40, off

; template <int MX>
; DI RecRaw rec_load(const Params& p, int b, int h, int dir, int T0, int tid) {
;     ...
;   if (MX == 0) {
;     const int fcol = (dir ? B_FB : B_FF) + h * 64 + k0;
;     w.a0 = *(const uint4*)(rp + fcol); w.a1 = *(const uint4*)(rp + fcol + 8);
;     w.b0 = *(const uint4*)(rp + B_Q + h * 64 + k0); w.b1 = *(const uint4*)(rp + B_Q + h * 64 + k0 + 8);
;     w.c0 = *(const uint4*)(rp + B_I + h * 64 + k0); w.c1 = *(const uint4*)(rp + B_I + h * 64 + k0 + 8);
; template <int MX, bool OUT>
; DI void rec_chunk(const Params& p, int l, int b, int h, int dir, int T0, unsigned char* smem, f32x4 (&St)[4], float& nst, float& dtot, int tid, const RecRaw& raw) {
;     ...
;     if (MX == 0) {
; #pragma unroll
;       for (int i = 0; i < 8; ++i) {
; #pragma unroll
;         for (int hh = 0; hh < 2; ++hh) {
;           const int k = 2 * i + hh;
;           float z = __uint_as_float(hh ? (au[i] & 0xffff0000u) : (au[i] << 16));
;           z = fminf(fmaxf(z, -30.f), 30.f);
;           const float e = __expf(-z);
;           const float sg = 1.f / (1.f + e);
;           const float lb = LB[k0 + k];
;           lf[k] = __log2f(lb + (1.f - lb) * sg);
;           kin[k] = (1.f - lb) * (e * sg);
;           qv[k] = __uint_as_float(hh ? (bu[i] & 0xffff0000u) : (bu[i] << 16)) * 0.125f;
;           vv[k] = __uint_as_float(hh ? (cu[i] & 0xffff0000u) : (cu[i] << 16));
;         }
;       }
.LBB0_701:
	v_add_co_u32_e64 v91, s[10:11], s81, 1
	s_and_b64 s[10:11], s[10:11], exec
	s_cselect_b32 s14, 3, s13
	s_cselect_b32 s15, 0, s81
	s_and_b64 s[10:11], s[6:7], exec
	s_cselect_b32 s10, s14, s15
	s_lshl_b32 s10, s10, 6
	s_ashr_i32 s11, s10, 31
	v_lshl_add_u64 v[0:1], v[80:81], 0, s[10:11]
	v_mov_b64_e32 v[2:3], s[20:21]
	v_mad_u64_u32 v[8:9], s[10:11], v0, s33, v[2:3]
	s_waitcnt vmcnt(0) lgkmcnt(0)
	v_lshlrev_b32_e32 v2, 16, v60
	v_max_f32_e32 v2, v2, v2
	v_med3_f32 v2, v2, s17, v190
	v_mul_f32_e32 v2, 0xbfb8aa3b, v2
	v_exp_f32_e32 v206, v2
	v_and_b32_e32 v60, 0xffff0000, v60
	v_max_f32_e32 v60, v60, v60
	v_med3_f32 v60, v60, s17, v190
	v_add_f32_e32 v64, 1.0, v206
	v_mul_f32_e32 v60, 0xbfb8aa3b, v60
	v_exp_f32_e32 v209, v60
	v_rcp_f32_e32 v66, v64
	v_mad_i32_i24 v9, v1, s33, v9
	v_lshl_add_u64 v[0:1], v[8:9], 0, v[160:161]
	v_add_f32_e32 v60, 1.0, v209
	v_fma_f32 v67, -v64, v66, 1.0
	v_fmac_f32_e32 v66, v67, v66
	v_mov_b32_e64 v67, 1.0
	v_rcp_f32_e32 v100, v60
	v_mul_f32_e32 v68, v67, v66
	v_fma_f32 v69, -v64, v68, v67
	v_fmac_f32_e32 v68, v69, v66
	v_fma_f32 v65, -v64, v68, v67
	v_fma_f32 v101, -v60, v100, 1.0
	v_fma_f32 v65, v65, v66, v68
	v_fmac_f32_e32 v100, v101, v100
	v_mov_b32_e64 v101, 1.0
	v_mul_f32_e32 v102, v101, v100
	v_fma_f32 v103, -v60, v102, v101
	v_fmac_f32_e32 v102, v103, v100
	v_fma_f32 v93, -v60, v102, v101
	v_lshlrev_b32_e32 v101, 16, v61
	v_max_f32_e32 v101, v101, v101
	v_med3_f32 v101, v101, s17, v190
	v_mul_f32_e32 v101, 0xbfb8aa3b, v101
	v_exp_f32_e32 v205, v101
	v_fma_f32 v93, v93, v100, v102
	v_div_fixup_f32 v212, v93, v60, 1.0
	v_and_b32_e32 v61, 0xffff0000, v61
	v_add_f32_e32 v60, 1.0, v205
	v_rcp_f32_e32 v100, v60
	v_max_f32_e32 v61, v61, v61
	v_med3_f32 v61, v61, s17, v190
	v_mul_f32_e32 v61, 0xbfb8aa3b, v61
	v_fma_f32 v101, -v60, v100, 1.0
	v_fmac_f32_e32 v100, v101, v100
	v_mov_b32_e64 v101, 1.0
	v_mul_f32_e32 v102, v101, v100
	v_fma_f32 v103, -v60, v102, v101
	v_exp_f32_e32 v202, v61
	v_fmac_f32_e32 v102, v103, v100
	v_fma_f32 v93, -v60, v102, v101
	v_fma_f32 v61, v93, v100, v102
	v_div_fixup_f32 v207, v61, v60, 1.0
	v_add_f32_e32 v60, 1.0, v202
	v_rcp_f32_e32 v93, v60
	v_lshl_add_u64 v[8:9], v[8:9], 0, s[26:27]
	v_lshl_add_u64 v[8:9], v[8:9], 0, v[94:95]
	global_load_dwordx4 v[4:7], v[0:1], off
	s_nop 0
	global_load_dwordx4 v[0:3], v[0:1], off offset:16
	v_fma_f32 v100, -v60, v93, 1.0
	v_fmac_f32_e32 v93, v100, v93
	v_mov_b32_e64 v100, 1.0
	v_mul_f32_e32 v101, v100, v93
	v_fma_f32 v102, -v60, v101, v100
	v_fmac_f32_e32 v101, v102, v93
	v_fma_f32 v61, -v60, v101, v100
	v_lshlrev_b32_e32 v100, 16, v62
	v_max_f32_e32 v100, v100, v100
	v_med3_f32 v100, v100, s17, v190
	v_mul_f32_e32 v100, 0xbfb8aa3b, v100
	v_exp_f32_e32 v199, v100
	v_fma_f32 v61, v61, v93, v101
	v_div_fixup_f32 v203, v61, v60, 1.0
	v_and_b32_e32 v62, 0xffff0000, v62
	v_add_f32_e32 v60, 1.0, v199
	v_rcp_f32_e32 v93, v60
	v_max_f32_e32 v62, v62, v62
	v_med3_f32 v62, v62, s17, v190
	v_mul_f32_e32 v62, 0xbfb8aa3b, v62
	v_fma_f32 v100, -v60, v93, 1.0
	v_fmac_f32_e32 v93, v100, v93
	v_mov_b32_e64 v100, 1.0
	v_mul_f32_e32 v101, v100, v93
	v_fma_f32 v102, -v60, v101, v100
	v_exp_f32_e32 v115, v62
	v_fmac_f32_e32 v101, v102, v93
	v_fma_f32 v61, -v60, v101, v100
	v_fma_f32 v61, v61, v93, v101
	v_div_fixup_f32 v200, v61, v60, 1.0
	v_add_f32_e32 v61, 1.0, v115
	global_load_dwordx4 v[20:23], v[8:9], off offset:1536
	global_load_dwordx4 v[16:19], v[8:9], off offset:1552
	global_load_dwordx4 v[12:15], v[8:9], off offset:3072
	s_nop 0
	global_load_dwordx4 v[8:11], v[8:9], off offset:3088
	v_div_fixup_f32 v210, v65, v64, 1.0
	ds_read_b128 v[68:71], v79
	ds_read_b128 v[96:99], v79 offset:16
	ds_read_b128 v[72:75], v79 offset:32
	ds_read_b128 v[64:67], v79 offset:48
	v_rcp_f32_e32 v93, v61
	s_waitcnt lgkmcnt(0)
	v_sub_f32_e32 v211, 1.0, v68
	v_sub_f32_e32 v201, 1.0, v96
	v_fma_f32 v60, v200, v201, v96
	v_fma_f32 v96, -v61, v93, 1.0
	v_fmac_f32_e32 v93, v96, v93
	v_mov_b32_e64 v96, 1.0
	v_mul_f32_e32 v100, v96, v93
	v_fma_f32 v101, -v61, v100, v96
	v_fmac_f32_e32 v100, v101, v93
	v_fma_f32 v62, -v61, v100, v96
	v_lshlrev_b32_e32 v96, 16, v63
	v_max_f32_e32 v96, v96, v96
	v_med3_f32 v96, v96, s17, v190
	v_mul_f32_e32 v96, 0xbfb8aa3b, v96
	v_exp_f32_e32 v112, v96
	v_fma_f32 v62, v62, v93, v100
	v_div_fixup_f32 v116, v62, v61, 1.0
	v_sub_f32_e32 v117, 1.0, v97
	v_add_f32_e32 v62, 1.0, v112
	v_rcp_f32_e32 v96, v62
	v_and_b32_e32 v63, 0xffff0000, v63
	v_fma_f32 v61, v116, v117, v97
	v_max_f32_e32 v63, v63, v63
	v_fma_f32 v97, -v62, v96, 1.0
	v_fmac_f32_e32 v96, v97, v96
	v_mov_b32_e64 v97, 1.0
	v_med3_f32 v63, v63, s17, v190
	v_mul_f32_e32 v100, v97, v96
	v_mul_f32_e32 v63, 0xbfb8aa3b, v63
	v_fma_f32 v101, -v62, v100, v97
	v_exp_f32_e32 v109, v63
	v_fmac_f32_e32 v100, v101, v96
	v_fma_f32 v93, -v62, v100, v97
	v_fma_f32 v63, v93, v96, v100
	v_div_fixup_f32 v113, v63, v62, 1.0
	v_add_f32_e32 v63, 1.0, v109
	v_rcp_f32_e32 v96, v63
	v_sub_f32_e32 v114, 1.0, v98
	v_fma_f32 v62, v113, v114, v98
	v_sub_f32_e32 v111, 1.0, v99
	v_fma_f32 v97, -v63, v96, 1.0
	v_fmac_f32_e32 v96, v97, v96
	v_mov_b32_e64 v97, 1.0
	v_mul_f32_e32 v98, v97, v96
	v_fma_f32 v100, -v63, v98, v97
	v_fmac_f32_e32 v98, v100, v96
	v_fma_f32 v93, -v63, v98, v97
	v_lshlrev_b32_e32 v97, 16, v56
	v_max_f32_e32 v97, v97, v97
	v_med3_f32 v97, v97, s17, v190
	v_mul_f32_e32 v97, 0xbfb8aa3b, v97
	v_exp_f32_e32 v106, v97
	v_fma_f32 v93, v93, v96, v98
	v_div_fixup_f32 v110, v93, v63, 1.0
	v_and_b32_e32 v56, 0xffff0000, v56
	v_add_f32_e32 v93, 1.0, v106
	v_rcp_f32_e32 v97, v93
	v_max_f32_e32 v56, v56, v56
	v_fmac_f32_e32 v99, v110, v111
	v_med3_f32 v56, v56, s17, v190
	v_fma_f32 v98, -v93, v97, 1.0
; template <int MX, bool OUT>
; DI void rec_chunk(const Params& p, int l, int b, int h, int dir, int T0, unsigned char* smem, f32x4 (&St)[4], float& nst, float& dtot, int tid, const RecRaw& raw) {
;     ...
;     if (MX == 0) {
; #pragma unroll
;       for (int i = 0; i < 8; ++i) {
; #pragma unroll
;         for (int hh = 0; hh < 2; ++hh) {
;           const int k = 2 * i + hh;
;           float z = __uint_as_float(hh ? (au[i] & 0xffff0000u) : (au[i] << 16));
;           z = fminf(fmaxf(z, -30.f), 30.f);
;           const float e = __expf(-z);
;           const float sg = 1.f / (1.f + e);
;           const float lb = LB[k0 + k];
;           lf[k] = __log2f(lb + (1.f - lb) * sg);
;           kin[k] = (1.f - lb) * (e * sg);
;           qv[k] = __uint_as_float(hh ? (bu[i] & 0xffff0000u) : (bu[i] << 16)) * 0.125f;
;           vv[k] = __uint_as_float(hh ? (cu[i] & 0xffff0000u) : (cu[i] << 16));
;         }
;       }
;     ...
;     const int k = tid & 63, part = tid >> 6;
;     float x[16];
;     float acc = 0.f;
;     if (dir == 0) {
; #pragma unroll
;       for (int i = 0; i < 16; ++i) { acc += CUM[(part * 16 + i) * 64 + k]; x[i] = acc; }
;     } else {
; #pragma unroll
;       for (int i = 15; i >= 0; --i) { acc += CUM[(part * 16 + i) * 64 + k]; x[i] = acc; }
;     }
	v_fmac_f32_e32 v97, v98, v97
	v_mov_b32_e64 v98, 1.0
	v_log_f32_e32 v63, v99
	v_mul_f32_e32 v99, v98, v97
	v_mul_f32_e32 v56, 0xbfb8aa3b, v56
	v_fma_f32 v100, -v93, v99, v98
	v_exp_f32_e32 v103, v56
	v_fmac_f32_e32 v99, v100, v97
	v_fma_f32 v96, -v93, v99, v98
	v_fma_f32 v56, v96, v97, v99
	v_div_fixup_f32 v107, v56, v93, 1.0
	v_add_f32_e32 v56, 1.0, v103
	v_rcp_f32_e32 v96, v56
	v_sub_f32_e32 v108, 1.0, v72
	v_fma_f32 v72, v107, v108, v72
	v_log_f32_e32 v214, v72
	v_fma_f32 v72, -v56, v96, 1.0
	v_fmac_f32_e32 v96, v72, v96
	v_mov_b32_e64 v72, 1.0
	v_mul_f32_e32 v97, v72, v96
	v_fma_f32 v98, -v56, v97, v72
	v_fmac_f32_e32 v97, v98, v96
	v_fma_f32 v72, -v56, v97, v72
	v_lshlrev_b32_e32 v93, 16, v57
	v_max_f32_e32 v93, v93, v93
	v_med3_f32 v93, v93, s17, v190
	v_mul_f32_e32 v93, 0xbfb8aa3b, v93
	v_exp_f32_e32 v100, v93
	v_fma_f32 v72, v72, v96, v97
	v_div_fixup_f32 v104, v72, v56, 1.0
	v_sub_f32_e32 v105, 1.0, v73
	v_add_f32_e32 v56, 1.0, v100
	v_rcp_f32_e32 v93, v56
	v_fma_f32 v73, v104, v105, v73
	v_log_f32_e32 v215, v73
	v_and_b32_e32 v57, 0xffff0000, v57
	v_fma_f32 v73, -v56, v93, 1.0
	v_fmac_f32_e32 v93, v73, v93
	v_mov_b32_e64 v73, 1.0
	v_max_f32_e32 v57, v57, v57
	v_mul_f32_e32 v96, v73, v93
	v_med3_f32 v57, v57, s17, v190
	v_fma_f32 v97, -v56, v96, v73
	v_mul_f32_e32 v57, 0xbfb8aa3b, v57
	v_fmac_f32_e32 v96, v97, v93
	v_exp_f32_e32 v97, v57
	v_fma_f32 v72, -v56, v96, v73
	v_fma_f32 v57, v72, v93, v96
	v_div_fixup_f32 v101, v57, v56, 1.0
	v_add_f32_e32 v56, 1.0, v97
	v_rcp_f32_e32 v72, v56
	v_sub_f32_e32 v102, 1.0, v74
	v_fma_f32 v73, v101, v102, v74
	v_log_f32_e32 v216, v73
	v_fma_f32 v73, -v56, v72, 1.0
	v_fmac_f32_e32 v72, v73, v72
	v_mov_b32_e64 v73, 1.0
	v_mul_f32_e32 v74, v73, v72
	v_fma_f32 v93, -v56, v74, v73
	v_fmac_f32_e32 v74, v93, v72
	v_fma_f32 v57, -v56, v74, v73
	v_lshlrev_b32_e32 v73, 16, v58
	v_max_f32_e32 v73, v73, v73
	v_med3_f32 v73, v73, s17, v190
	v_mul_f32_e32 v73, 0xbfb8aa3b, v73
	v_exp_f32_e32 v93, v73
	v_fma_f32 v57, v57, v72, v74
	v_div_fixup_f32 v98, v57, v56, 1.0
	v_sub_f32_e32 v99, 1.0, v75
	v_add_f32_e32 v56, 1.0, v93
	v_rcp_f32_e32 v73, v56
	v_and_b32_e32 v58, 0xffff0000, v58
	v_fmac_f32_e32 v75, v98, v99
	v_max_f32_e32 v58, v58, v58
	v_fma_f32 v72, -v56, v73, 1.0
	v_fmac_f32_e32 v73, v72, v73
	v_mov_b32_e64 v72, 1.0
	v_mul_f32_e32 v74, v72, v73
	v_log_f32_e32 v217, v75
	v_fma_f32 v75, -v56, v74, v72
	v_med3_f32 v58, v58, s17, v190
	v_fmac_f32_e32 v74, v75, v73
	v_mul_f32_e32 v58, 0xbfb8aa3b, v58
	v_fma_f32 v57, -v56, v74, v72
	v_exp_f32_e32 v72, v58
	v_fma_f32 v57, v57, v73, v74
	v_div_fixup_f32 v75, v57, v56, 1.0
	v_sub_f32_e32 v96, 1.0, v64
	v_add_f32_e32 v56, 1.0, v72
	v_rcp_f32_e32 v58, v56
	v_fma_f32 v64, v75, v96, v64
	v_log_f32_e32 v218, v64
	v_sub_f32_e32 v213, 1.0, v69
	v_fma_f32 v64, -v56, v58, 1.0
	v_fmac_f32_e32 v58, v64, v58
	v_mov_b32_e64 v64, 1.0
	v_mul_f32_e32 v73, v64, v58
	v_fma_f32 v74, -v56, v73, v64
	v_fmac_f32_e32 v73, v74, v58
	v_fma_f32 v57, -v56, v73, v64
	v_lshlrev_b32_e32 v64, 16, v59
	v_max_f32_e32 v64, v64, v64
	v_med3_f32 v64, v64, s17, v190
	v_mul_f32_e32 v64, 0xbfb8aa3b, v64
	v_exp_f32_e32 v64, v64
	v_fma_f32 v57, v57, v58, v73
	v_div_fixup_f32 v73, v57, v56, 1.0
	v_sub_f32_e32 v74, 1.0, v65
	v_add_f32_e32 v57, 1.0, v64
	v_rcp_f32_e32 v58, v57
	v_fma_f32 v65, v73, v74, v65
	v_log_f32_e32 v219, v65
	v_sub_f32_e32 v208, 1.0, v70
	v_fma_f32 v65, -v57, v58, 1.0
	v_fmac_f32_e32 v58, v65, v58
	v_mov_b32_e64 v65, 1.0
	v_mul_f32_e32 v220, v65, v58
	v_fma_f32 v221, -v57, v220, v65
	v_fmac_f32_e32 v220, v221, v58
	v_fma_f32 v65, -v57, v220, v65
	v_and_b32_e32 v56, 0xffff0000, v59
	v_max_f32_e32 v56, v56, v56
	v_med3_f32 v56, v56, s17, v190
	v_mul_f32_e32 v56, 0xbfb8aa3b, v56
	v_exp_f32_e32 v56, v56
	v_fma_f32 v58, v65, v58, v220
	v_div_fixup_f32 v59, v58, v57, 1.0
	v_sub_f32_e32 v65, 1.0, v66
	v_add_f32_e32 v57, 1.0, v56
	v_rcp_f32_e32 v221, v57
	v_fma_f32 v66, v59, v65, v66
	v_log_f32_e32 v220, v66
	v_sub_f32_e32 v204, 1.0, v71
	v_fma_f32 v66, -v57, v221, 1.0
	v_fmac_f32_e32 v221, v66, v221
	v_mov_b32_e64 v66, 1.0
	v_mul_f32_e32 v222, v66, v221
	v_fma_f32 v223, -v57, v222, v66
	v_fmac_f32_e32 v222, v223, v221
	v_fma_f32 v68, v210, v211, v68
	v_fma_f32 v69, v212, v213, v69
	v_fma_f32 v70, v207, v208, v70
	v_fmac_f32_e32 v71, v203, v204
	v_fma_f32 v58, -v57, v222, v66
	v_log_f32_e32 v68, v68
	v_log_f32_e32 v69, v69
	v_log_f32_e32 v70, v70
	v_log_f32_e32 v71, v71
	v_fma_f32 v58, v58, v221, v222
	v_log_f32_e32 v60, v60
	v_log_f32_e32 v61, v61
	v_log_f32_e32 v62, v62
	v_div_fixup_f32 v57, v58, v57, 1.0
	v_sub_f32_e32 v58, 1.0, v67
	v_fmac_f32_e32 v67, v57, v58
	v_log_f32_e32 v221, v67
	ds_write_b128 v118, v[68:71]
	ds_write_b128 v118, v[60:63] offset:16
	ds_write_b128 v118, v[214:217] offset:32
	ds_write_b128 v118, v[218:221] offset:48
	v_cndmask_b32_e64 v60, 0, 1, s[8:9]
	v_cmp_ne_u32_e64 s[78:79], 1, v60
	s_andn2_b64 vcc, exec, s[8:9]
	s_mov_b64 s[10:11], -1
	s_waitcnt lgkmcnt(0)
	s_barrier
	s_cbranch_vccnz .LBB0_703
	ds_read2st64_b32 v[60:61], v119 offset0:14 offset1:15
	ds_read2st64_b32 v[214:215], v119 offset0:6 offset1:7
	ds_read2st64_b32 v[216:217], v119 offset0:4 offset1:5
	ds_read2st64_b32 v[218:219], v119 offset0:2 offset1:3
	ds_read2st64_b32 v[220:221], v119 offset1:1
	s_waitcnt lgkmcnt(0)
	v_add_f32_e32 v70, 0, v61
	v_add_f32_e32 v71, v70, v60
	ds_read2st64_b32 v[60:61], v119 offset0:12 offset1:13
	s_mov_b64 s[10:11], 0
	ds_read2st64_b32 v[62:63], v119 offset0:8 offset1:9
	s_waitcnt lgkmcnt(0)
	v_add_f32_e32 v66, v71, v61
	v_add_f32_e32 v67, v66, v60
	ds_read2st64_b32 v[60:61], v119 offset0:10 offset1:11
	s_waitcnt lgkmcnt(0)
	v_add_f32_e32 v68, v67, v61
	v_add_f32_e32 v69, v68, v60
	v_add_f32_e32 v60, v69, v63
	v_add_f32_e32 v61, v60, v62
	v_add_f32_e32 v62, v61, v215
	v_add_f32_e32 v63, v62, v214
	v_add_f32_e32 v214, v63, v217
	v_add_f32_e32 v215, v214, v216
	v_add_f32_e32 v216, v215, v219
	v_add_f32_e32 v217, v216, v218
	v_add_f32_e32 v218, v217, v221
	v_add_f32_e32 v219, v218, v220

; DI size_t kblk(int row, int col, int nrows) { return ((size_t)(col >> 5) * nrows + row) * 32 + (col & 31); }
; DI float siluf_(float z) { return z / (1.f + __expf(-z)); }
; #define MFMA16(a, b, c) __builtin_amdgcn_mfma_f32_16x16x32_bf16((a), (b), (c), 0, 0, 0)
; template <int MX, bool OUT>
; DI void rec_chunk(const Params& p, int l, int b, int h, int dir, int T0, unsigned char* smem, f32x4 (&St)[4], float& nst, float& dtot, int tid, const RecRaw& raw) {
;     ...
; #pragma unroll
;     for (int ks = 0; ks < 2; ++ks) {
;       const bf16x8 fb = *(const bf16x8*)(smem + L_QS + swz(t, ks * 4 + g));
; #pragma unroll
;       for (int a = 0; a < 4; ++a) {
;         const bf16x8 fa = *(const bf16x8*)(smem + L_STT + swz(16 * a + col, ks * 4 + g));
;         O[a] = MFMA16(fa, fb, O[a]);
;       }
;     }
;     ...
;     } else {
;       float ss = 0.f;
; #pragma unroll
;       for (int a = 0; a < 4; ++a) {
;         const uint2 u = *(const uint2*)(MIX + kblk((int)orow, cb + 16 * a + 4 * g, ROWS));
;         O[a][0] += __uint_as_float(u.x << 16); O[a][1] += __uint_as_float(u.x & 0xffff0000u);
;         O[a][2] += __uint_as_float(u.y << 16); O[a][3] += __uint_as_float(u.y & 0xffff0000u);
; #pragma unroll
;         for (int j = 0; j < 4; ++j) ss += O[a][j] * O[a][j];
;       }
;       ss += __shfl_xor(ss, 16);
;       ss += __shfl_xor(ss, 32);
;       const float rstd = rsqrtf(ss * (1.f / 64.f) + EPS);
;       const float* gvec = (MX ? p.ml_g : p.hg_g) + l * 64;
; #pragma unroll
;       for (int a = 0; a < 4; ++a) {
;         const int v0 = 16 * a + 4 * g;
;         const uint2 gt = *(const uint2*)(prow + GATE + cb + v0);
;         const float4 gg = *(const float4*)(gvec + v0);
;         float y0 = O[a][0] * rstd * gg.x * siluf_(__uint_as_float(gt.x << 16));
;         float y1 = O[a][1] * rstd * gg.y * siluf_(__uint_as_float(gt.x & 0xffff0000u));
;         float y2 = O[a][2] * rstd * gg.z * siluf_(__uint_as_float(gt.y << 16));
;         float y3 = O[a][3] * rstd * gg.w * siluf_(__uint_as_float(gt.y & 0xffff0000u));
.LBB0_765:
	s_or_b64 exec, exec, vcc
	s_add_i32 s10, s13, -1
	v_mov_b32_e32 v40, s10
	v_cndmask_b32_e64 v40, v91, v40, s[6:7]
	v_lshlrev_b32_e32 v40, 6, v40
	v_add_u32_e32 v40, s12, v40
	v_mov_b32_e32 v41, v161
	v_lshl_add_u64 v[68:69], v[40:41], 0, v[82:83]
	ds_read_b128 v[40:43], v202 offset:32768
	ds_read_b128 v[44:47], v200 offset:57344
	ds_read_b128 v[48:51], v200 offset:59392
	ds_read_b128 v[52:55], v200 offset:61440
	s_waitcnt lgkmcnt(0)
	v_mfma_f32_16x16x32_bf16 v[44:47], v[44:47], v[40:43], v[56:59]
	s_mov_b64 s[10:11], -1
	s_nop 1
	ds_read_b128 v[56:59], v200 offset:63488
	s_and_b64 vcc, exec, s[78:79]
	v_mfma_f32_16x16x32_bf16 v[48:51], v[48:51], v[40:43], v[60:63]
	v_ashrrev_i32_e32 v203, 31, v68
	v_mfma_f32_16x16x32_bf16 v[52:55], v[52:55], v[40:43], v[64:67]
	s_waitcnt lgkmcnt(0)
	v_mfma_f32_16x16x32_bf16 v[56:59], v[56:59], v[40:43], v[72:75]
	ds_read_b128 v[60:63], v201 offset:32768
	ds_read_b128 v[40:43], v199 offset:57344
	s_waitcnt lgkmcnt(0)
	v_mfma_f32_16x16x32_bf16 v[40:43], v[40:43], v[60:63], v[44:47]
	s_nop 2
	ds_read_b128 v[44:47], v199 offset:59392
	s_waitcnt lgkmcnt(0)
	v_mfma_f32_16x16x32_bf16 v[48:51], v[44:47], v[60:63], v[48:51]
	ds_read_b128 v[44:47], v199 offset:61440
	s_waitcnt lgkmcnt(0)
	v_mfma_f32_16x16x32_bf16 v[52:55], v[44:47], v[60:63], v[52:55]
	ds_read_b128 v[44:47], v199 offset:63488
	s_waitcnt lgkmcnt(0)
	v_mfma_f32_16x16x32_bf16 v[44:47], v[44:47], v[60:63], v[56:59]
	s_cbranch_vccnz .LBB0_767
	s_nop 1
	v_mov_b64_e32 v[56:57], s[40:41]
	v_mad_u64_u32 v[56:57], s[10:11], v68, s33, v[56:57]
	v_mad_i32_i24 v57, v69, s33, v57
	v_mov_b32_e32 v69, v203
	v_lshl_add_u64 v[60:61], v[68:69], 0, s[30:31]
	v_lshlrev_b64 v[60:61], 6, v[60:61]
	v_lshl_add_u64 v[70:71], v[88:89], 0, v[60:61]
	global_load_dwordx2 v[60:61], v[70:71], off
	v_lshl_add_u64 v[58:59], v[68:69], 0, s[28:29]
	v_lshlrev_b64 v[58:59], 6, v[58:59]
	v_mov_b32_e32 v91, v161
	v_lshl_add_u64 v[96:97], v[84:85], 0, v[58:59]
	global_load_dwordx2 v[58:59], v[96:97], off
	s_mov_b64 s[10:11], 0x41c7a20
	v_lshl_add_u64 v[56:57], v[56:57], 0, s[10:11]
	s_waitcnt vmcnt(0) lgkmcnt(0)
	v_lshlrev_b32_e32 v74, 16, v60
	v_and_b32_e32 v75, 0xffff0000, v60
	v_lshlrev_b32_e32 v98, 16, v61
	v_and_b32_e32 v99, 0xffff0000, v61
	v_lshl_add_u64 v[60:61], v[68:69], 0, s[42:43]
	v_lshlrev_b64 v[60:61], 6, v[60:61]
	v_lshl_add_u64 v[60:61], s[34:35], 0, v[60:61]
	v_lshl_add_u64 v[66:67], v[60:61], 0, v[90:91]
	global_load_dwordx2 v[62:63], v[66:67], off
	v_mbcnt_hi_u32_b32 v69, -1, v185
	v_and_b32_e32 v73, 64, v69
	v_xor_b32_e32 v72, 16, v69
	v_add_u32_e32 v73, 64, v73
	v_cmp_lt_i32_e32 vcc, v72, v73
	v_lshlrev_b32_e32 v112, 16, v58
	v_and_b32_e32 v113, 0xffff0000, v58
	v_cndmask_b32_e32 v72, v69, v72, vcc
	v_lshlrev_b32_e32 v93, 2, v72
	v_xor_b32_e32 v72, 32, v69
	v_cmp_lt_i32_e32 vcc, v72, v73
	v_lshlrev_b32_e32 v58, 16, v59
	v_and_b32_e32 v59, 0xffff0000, v59
	v_cndmask_b32_e32 v69, v69, v72, vcc
	v_lshl_add_u64 v[72:73], v[56:57], 0, s[2:3]
	v_lshl_add_u64 v[56:57], v[56:57], 0, v[90:91]
	v_lshl_add_u64 v[56:57], v[56:57], 0, s[2:3]
	global_load_dwordx2 v[56:57], v[56:57], off
	v_pk_add_f32 v[108:109], v[42:43], v[58:59]
	v_pk_add_f32 v[112:113], v[40:41], v[112:113]
	v_pk_mul_f32 v[110:111], v[108:109], v[108:109]
	v_pk_mul_f32 v[116:117], v[112:113], v[112:113]
	v_lshl_add_u64 v[72:73], v[72:73], 0, v[90:91]
	v_add_f32_e32 v91, v116, v117
	v_add_f32_e32 v91, v91, v110
	v_add_f32_e32 v91, v111, v91
	v_lshlrev_b32_e32 v69, 2, v69
	s_waitcnt vmcnt(0) lgkmcnt(0)
	v_lshlrev_b32_e32 v104, 16, v62
	v_and_b32_e32 v105, 0xffff0000, v62
	v_lshlrev_b32_e32 v106, 16, v63
	v_and_b32_e32 v107, 0xffff0000, v63
	global_load_dwordx2 v[62:63], v[66:67], off offset:32
	v_pk_add_f32 v[104:105], v[52:53], v[104:105]
	v_lshlrev_b32_e32 v204, 16, v56
	v_and_b32_e32 v205, 0xffff0000, v56
	v_mul_f32_e32 v114, 0xbfb8aa3b, v204
	v_mul_f32_e32 v115, 0xbfb8aa3b, v205
	v_exp_f32_e32 v114, v114
	v_exp_f32_e32 v115, v115
	v_lshlrev_b32_e32 v206, 16, v57
	v_and_b32_e32 v207, 0xffff0000, v57
	global_load_dwordx4 v[56:59], v[86:87], off
	v_pk_add_f32 v[114:115], v[114:115], 1.0 op_sel_hi:[1,0]
	s_waitcnt vmcnt(0) lgkmcnt(0)
	v_lshlrev_b32_e32 v64, 16, v62
	v_rcp_f32_e32 v209, v115
	v_and_b32_e32 v65, 0xffff0000, v62
	v_pk_add_f32 v[64:65], v[44:45], v[64:65]
	v_lshlrev_b32_e32 v62, 16, v63
	v_fma_f32 v210, -v115, v209, 1.0
	v_fmac_f32_e32 v209, v210, v209
	v_mul_f32_e32 v211, v205, v209
	v_fma_f32 v212, -v115, v211, v205
	v_fmac_f32_e32 v211, v212, v209
	v_fma_f32 v208, -v115, v211, v205
	v_fma_f32 v208, v208, v209, v211
	v_div_fixup_f32 v115, v208, v115, v205
	v_rcp_f32_e32 v208, v114
	v_and_b32_e32 v63, 0xffff0000, v63
	v_pk_mul_f32 v[100:101], v[64:65], v[64:65]
	v_pk_add_f32 v[62:63], v[46:47], v[62:63]
	v_fma_f32 v209, -v114, v208, 1.0
	v_fmac_f32_e32 v208, v209, v208
	v_mul_f32_e32 v210, v204, v208
	v_fma_f32 v211, -v114, v210, v204
	v_fmac_f32_e32 v210, v211, v208
	v_fma_f32 v205, -v114, v210, v204
	v_fma_f32 v205, v205, v208, v210
	v_div_fixup_f32 v114, v205, v114, v204
	v_mul_f32_e32 v204, 0xbfb8aa3b, v206
	v_mul_f32_e32 v205, 0xbfb8aa3b, v207
	v_exp_f32_e32 v204, v204
	v_exp_f32_e32 v205, v205
	v_pk_mul_f32 v[102:103], v[62:63], v[62:63]
	v_pk_add_f32 v[204:205], v[204:205], 1.0 op_sel_hi:[1,0]
	s_nop 0
	v_rcp_f32_e32 v209, v205
	s_nop 0
	v_fma_f32 v210, -v205, v209, 1.0
	v_fmac_f32_e32 v209, v210, v209
	v_mul_f32_e32 v211, v207, v209
	v_fma_f32 v212, -v205, v211, v207
	v_fmac_f32_e32 v211, v212, v209
	v_fma_f32 v208, -v205, v211, v207
	v_fma_f32 v208, v208, v209, v211
	v_div_fixup_f32 v205, v208, v205, v207
	v_rcp_f32_e32 v208, v204
	v_pk_mul_f32 v[212:213], v[104:105], v[104:105]
	v_fma_f32 v209, -v204, v208, 1.0
	v_fmac_f32_e32 v208, v209, v208
	v_mul_f32_e32 v210, v206, v208
	v_fma_f32 v211, -v204, v210, v206
	v_fmac_f32_e32 v210, v211, v208
	v_fma_f32 v207, -v204, v210, v206
	v_fma_f32 v207, v207, v208, v210
	v_pk_add_f32 v[210:211], v[48:49], v[74:75]
	v_div_fixup_f32 v204, v207, v204, v206
	v_pk_mul_f32 v[74:75], v[210:211], v[210:211]
	v_pk_add_f32 v[206:207], v[50:51], v[98:99]
	v_add_f32_e32 v74, v74, v91
	v_pk_mul_f32 v[208:209], v[206:207], v[206:207]
	v_add_f32_e32 v74, v75, v74
	v_add_f32_e32 v74, v208, v74
	v_add_f32_e32 v74, v209, v74
	v_pk_add_f32 v[98:99], v[54:55], v[106:107]
	v_add_f32_e32 v74, v212, v74
	v_pk_mul_f32 v[106:107], v[98:99], v[98:99]
	v_add_f32_e32 v74, v213, v74
	v_add_f32_e32 v74, v106, v74
	v_add_f32_e32 v74, v107, v74
	v_add_f32_e32 v74, v100, v74
	v_add_f32_e32 v74, v101, v74
	v_add_f32_e32 v74, v102, v74
	v_add_f32_e32 v74, v103, v74
	ds_bpermute_b32 v75, v93, v74
	s_waitcnt lgkmcnt(0)
; DI size_t kblk(int row, int col, int nrows) { return ((size_t)(col >> 5) * nrows + row) * 32 + (col & 31); }
; DI unsigned pk2(float a, float b) { hwf32x2 f = {a, b}; hwbf16x2 r = __builtin_convertvector(f, hwbf16x2); return __builtin_bit_cast(unsigned, r); }
; DI float sigmoidf_(float z) { return 1.f / (1.f + __expf(-z)); }
; DI float siluf_(float z) { return z / (1.f + __expf(-z)); }
; template <int MX, bool OUT>
; DI void rec_chunk(const Params& p, int l, int b, int h, int dir, int T0, unsigned char* smem, f32x4 (&St)[4], float& nst, float& dtot, int tid, const RecRaw& raw) {
;     ...
;       ss += __shfl_xor(ss, 16);
;       ss += __shfl_xor(ss, 32);
;       const float rstd = rsqrtf(ss * (1.f / 64.f) + EPS);
;       const float* gvec = (MX ? p.ml_g : p.hg_g) + l * 64;
; #pragma unroll
;       for (int a = 0; a < 4; ++a) {
;         const int v0 = 16 * a + 4 * g;
;         const uint2 gt = *(const uint2*)(prow + GATE + cb + v0);
;         const float4 gg = *(const float4*)(gvec + v0);
;         float y0 = O[a][0] * rstd * gg.x * siluf_(__uint_as_float(gt.x << 16));
;         float y1 = O[a][1] * rstd * gg.y * siluf_(__uint_as_float(gt.x & 0xffff0000u));
;         float y2 = O[a][2] * rstd * gg.z * siluf_(__uint_as_float(gt.y << 16));
;         float y3 = O[a][3] * rstd * gg.w * siluf_(__uint_as_float(gt.y & 0xffff0000u));
;         if (MX == 1) {
;           const uint2 og = *(const uint2*)(prow + D_OG + h * 64 + v0);
;           y0 *= sigmoidf_(__uint_as_float(og.x << 16)); y1 *= sigmoidf_(__uint_as_float(og.x & 0xffff0000u));
;           y2 *= sigmoidf_(__uint_as_float(og.y << 16)); y3 *= sigmoidf_(__uint_as_float(og.y & 0xffff0000u));
;         }
;         *(uint2*)(MIX + kblk((int)orow, cb + v0, ROWS)) = make_uint2(pk2(y0, y1), pk2(y2, y3));
	v_add_f32_e32 v74, v74, v75
	ds_bpermute_b32 v69, v69, v74
	s_waitcnt lgkmcnt(0)
	v_add_f32_e32 v69, v74, v69
	v_fmamk_f32 v69, v69, 0x3c800000, v162
	v_cmp_gt_f32_e32 vcc, s38, v69
	v_mul_f32_e32 v74, 0x4b800000, v69
	s_nop 0
	v_cndmask_b32_e32 v69, v69, v74, vcc
	v_rsq_f32_e32 v69, v69
	s_nop 0
	v_mul_f32_e32 v74, 0x45800000, v69
	v_cndmask_b32_e32 v74, v69, v74, vcc
	v_pk_mul_f32 v[100:101], v[112:113], v[74:75] op_sel_hi:[1,0]
	s_nop 0
	v_pk_mul_f32 v[56:57], v[56:57], v[100:101]
	v_pk_mul_f32 v[100:101], v[108:109], v[74:75] op_sel_hi:[1,0]
	v_pk_mul_f32 v[56:57], v[114:115], v[56:57]
	v_pk_mul_f32 v[58:59], v[58:59], v[100:101]
	v_cvt_pk_bf16_f32 v56, v56, v57
	v_pk_mul_f32 v[58:59], v[204:205], v[58:59]
	s_nop 0
	v_cvt_pk_bf16_f32 v57, v58, v59
	global_store_dwordx2 v[96:97], v[56:57], off
	global_load_dwordx2 v[96:97], v[72:73], off offset:32
	s_nop 0
	global_load_dwordx4 v[56:59], v[86:87], off offset:64
	s_waitcnt vmcnt(0) lgkmcnt(0)
	v_lshlrev_b32_e32 v69, 16, v96
	v_and_b32_e32 v75, 0xffff0000, v96
	v_mul_f32_e32 v91, 0xbfb8aa3b, v69
	v_exp_f32_e32 v100, v91
	v_mul_f32_e32 v91, 0xbfb8aa3b, v75
	v_exp_f32_e32 v101, v91
	v_pk_mul_f32 v[102:103], v[210:211], v[74:75] op_sel_hi:[1,0]
	v_pk_add_f32 v[100:101], v[100:101], 1.0 op_sel_hi:[1,0]
	s_nop 0
	v_rcp_f32_e32 v93, v101
	v_pk_mul_f32 v[56:57], v[56:57], v[102:103]
	v_fma_f32 v96, -v101, v93, 1.0
	v_fmac_f32_e32 v93, v96, v93
	v_mul_f32_e32 v102, v75, v93
	v_fma_f32 v103, -v101, v102, v75
	v_fmac_f32_e32 v102, v103, v93
	v_fma_f32 v91, -v101, v102, v75
	v_fma_f32 v91, v91, v93, v102
	v_div_fixup_f32 v101, v91, v101, v75
	v_rcp_f32_e32 v91, v100
	s_nop 0
	v_fma_f32 v93, -v100, v91, 1.0
	v_fmac_f32_e32 v91, v93, v91
	v_mul_f32_e32 v96, v69, v91
	v_fma_f32 v102, -v100, v96, v69
	v_fmac_f32_e32 v96, v102, v91
	v_fma_f32 v75, -v100, v96, v69
	v_fma_f32 v75, v75, v91, v96
	v_div_fixup_f32 v100, v75, v100, v69
	v_lshlrev_b32_e32 v69, 16, v97
	v_and_b32_e32 v75, 0xffff0000, v97
	v_mul_f32_e32 v91, 0xbfb8aa3b, v69
	v_exp_f32_e32 v96, v91
	v_mul_f32_e32 v91, 0xbfb8aa3b, v75
	v_exp_f32_e32 v97, v91
	v_pk_mul_f32 v[56:57], v[100:101], v[56:57]
	v_pk_mul_f32 v[100:101], v[206:207], v[74:75] op_sel_hi:[1,0]
	v_cvt_pk_bf16_f32 v56, v56, v57
	v_pk_add_f32 v[96:97], v[96:97], 1.0 op_sel_hi:[1,0]
	v_pk_mul_f32 v[58:59], v[58:59], v[100:101]
	v_rcp_f32_e32 v93, v97
	s_nop 0
	v_fma_f32 v100, -v97, v93, 1.0
	v_fmac_f32_e32 v93, v100, v93
	v_mul_f32_e32 v101, v75, v93
	v_fma_f32 v102, -v97, v101, v75
	v_fmac_f32_e32 v101, v102, v93
	v_fma_f32 v91, -v97, v101, v75
	v_fma_f32 v91, v91, v93, v101
	v_div_fixup_f32 v97, v91, v97, v75
	v_rcp_f32_e32 v91, v96
	s_nop 0
	v_fma_f32 v93, -v96, v91, 1.0
	v_fmac_f32_e32 v91, v93, v91
	v_mul_f32_e32 v100, v69, v91
	v_fma_f32 v101, -v96, v100, v69
	v_fmac_f32_e32 v100, v101, v91
	v_fma_f32 v75, -v96, v100, v69
	v_fma_f32 v75, v75, v91, v100
	v_div_fixup_f32 v96, v75, v96, v69
	v_pk_mul_f32 v[58:59], v[96:97], v[58:59]
	s_nop 0
	v_cvt_pk_bf16_f32 v57, v58, v59
	global_store_dwordx2 v[70:71], v[56:57], off
	global_load_dwordx2 v[70:71], v[72:73], off offset:64
	s_nop 0
	global_load_dwordx4 v[56:59], v[86:87], off offset:128
	s_waitcnt vmcnt(0) lgkmcnt(0)
; DI size_t kblk(int row, int col, int nrows) { return ((size_t)(col >> 5) * nrows + row) * 32 + (col & 31); }
; DI unsigned pk2(float a, float b) { hwf32x2 f = {a, b}; hwbf16x2 r = __builtin_convertvector(f, hwbf16x2); return __builtin_bit_cast(unsigned, r); }
; DI float sigmoidf_(float z) { return 1.f / (1.f + __expf(-z)); }
; DI float siluf_(float z) { return z / (1.f + __expf(-z)); }
; template <int MX, bool OUT>
; DI void rec_chunk(const Params& p, int l, int b, int h, int dir, int T0, unsigned char* smem, f32x4 (&St)[4], float& nst, float& dtot, int tid, const RecRaw& raw) {
;     ...
;       for (int a = 0; a < 4; ++a) {
;         const int v0 = 16 * a + 4 * g;
;         const uint2 gt = *(const uint2*)(prow + GATE + cb + v0);
;         const float4 gg = *(const float4*)(gvec + v0);
;         float y0 = O[a][0] * rstd * gg.x * siluf_(__uint_as_float(gt.x << 16));
;         float y1 = O[a][1] * rstd * gg.y * siluf_(__uint_as_float(gt.x & 0xffff0000u));
;         float y2 = O[a][2] * rstd * gg.z * siluf_(__uint_as_float(gt.y << 16));
;         float y3 = O[a][3] * rstd * gg.w * siluf_(__uint_as_float(gt.y & 0xffff0000u));
;         if (MX == 1) {
;           const uint2 og = *(const uint2*)(prow + D_OG + h * 64 + v0);
;           y0 *= sigmoidf_(__uint_as_float(og.x << 16)); y1 *= sigmoidf_(__uint_as_float(og.x & 0xffff0000u));
;           y2 *= sigmoidf_(__uint_as_float(og.y << 16)); y3 *= sigmoidf_(__uint_as_float(og.y & 0xffff0000u));
;         }
;         *(uint2*)(MIX + kblk((int)orow, cb + v0, ROWS)) = make_uint2(pk2(y0, y1), pk2(y2, y3));
	v_lshlrev_b32_e32 v69, 16, v70
	v_and_b32_e32 v70, 0xffff0000, v70
	v_mul_f32_e32 v75, 0xbfb8aa3b, v69
	v_exp_f32_e32 v96, v75
	v_pk_mul_f32 v[100:101], v[104:105], v[74:75] op_sel_hi:[1,0]
	v_mul_f32_e32 v75, 0xbfb8aa3b, v70
	v_exp_f32_e32 v97, v75
	v_pk_mul_f32 v[56:57], v[100:101], v[56:57]
	v_pk_add_f32 v[96:97], v[96:97], 1.0 op_sel_hi:[1,0]
	s_nop 0
	v_rcp_f32_e32 v91, v97
	s_nop 0
	v_fma_f32 v93, -v97, v91, 1.0
	v_fmac_f32_e32 v91, v93, v91
	v_mul_f32_e32 v100, v70, v91
	v_fma_f32 v101, -v97, v100, v70
	v_fmac_f32_e32 v100, v101, v91
	v_fma_f32 v75, -v97, v100, v70
	v_fma_f32 v75, v75, v91, v100
	v_div_fixup_f32 v97, v75, v97, v70
	v_rcp_f32_e32 v75, v96
	s_nop 0
	v_fma_f32 v91, -v96, v75, 1.0
	v_fmac_f32_e32 v75, v91, v75
	v_mul_f32_e32 v93, v69, v75
	v_fma_f32 v100, -v96, v93, v69
	v_fmac_f32_e32 v93, v100, v75
	v_fma_f32 v70, -v96, v93, v69
	v_fma_f32 v70, v70, v75, v93
	v_div_fixup_f32 v96, v70, v96, v69
	v_lshlrev_b32_e32 v69, 16, v71
	v_and_b32_e32 v75, 0xffff0000, v71
	v_mul_f32_e32 v70, 0xbfb8aa3b, v69
	v_mul_f32_e32 v71, 0xbfb8aa3b, v75
	v_exp_f32_e32 v70, v70
	v_exp_f32_e32 v71, v71
	v_pk_mul_f32 v[56:57], v[56:57], v[96:97]
	v_pk_mul_f32 v[96:97], v[98:99], v[74:75] op_sel_hi:[1,0]
	v_cvt_pk_bf16_f32 v56, v56, v57
	v_pk_add_f32 v[70:71], v[70:71], 1.0 op_sel_hi:[1,0]
	v_pk_mul_f32 v[58:59], v[96:97], v[58:59]
	v_rcp_f32_e32 v93, v71
	s_nop 0
	v_fma_f32 v96, -v71, v93, 1.0
	v_fmac_f32_e32 v93, v96, v93
	v_mul_f32_e32 v97, v75, v93
	v_fma_f32 v98, -v71, v97, v75
	v_fmac_f32_e32 v97, v98, v93
	v_fma_f32 v91, -v71, v97, v75
	v_fma_f32 v91, v91, v93, v97
	v_div_fixup_f32 v71, v91, v71, v75
	v_rcp_f32_e32 v91, v70
	s_nop 0
	v_fma_f32 v93, -v70, v91, 1.0
	v_fmac_f32_e32 v91, v93, v91
	v_mul_f32_e32 v96, v69, v91
	v_fma_f32 v97, -v70, v96, v69
	v_fmac_f32_e32 v96, v97, v91
	v_fma_f32 v75, -v70, v96, v69
	v_fma_f32 v75, v75, v91, v96
	v_div_fixup_f32 v70, v75, v70, v69
	v_pk_mul_f32 v[58:59], v[58:59], v[70:71]
	v_pk_mul_f32 v[64:65], v[64:65], v[74:75] op_sel_hi:[1,0]
	v_cvt_pk_bf16_f32 v57, v58, v59
	global_store_dwordx2 v[66:67], v[56:57], off
	global_load_dwordx2 v[66:67], v[72:73], off offset:96
	v_mov_b32_e32 v93, v161
	global_load_dwordx4 v[56:59], v[86:87], off offset:192
	s_waitcnt vmcnt(0) lgkmcnt(0)
	v_lshlrev_b32_e32 v69, 16, v66
	v_and_b32_e32 v66, 0xffff0000, v66
	v_mul_f32_e32 v70, 0xbfb8aa3b, v69
	v_pk_mul_f32 v[56:57], v[64:65], v[56:57]
	v_mul_f32_e32 v64, 0xbfb8aa3b, v66
	v_exp_f32_e32 v70, v70
	v_exp_f32_e32 v71, v64
	s_nop 0
	v_pk_add_f32 v[64:65], v[70:71], 1.0 op_sel_hi:[1,0]
	s_nop 0
	v_rcp_f32_e32 v71, v65
	s_nop 0
	v_fma_f32 v72, -v65, v71, 1.0
	v_fmac_f32_e32 v71, v72, v71
	v_mul_f32_e32 v73, v66, v71
	v_fma_f32 v75, -v65, v73, v66
	v_fmac_f32_e32 v73, v75, v71
	v_fma_f32 v70, -v65, v73, v66
	v_fma_f32 v70, v70, v71, v73
	v_div_fixup_f32 v65, v70, v65, v66
	v_rcp_f32_e32 v70, v64
	v_pk_mul_f32 v[62:63], v[62:63], v[74:75] op_sel_hi:[1,0]
	v_fma_f32 v71, -v64, v70, 1.0
	v_fmac_f32_e32 v70, v71, v70
	v_mul_f32_e32 v72, v69, v70
	v_fma_f32 v73, -v64, v72, v69
	v_fmac_f32_e32 v72, v73, v70
	v_fma_f32 v66, -v64, v72, v69
	v_fma_f32 v66, v66, v70, v72
	v_div_fixup_f32 v64, v66, v64, v69
	v_lshlrev_b32_e32 v66, 16, v67
	v_and_b32_e32 v67, 0xffff0000, v67
	v_pk_mul_f32 v[64:65], v[56:57], v[64:65]
	v_mul_f32_e32 v56, 0xbfb8aa3b, v66
	v_mul_f32_e32 v57, 0xbfb8aa3b, v67
	v_exp_f32_e32 v56, v56
	v_exp_f32_e32 v57, v57
	v_pk_mul_f32 v[58:59], v[62:63], v[58:59]
	v_pk_add_f32 v[56:57], v[56:57], 1.0 op_sel_hi:[1,0]
	s_nop 0
	v_rcp_f32_e32 v63, v57
	s_nop 0
	v_fma_f32 v69, -v57, v63, 1.0
	v_fmac_f32_e32 v63, v69, v63
	v_mul_f32_e32 v70, v67, v63
	v_fma_f32 v71, -v57, v70, v67
	v_fmac_f32_e32 v70, v71, v63
	v_fma_f32 v62, -v57, v70, v67
	v_fma_f32 v62, v62, v63, v70
	v_div_fixup_f32 v57, v62, v57, v67
	v_rcp_f32_e32 v63, v56
	s_mov_b64 s[10:11], 0
	v_fma_f32 v67, -v56, v63, 1.0
	v_fmac_f32_e32 v63, v67, v63
	v_mul_f32_e32 v69, v66, v63
	v_fma_f32 v70, -v56, v69, v66
	v_fmac_f32_e32 v69, v70, v63
	v_fma_f32 v62, -v56, v69, v66
	v_fma_f32 v62, v62, v63, v69
	v_div_fixup_f32 v56, v62, v56, v66
	v_pk_mul_f32 v[56:57], v[58:59], v[56:57]
	v_cvt_pk_bf16_f32 v62, v64, v65
	v_lshl_add_u64 v[58:59], v[60:61], 0, v[92:93]
	global_store_dword v[58:59], v62, off

; DI size_t kblk(int row, int col, int nrows) { return ((size_t)(col >> 5) * nrows + row) * 32 + (col & 31); }
; DI float bf2f(bf16_t v) { return __uint_as_float(((unsigned)v) << 16); }
; DI unsigned pk2(float a, float b) { hwf32x2 f = {a, b}; hwbf16x2 r = __builtin_convertvector(f, hwbf16x2); return __builtin_bit_cast(unsigned, r); }
; DI float siluf_(float z) { return z / (1.f + __expf(-z)); }
; template <int MODE>
; DI void attn_mfma(const Params& p, int l, int b, int hd, int qb, unsigned char* smem) {
;     ...
;   const float ltot = lsum + __shfl_xor(lsum, 32);
;   if (MODE == 0) {
;     ...
;   } else {
;     const float i0 = 1.f / ltot;
; #pragma unroll
;     for (int vt = 0; vt < 2; ++vt)
; #pragma unroll
;       for (int g4 = 0; g4 < 4; ++g4) {
;         const int v0 = vt * 32 + 8 * g4 + 4 * h2;
;         const ushort4 gt = *(const ushort4*)(P + qrow * PW + GATE + 512 + hd * 64 + v0);
;         uint2 o;
;         o.x = pk2(O[vt][4 * g4 + 0] * i0 * siluf_(bf2f(gt.x)), O[vt][4 * g4 + 1] * i0 * siluf_(bf2f(gt.y)));
;         o.y = pk2(O[vt][4 * g4 + 2] * i0 * siluf_(bf2f(gt.z)), O[vt][4 * g4 + 3] * i0 * siluf_(bf2f(gt.w)));
;         *(uint2*)(MIX + kblk((int)qrow, 512 + hd * 64 + v0, ROWS)) = o;
;       }
;   }
.LBB0_829:
	v_cmp_lt_i32_e32 vcc, v33, v34
	s_add_u32 s0, s14, 0x1dc6000
	s_addc_u32 s1, s15, 0
	v_cndmask_b32_e32 v32, v32, v33, vcc
	v_lshlrev_b32_e32 v32, 2, v32
	ds_bpermute_b32 v32, v32, v200
	s_lshl_b32 s2, s11, 1
	v_ashrrev_i32_e32 v145, 31, v144
	v_mov_b32_e32 v153, v161
	v_lshlrev_b64 v[38:39], 1, v[152:153]
	s_waitcnt lgkmcnt(0)
	v_add_f32_e32 v32, v200, v32
	v_rcp_f32_e32 v34, v32
	s_mov_b64 s[4:5], 0x1e20
	v_mov_b32_e32 v151, v161
	v_mov_b32_e32 v149, v161
	v_fma_f32 v35, -v32, v34, 1.0
	v_fmac_f32_e32 v34, v35, v34
	v_mov_b32_e64 v35, 1.0
	v_mul_f32_e32 v36, v35, v34
	v_fma_f32 v37, -v32, v36, v35
	v_fmac_f32_e32 v36, v37, v34
	v_fma_f32 v33, -v32, v36, v35
	v_fma_f32 v33, v33, v34, v36
	v_lshl_add_u64 v[34:35], v[154:155], 0, s[2:3]
	v_lshl_add_u64 v[42:43], v[34:35], 0, s[4:5]
	s_mul_i32 s4, s10, 0x9000
	s_add_i32 s2, s4, 0x48000
	v_lshl_add_u64 v[34:35], v[144:145], 0, s[2:3]
	v_lshlrev_b64 v[34:35], 6, v[34:35]
	v_lshl_add_u64 v[40:41], s[0:1], 0, v[34:35]
	v_lshl_add_u64 v[34:35], v[42:43], 0, v[38:39]
	global_load_dwordx2 v[204:205], v[34:35], off
	global_load_dwordx2 v[206:207], v[34:35], off offset:16
	global_load_dwordx2 v[208:209], v[34:35], off offset:32
	global_load_dwordx2 v[210:211], v[34:35], off offset:48
	global_load_dwordx2 v[212:213], v[34:35], off offset:64
	global_load_dwordx2 v[214:215], v[34:35], off offset:80
	global_load_dwordx2 v[216:217], v[34:35], off offset:96
	global_load_dwordx2 v[218:219], v[34:35], off offset:112
	s_nop 0
	v_div_fixup_f32 v32, v33, v32, 1.0
	v_mov_b32_e32 v147, v161
	s_add_i32 s2, s4, 0x4c800
	s_waitcnt vmcnt(0) lgkmcnt(0)
	v_mov_b32_e32 v36, v204
	v_mov_b32_e32 v37, v205
	v_and_b32_e32 v33, 0xffff0000, v36
	v_lshlrev_b32_e32 v36, 16, v36
	v_mul_f32_e32 v44, 0xbfb8aa3b, v36
	v_mul_f32_e32 v45, 0xbfb8aa3b, v33
	v_exp_f32_e32 v44, v44
	v_exp_f32_e32 v45, v45
	v_pk_mul_f32 v[16:17], v[16:17], v[32:33] op_sel_hi:[1,0]
	v_pk_add_f32 v[44:45], v[44:45], 1.0 op_sel_hi:[1,0]
	s_nop 0
	v_rcp_f32_e32 v47, v45
	s_nop 0
	v_fma_f32 v48, -v45, v47, 1.0
	v_fmac_f32_e32 v47, v48, v47
	v_mul_f32_e32 v49, v33, v47
	v_fma_f32 v50, -v45, v49, v33
	v_fmac_f32_e32 v49, v50, v47
	v_fma_f32 v46, -v45, v49, v33
	v_fma_f32 v46, v46, v47, v49
	v_div_fixup_f32 v45, v46, v45, v33
	v_rcp_f32_e32 v46, v44
	s_nop 0
	v_fma_f32 v47, -v44, v46, 1.0
	v_fmac_f32_e32 v46, v47, v46
	v_mul_f32_e32 v48, v36, v46
	v_fma_f32 v49, -v44, v48, v36
	v_fmac_f32_e32 v48, v49, v46
	v_fma_f32 v33, -v44, v48, v36
	v_fma_f32 v33, v33, v46, v48
	v_div_fixup_f32 v44, v33, v44, v36
	v_pk_mul_f32 v[16:17], v[16:17], v[44:45]
	v_lshlrev_b32_e32 v33, 16, v37
	v_cvt_pk_bf16_f32 v16, v16, v17
	v_and_b32_e32 v17, 0xffff0000, v37
	v_mul_f32_e32 v36, 0xbfb8aa3b, v33
	v_mul_f32_e32 v37, 0xbfb8aa3b, v17
	v_exp_f32_e32 v36, v36
	v_exp_f32_e32 v37, v37
	v_pk_mul_f32 v[18:19], v[18:19], v[32:33] op_sel_hi:[1,0]
	v_pk_add_f32 v[36:37], v[36:37], 1.0 op_sel_hi:[1,0]
	s_nop 0
	v_rcp_f32_e32 v45, v37
	s_nop 0
	v_fma_f32 v46, -v37, v45, 1.0
	v_fmac_f32_e32 v45, v46, v45
	v_mul_f32_e32 v47, v17, v45
	v_fma_f32 v48, -v37, v47, v17
	v_fmac_f32_e32 v47, v48, v45
	v_fma_f32 v44, -v37, v47, v17
	v_fma_f32 v44, v44, v45, v47
	v_div_fixup_f32 v37, v44, v37, v17
	v_rcp_f32_e32 v44, v36
	s_nop 0
	v_fma_f32 v45, -v36, v44, 1.0
	v_fmac_f32_e32 v44, v45, v44
	v_mul_f32_e32 v46, v33, v44
	v_fma_f32 v47, -v36, v46, v33
	v_fmac_f32_e32 v46, v47, v44
	v_fma_f32 v17, -v36, v46, v33
	v_fma_f32 v17, v17, v44, v46
	v_div_fixup_f32 v36, v17, v36, v33
	v_pk_mul_f32 v[18:19], v[18:19], v[36:37]
	v_lshlrev_b64 v[36:37], 1, v[150:151]
	v_cvt_pk_bf16_f32 v17, v18, v19
	v_lshl_add_u64 v[18:19], v[40:41], 0, v[38:39]
	global_store_dwordx2 v[18:19], v[16:17], off
	v_lshl_add_u64 v[16:17], v[42:43], 0, v[36:37]
	s_nop 0
	s_waitcnt lgkmcnt(0)
	v_mov_b32_e32 v16, v206
	v_mov_b32_e32 v17, v207
	v_and_b32_e32 v33, 0xffff0000, v16
	v_lshlrev_b32_e32 v16, 16, v16
	v_mul_f32_e32 v18, 0xbfb8aa3b, v16
	v_mul_f32_e32 v19, 0xbfb8aa3b, v33
	v_exp_f32_e32 v18, v18
	v_exp_f32_e32 v19, v19
	v_pk_mul_f32 v[20:21], v[20:21], v[32:33] op_sel_hi:[1,0]
	v_pk_add_f32 v[18:19], v[18:19], 1.0 op_sel_hi:[1,0]
	s_nop 0
	v_rcp_f32_e32 v45, v19
	s_nop 0
	v_fma_f32 v46, -v19, v45, 1.0
	v_fmac_f32_e32 v45, v46, v45
	v_mul_f32_e32 v47, v33, v45
	v_fma_f32 v48, -v19, v47, v33
	v_fmac_f32_e32 v47, v48, v45
	v_fma_f32 v44, -v19, v47, v33
	v_fma_f32 v44, v44, v45, v47
	v_div_fixup_f32 v19, v44, v19, v33
	v_rcp_f32_e32 v44, v18
	s_nop 0
	v_fma_f32 v45, -v18, v44, 1.0
	v_fmac_f32_e32 v44, v45, v44
	v_mul_f32_e32 v46, v16, v44
	v_fma_f32 v47, -v18, v46, v16
	v_fmac_f32_e32 v46, v47, v44
	v_fma_f32 v33, -v18, v46, v16
	v_fma_f32 v33, v33, v44, v46
	v_div_fixup_f32 v18, v33, v18, v16
	v_pk_mul_f32 v[18:19], v[20:21], v[18:19]
	v_and_b32_e32 v33, 0xffff0000, v17
	v_lshlrev_b32_e32 v17, 16, v17
	v_cvt_pk_bf16_f32 v16, v18, v19
	v_mul_f32_e32 v18, 0xbfb8aa3b, v17
	v_mul_f32_e32 v19, 0xbfb8aa3b, v33
	v_exp_f32_e32 v18, v18
	v_exp_f32_e32 v19, v19
	v_pk_mul_f32 v[20:21], v[22:23], v[32:33] op_sel_hi:[1,0]
	v_pk_add_f32 v[18:19], v[18:19], 1.0 op_sel_hi:[1,0]
	s_nop 0
	v_rcp_f32_e32 v23, v19
	s_nop 0
	v_fma_f32 v44, -v19, v23, 1.0
	v_fmac_f32_e32 v23, v44, v23
	v_mul_f32_e32 v45, v33, v23
	v_fma_f32 v46, -v19, v45, v33
	v_fmac_f32_e32 v45, v46, v23
	v_fma_f32 v22, -v19, v45, v33
	v_fma_f32 v22, v22, v23, v45
	v_div_fixup_f32 v19, v22, v19, v33
	v_rcp_f32_e32 v23, v18
	s_nop 0
	v_fma_f32 v33, -v18, v23, 1.0
	v_fmac_f32_e32 v23, v33, v23
	v_mul_f32_e32 v44, v17, v23
	v_fma_f32 v45, -v18, v44, v17
	v_fmac_f32_e32 v44, v45, v23
	v_fma_f32 v22, -v18, v44, v17
	v_fma_f32 v22, v22, v23, v44
	v_div_fixup_f32 v18, v22, v18, v17
	v_pk_mul_f32 v[18:19], v[20:21], v[18:19]
	s_nop 0
	v_cvt_pk_bf16_f32 v17, v18, v19
	v_lshl_add_u64 v[18:19], v[40:41], 0, v[36:37]
	global_store_dwordx2 v[18:19], v[16:17], off
	v_lshlrev_b64 v[18:19], 1, v[148:149]
	v_lshl_add_u64 v[16:17], v[42:43], 0, v[18:19]
	s_nop 0
	s_waitcnt lgkmcnt(0)
; DI size_t kblk(int row, int col, int nrows) { return ((size_t)(col >> 5) * nrows + row) * 32 + (col & 31); }
; DI float bf2f(bf16_t v) { return __uint_as_float(((unsigned)v) << 16); }
; DI unsigned pk2(float a, float b) { hwf32x2 f = {a, b}; hwbf16x2 r = __builtin_convertvector(f, hwbf16x2); return __builtin_bit_cast(unsigned, r); }
; DI float siluf_(float z) { return z / (1.f + __expf(-z)); }
; template <int MODE>
; DI void attn_mfma(const Params& p, int l, int b, int hd, int qb, unsigned char* smem) {
;     ...
;     for (int vt = 0; vt < 2; ++vt)
; #pragma unroll
;       for (int g4 = 0; g4 < 4; ++g4) {
;         const int v0 = vt * 32 + 8 * g4 + 4 * h2;
;         const ushort4 gt = *(const ushort4*)(P + qrow * PW + GATE + 512 + hd * 64 + v0);
;         uint2 o;
;         o.x = pk2(O[vt][4 * g4 + 0] * i0 * siluf_(bf2f(gt.x)), O[vt][4 * g4 + 1] * i0 * siluf_(bf2f(gt.y)));
;         o.y = pk2(O[vt][4 * g4 + 2] * i0 * siluf_(bf2f(gt.z)), O[vt][4 * g4 + 3] * i0 * siluf_(bf2f(gt.w)));
;         *(uint2*)(MIX + kblk((int)qrow, 512 + hd * 64 + v0, ROWS)) = o;
;       }
	v_mov_b32_e32 v16, v208
	v_mov_b32_e32 v17, v209
	v_and_b32_e32 v33, 0xffff0000, v16
	v_lshlrev_b32_e32 v16, 16, v16
	v_mul_f32_e32 v20, 0xbfb8aa3b, v16
	v_mul_f32_e32 v21, 0xbfb8aa3b, v33
	v_exp_f32_e32 v20, v20
	v_exp_f32_e32 v21, v21
	v_pk_mul_f32 v[22:23], v[24:25], v[32:33] op_sel_hi:[1,0]
	v_pk_add_f32 v[20:21], v[20:21], 1.0 op_sel_hi:[1,0]
	s_nop 0
	v_rcp_f32_e32 v25, v21
	s_nop 0
	v_fma_f32 v44, -v21, v25, 1.0
	v_fmac_f32_e32 v25, v44, v25
	v_mul_f32_e32 v45, v33, v25
	v_fma_f32 v46, -v21, v45, v33
	v_fmac_f32_e32 v45, v46, v25
	v_fma_f32 v24, -v21, v45, v33
	v_fma_f32 v24, v24, v25, v45
	v_div_fixup_f32 v21, v24, v21, v33
	v_rcp_f32_e32 v25, v20
	s_nop 0
	v_fma_f32 v33, -v20, v25, 1.0
	v_fmac_f32_e32 v25, v33, v25
	v_mul_f32_e32 v44, v16, v25
	v_fma_f32 v45, -v20, v44, v16
	v_fmac_f32_e32 v44, v45, v25
	v_fma_f32 v24, -v20, v44, v16
	v_fma_f32 v24, v24, v25, v44
	v_div_fixup_f32 v20, v24, v20, v16
	v_pk_mul_f32 v[20:21], v[22:23], v[20:21]
	v_and_b32_e32 v24, 0xffff0000, v17
	v_lshlrev_b32_e32 v17, 16, v17
	v_cvt_pk_bf16_f32 v16, v20, v21
	v_mul_f32_e32 v20, 0xbfb8aa3b, v17
	v_mul_f32_e32 v21, 0xbfb8aa3b, v24
	v_exp_f32_e32 v20, v20
	v_exp_f32_e32 v21, v21
	v_pk_mul_f32 v[22:23], v[26:27], v[32:33] op_sel_hi:[1,0]
	v_pk_add_f32 v[20:21], v[20:21], 1.0 op_sel_hi:[1,0]
	s_nop 0
	v_rcp_f32_e32 v26, v21
	s_nop 0
	v_fma_f32 v27, -v21, v26, 1.0
	v_fmac_f32_e32 v26, v27, v26
	v_mul_f32_e32 v33, v24, v26
	v_fma_f32 v44, -v21, v33, v24
	v_fmac_f32_e32 v33, v44, v26
	v_fma_f32 v25, -v21, v33, v24
	v_fma_f32 v25, v25, v26, v33
	v_div_fixup_f32 v21, v25, v21, v24
	v_rcp_f32_e32 v25, v20
	s_nop 0
	v_fma_f32 v26, -v20, v25, 1.0
	v_fmac_f32_e32 v25, v26, v25
	v_mul_f32_e32 v27, v17, v25
	v_fma_f32 v33, -v20, v27, v17
	v_fmac_f32_e32 v27, v33, v25
	v_fma_f32 v24, -v20, v27, v17
	v_fma_f32 v24, v24, v25, v27
	v_div_fixup_f32 v20, v24, v20, v17
	v_pk_mul_f32 v[20:21], v[22:23], v[20:21]
	v_pk_mul_f32 v[24:25], v[28:29], v[32:33] op_sel_hi:[1,0]
	v_cvt_pk_bf16_f32 v17, v20, v21
	v_lshl_add_u64 v[20:21], v[40:41], 0, v[18:19]
	global_store_dwordx2 v[20:21], v[16:17], off
	v_lshlrev_b64 v[16:17], 1, v[146:147]
	v_lshl_add_u64 v[20:21], v[42:43], 0, v[16:17]
	s_nop 0
	s_waitcnt lgkmcnt(0)
	v_mov_b32_e32 v20, v210
	v_mov_b32_e32 v21, v211
	v_and_b32_e32 v26, 0xffff0000, v20
	v_lshlrev_b32_e32 v20, 16, v20
	v_mul_f32_e32 v22, 0xbfb8aa3b, v20
	v_mul_f32_e32 v23, 0xbfb8aa3b, v26
	v_exp_f32_e32 v22, v22
	v_exp_f32_e32 v23, v23
	s_nop 0
	v_pk_add_f32 v[22:23], v[22:23], 1.0 op_sel_hi:[1,0]
	s_nop 0
	v_rcp_f32_e32 v28, v23
	s_nop 0
	v_fma_f32 v29, -v23, v28, 1.0
	v_fmac_f32_e32 v28, v29, v28
	v_mul_f32_e32 v33, v26, v28
	v_fma_f32 v42, -v23, v33, v26
	v_fmac_f32_e32 v33, v42, v28
	v_fma_f32 v27, -v23, v33, v26
	v_fma_f32 v27, v27, v28, v33
	v_div_fixup_f32 v23, v27, v23, v26
	v_rcp_f32_e32 v27, v22
	s_nop 0
	v_fma_f32 v28, -v22, v27, 1.0
	v_fmac_f32_e32 v27, v28, v27
	v_mul_f32_e32 v29, v20, v27
	v_fma_f32 v33, -v22, v29, v20
	v_fmac_f32_e32 v29, v33, v27
	v_fma_f32 v26, -v22, v29, v20
	v_fma_f32 v26, v26, v27, v29
	v_div_fixup_f32 v22, v26, v22, v20
	v_pk_mul_f32 v[22:23], v[24:25], v[22:23]
	v_and_b32_e32 v26, 0xffff0000, v21
	v_lshlrev_b32_e32 v21, 16, v21
	v_cvt_pk_bf16_f32 v20, v22, v23
	v_mul_f32_e32 v22, 0xbfb8aa3b, v21
	v_mul_f32_e32 v23, 0xbfb8aa3b, v26
	v_exp_f32_e32 v22, v22
	v_exp_f32_e32 v23, v23
	v_pk_mul_f32 v[24:25], v[30:31], v[32:33] op_sel_hi:[1,0]
	v_pk_mul_f32 v[0:1], v[0:1], v[32:33] op_sel_hi:[1,0]
	v_pk_mul_f32 v[2:3], v[2:3], v[32:33] op_sel_hi:[1,0]
	v_pk_add_f32 v[22:23], v[22:23], 1.0 op_sel_hi:[1,0]
	v_pk_mul_f32 v[4:5], v[4:5], v[32:33] op_sel_hi:[1,0]
	v_rcp_f32_e32 v28, v23
	s_nop 0
	v_fma_f32 v29, -v23, v28, 1.0
	v_fmac_f32_e32 v28, v29, v28
	v_mul_f32_e32 v30, v26, v28
	v_fma_f32 v31, -v23, v30, v26
	v_fmac_f32_e32 v30, v31, v28
	v_fma_f32 v27, -v23, v30, v26
	v_fma_f32 v27, v27, v28, v30
	v_div_fixup_f32 v23, v27, v23, v26
	v_rcp_f32_e32 v27, v22
	s_nop 0
	v_fma_f32 v28, -v22, v27, 1.0
	v_fmac_f32_e32 v27, v28, v27
	v_mul_f32_e32 v29, v21, v27
	v_fma_f32 v30, -v22, v29, v21
	v_fmac_f32_e32 v29, v30, v27
	v_fma_f32 v26, -v22, v29, v21
	v_fma_f32 v26, v26, v27, v29
	v_div_fixup_f32 v22, v26, v22, v21
	v_pk_mul_f32 v[22:23], v[24:25], v[22:23]
	s_nop 0
	v_cvt_pk_bf16_f32 v21, v22, v23
	v_lshl_add_u64 v[22:23], v[40:41], 0, v[16:17]
	global_store_dwordx2 v[22:23], v[20:21], off
	s_nop 0
	v_lshl_add_u64 v[20:21], v[144:145], 0, s[2:3]
	v_lshlrev_b64 v[20:21], 6, v[20:21]
	v_lshl_add_u64 v[20:21], s[0:1], 0, v[20:21]
	s_waitcnt lgkmcnt(0)
	v_mov_b32_e32 v22, v212
	v_mov_b32_e32 v23, v213
	v_and_b32_e32 v26, 0xffff0000, v22
	v_lshlrev_b32_e32 v22, 16, v22
	v_mul_f32_e32 v24, 0xbfb8aa3b, v22
	v_mul_f32_e32 v25, 0xbfb8aa3b, v26
	v_exp_f32_e32 v24, v24
	v_exp_f32_e32 v25, v25
	s_nop 0
	v_pk_add_f32 v[24:25], v[24:25], 1.0 op_sel_hi:[1,0]
	s_nop 0
	v_rcp_f32_e32 v28, v25
	s_nop 0
	v_fma_f32 v29, -v25, v28, 1.0
	v_fmac_f32_e32 v28, v29, v28
	v_mul_f32_e32 v30, v26, v28
	v_fma_f32 v31, -v25, v30, v26
	v_fmac_f32_e32 v30, v31, v28
	v_fma_f32 v27, -v25, v30, v26
	v_fma_f32 v27, v27, v28, v30
	v_div_fixup_f32 v25, v27, v25, v26
	v_rcp_f32_e32 v27, v24
	s_nop 0
	v_fma_f32 v28, -v24, v27, 1.0
	v_fmac_f32_e32 v27, v28, v27
	v_mul_f32_e32 v29, v22, v27
	v_fma_f32 v30, -v24, v29, v22
	v_fmac_f32_e32 v29, v30, v27
	v_fma_f32 v26, -v24, v29, v22
	v_fma_f32 v26, v26, v27, v29
	v_div_fixup_f32 v24, v26, v24, v22
	v_pk_mul_f32 v[0:1], v[0:1], v[24:25]
	v_lshlrev_b32_e32 v24, 16, v23
	v_cvt_pk_bf16_f32 v0, v0, v1
	v_and_b32_e32 v1, 0xffff0000, v23
	v_mul_f32_e32 v22, 0xbfb8aa3b, v24
	v_mul_f32_e32 v23, 0xbfb8aa3b, v1
	v_exp_f32_e32 v22, v22
	v_exp_f32_e32 v23, v23
	s_nop 0
	v_pk_add_f32 v[22:23], v[22:23], 1.0 op_sel_hi:[1,0]
	s_nop 0
	v_rcp_f32_e32 v26, v23
	s_nop 0
	v_fma_f32 v27, -v23, v26, 1.0
	v_fmac_f32_e32 v26, v27, v26
	v_mul_f32_e32 v28, v1, v26
	v_fma_f32 v29, -v23, v28, v1
	v_fmac_f32_e32 v28, v29, v26
	v_fma_f32 v25, -v23, v28, v1
	v_fma_f32 v25, v25, v26, v28
	v_div_fixup_f32 v23, v25, v23, v1
	v_rcp_f32_e32 v25, v22
	s_nop 0
	v_fma_f32 v26, -v22, v25, 1.0
	v_fmac_f32_e32 v25, v26, v25
	v_mul_f32_e32 v27, v24, v25
	v_fma_f32 v28, -v22, v27, v24
	v_fmac_f32_e32 v27, v28, v25
	v_fma_f32 v1, -v22, v27, v24
	v_fma_f32 v1, v1, v25, v27
	v_div_fixup_f32 v22, v1, v22, v24
	v_pk_mul_f32 v[2:3], v[2:3], v[22:23]
	s_nop 0
	v_cvt_pk_bf16_f32 v1, v2, v3
	v_lshl_add_u64 v[2:3], v[20:21], 0, v[38:39]
	global_store_dwordx2 v[2:3], v[0:1], off
	s_nop 0
	s_waitcnt lgkmcnt(0)
; DI size_t kblk(int row, int col, int nrows) { return ((size_t)(col >> 5) * nrows + row) * 32 + (col & 31); }
; DI float bf2f(bf16_t v) { return __uint_as_float(((unsigned)v) << 16); }
; DI unsigned pk2(float a, float b) { hwf32x2 f = {a, b}; hwbf16x2 r = __builtin_convertvector(f, hwbf16x2); return __builtin_bit_cast(unsigned, r); }
; DI float siluf_(float z) { return z / (1.f + __expf(-z)); }
; template <int MODE>
; DI void attn_mfma(const Params& p, int l, int b, int hd, int qb, unsigned char* smem) {
;     ...
;     for (int vt = 0; vt < 2; ++vt)
; #pragma unroll
;       for (int g4 = 0; g4 < 4; ++g4) {
;         const int v0 = vt * 32 + 8 * g4 + 4 * h2;
;         const ushort4 gt = *(const ushort4*)(P + qrow * PW + GATE + 512 + hd * 64 + v0);
;         uint2 o;
;         o.x = pk2(O[vt][4 * g4 + 0] * i0 * siluf_(bf2f(gt.x)), O[vt][4 * g4 + 1] * i0 * siluf_(bf2f(gt.y)));
;         o.y = pk2(O[vt][4 * g4 + 2] * i0 * siluf_(bf2f(gt.z)), O[vt][4 * g4 + 3] * i0 * siluf_(bf2f(gt.w)));
;         *(uint2*)(MIX + kblk((int)qrow, 512 + hd * 64 + v0, ROWS)) = o;
;       }
	v_mov_b32_e32 v0, v214
	v_mov_b32_e32 v1, v215
	v_and_b32_e32 v22, 0xffff0000, v0
	v_lshlrev_b32_e32 v0, 16, v0
	v_mul_f32_e32 v2, 0xbfb8aa3b, v0
	v_mul_f32_e32 v3, 0xbfb8aa3b, v22
	v_exp_f32_e32 v2, v2
	v_exp_f32_e32 v3, v3
	s_nop 0
	v_pk_add_f32 v[2:3], v[2:3], 1.0 op_sel_hi:[1,0]
	s_nop 0
	v_rcp_f32_e32 v24, v3
	s_nop 0
	v_fma_f32 v25, -v3, v24, 1.0
	v_fmac_f32_e32 v24, v25, v24
	v_mul_f32_e32 v26, v22, v24
	v_fma_f32 v27, -v3, v26, v22
	v_fmac_f32_e32 v26, v27, v24
	v_fma_f32 v23, -v3, v26, v22
	v_fma_f32 v23, v23, v24, v26
	v_div_fixup_f32 v3, v23, v3, v22
	v_rcp_f32_e32 v23, v2
	s_nop 0
	v_fma_f32 v24, -v2, v23, 1.0
	v_fmac_f32_e32 v23, v24, v23
	v_mul_f32_e32 v25, v0, v23
	v_fma_f32 v26, -v2, v25, v0
	v_fmac_f32_e32 v25, v26, v23
	v_fma_f32 v22, -v2, v25, v0
	v_fma_f32 v22, v22, v23, v25
	v_div_fixup_f32 v2, v22, v2, v0
	v_pk_mul_f32 v[2:3], v[4:5], v[2:3]
	v_and_b32_e32 v22, 0xffff0000, v1
	v_lshlrev_b32_e32 v1, 16, v1
	v_cvt_pk_bf16_f32 v0, v2, v3
	v_mul_f32_e32 v2, 0xbfb8aa3b, v1
	v_mul_f32_e32 v3, 0xbfb8aa3b, v22
	v_exp_f32_e32 v2, v2
	v_exp_f32_e32 v3, v3
	v_pk_mul_f32 v[4:5], v[6:7], v[32:33] op_sel_hi:[1,0]
	v_pk_add_f32 v[2:3], v[2:3], 1.0 op_sel_hi:[1,0]
	s_nop 0
	v_rcp_f32_e32 v7, v3
	s_nop 0
	v_fma_f32 v23, -v3, v7, 1.0
	v_fmac_f32_e32 v7, v23, v7
	v_mul_f32_e32 v24, v22, v7
	v_fma_f32 v25, -v3, v24, v22
	v_fmac_f32_e32 v24, v25, v7
	v_fma_f32 v6, -v3, v24, v22
	v_fma_f32 v6, v6, v7, v24
	v_div_fixup_f32 v3, v6, v3, v22
	v_rcp_f32_e32 v7, v2
	s_nop 0
	v_fma_f32 v22, -v2, v7, 1.0
	v_fmac_f32_e32 v7, v22, v7
	v_mul_f32_e32 v23, v1, v7
	v_fma_f32 v24, -v2, v23, v1
	v_fmac_f32_e32 v23, v24, v7
	v_fma_f32 v6, -v2, v23, v1
	v_fma_f32 v6, v6, v7, v23
	v_div_fixup_f32 v2, v6, v2, v1
	v_pk_mul_f32 v[2:3], v[4:5], v[2:3]
	v_pk_mul_f32 v[4:5], v[8:9], v[32:33] op_sel_hi:[1,0]
	v_cvt_pk_bf16_f32 v1, v2, v3
	v_lshl_add_u64 v[2:3], v[20:21], 0, v[36:37]
	global_store_dwordx2 v[2:3], v[0:1], off
	s_nop 0
	s_waitcnt lgkmcnt(0)
	v_mov_b32_e32 v0, v216
	v_mov_b32_e32 v1, v217
	v_and_b32_e32 v6, 0xffff0000, v0
	v_lshlrev_b32_e32 v0, 16, v0
	v_mul_f32_e32 v2, 0xbfb8aa3b, v0
	v_mul_f32_e32 v3, 0xbfb8aa3b, v6
	v_exp_f32_e32 v2, v2
	v_exp_f32_e32 v3, v3
	s_nop 0
	v_pk_add_f32 v[2:3], v[2:3], 1.0 op_sel_hi:[1,0]
	s_nop 0
	v_rcp_f32_e32 v8, v3
	s_nop 0
	v_fma_f32 v9, -v3, v8, 1.0
	v_fmac_f32_e32 v8, v9, v8
	v_mul_f32_e32 v22, v6, v8
	v_fma_f32 v23, -v3, v22, v6
	v_fmac_f32_e32 v22, v23, v8
	v_fma_f32 v7, -v3, v22, v6
	v_fma_f32 v7, v7, v8, v22
	v_div_fixup_f32 v3, v7, v3, v6
	v_rcp_f32_e32 v7, v2
	s_nop 0
	v_fma_f32 v8, -v2, v7, 1.0
	v_fmac_f32_e32 v7, v8, v7
	v_mul_f32_e32 v9, v0, v7
	v_fma_f32 v22, -v2, v9, v0
	v_fmac_f32_e32 v9, v22, v7
	v_fma_f32 v6, -v2, v9, v0
	v_fma_f32 v6, v6, v7, v9
	v_div_fixup_f32 v2, v6, v2, v0
	v_pk_mul_f32 v[2:3], v[4:5], v[2:3]
	v_and_b32_e32 v6, 0xffff0000, v1
	v_lshlrev_b32_e32 v1, 16, v1
	v_cvt_pk_bf16_f32 v0, v2, v3
	v_mul_f32_e32 v2, 0xbfb8aa3b, v1
	v_mul_f32_e32 v3, 0xbfb8aa3b, v6
	v_exp_f32_e32 v2, v2
	v_exp_f32_e32 v3, v3
	v_pk_mul_f32 v[4:5], v[10:11], v[32:33] op_sel_hi:[1,0]
	v_pk_add_f32 v[2:3], v[2:3], 1.0 op_sel_hi:[1,0]
	s_nop 0
	v_rcp_f32_e32 v8, v3
	s_nop 0
	v_fma_f32 v9, -v3, v8, 1.0
	v_fmac_f32_e32 v8, v9, v8
	v_mul_f32_e32 v10, v6, v8
	v_fma_f32 v11, -v3, v10, v6
	v_fmac_f32_e32 v10, v11, v8
	v_fma_f32 v7, -v3, v10, v6
	v_fma_f32 v7, v7, v8, v10
	v_div_fixup_f32 v3, v7, v3, v6
	v_rcp_f32_e32 v7, v2
	s_nop 0
	v_fma_f32 v8, -v2, v7, 1.0
	v_fmac_f32_e32 v7, v8, v7
	v_mul_f32_e32 v9, v1, v7
	v_fma_f32 v10, -v2, v9, v1
	v_fmac_f32_e32 v9, v10, v7
	v_fma_f32 v6, -v2, v9, v1
	v_fma_f32 v6, v6, v7, v9
	v_div_fixup_f32 v2, v6, v2, v1
	v_pk_mul_f32 v[2:3], v[4:5], v[2:3]
	v_pk_mul_f32 v[4:5], v[12:13], v[32:33] op_sel_hi:[1,0]
	v_cvt_pk_bf16_f32 v1, v2, v3
	v_lshl_add_u64 v[2:3], v[20:21], 0, v[18:19]
	global_store_dwordx2 v[2:3], v[0:1], off
	s_nop 0
	s_waitcnt lgkmcnt(0)
	v_mov_b32_e32 v0, v218
	v_mov_b32_e32 v1, v219
	v_and_b32_e32 v6, 0xffff0000, v0
	v_lshlrev_b32_e32 v0, 16, v0
	v_mul_f32_e32 v2, 0xbfb8aa3b, v0
	v_mul_f32_e32 v3, 0xbfb8aa3b, v6
	v_exp_f32_e32 v2, v2
	v_exp_f32_e32 v3, v3
	s_nop 0
	v_pk_add_f32 v[2:3], v[2:3], 1.0 op_sel_hi:[1,0]
	s_nop 0
	v_rcp_f32_e32 v8, v3
	s_nop 0
	v_fma_f32 v9, -v3, v8, 1.0
	v_fmac_f32_e32 v8, v9, v8
	v_mul_f32_e32 v10, v6, v8
	v_fma_f32 v11, -v3, v10, v6
	v_fmac_f32_e32 v10, v11, v8
	v_fma_f32 v7, -v3, v10, v6
	v_fma_f32 v7, v7, v8, v10
	v_div_fixup_f32 v3, v7, v3, v6
	v_rcp_f32_e32 v7, v2
	s_nop 0
	v_fma_f32 v8, -v2, v7, 1.0
	v_fmac_f32_e32 v7, v8, v7
	v_mul_f32_e32 v9, v0, v7
	v_fma_f32 v10, -v2, v9, v0
	v_fmac_f32_e32 v9, v10, v7
	v_fma_f32 v6, -v2, v9, v0
	v_fma_f32 v6, v6, v7, v9
	v_div_fixup_f32 v2, v6, v2, v0
	v_pk_mul_f32 v[2:3], v[4:5], v[2:3]
	v_and_b32_e32 v6, 0xffff0000, v1
	v_lshlrev_b32_e32 v1, 16, v1
	v_cvt_pk_bf16_f32 v0, v2, v3
	v_mul_f32_e32 v2, 0xbfb8aa3b, v1
	v_mul_f32_e32 v3, 0xbfb8aa3b, v6
	v_exp_f32_e32 v2, v2
	v_exp_f32_e32 v3, v3
	v_pk_mul_f32 v[4:5], v[14:15], v[32:33] op_sel_hi:[1,0]
	v_pk_add_f32 v[2:3], v[2:3], 1.0 op_sel_hi:[1,0]
	s_nop 0
	v_rcp_f32_e32 v8, v3
	s_nop 0
	v_fma_f32 v9, -v3, v8, 1.0
	v_fmac_f32_e32 v8, v9, v8
	v_mul_f32_e32 v10, v6, v8
	v_fma_f32 v11, -v3, v10, v6
	v_fmac_f32_e32 v10, v11, v8
	v_fma_f32 v7, -v3, v10, v6
	v_fma_f32 v7, v7, v8, v10
	v_div_fixup_f32 v3, v7, v3, v6
	v_rcp_f32_e32 v7, v2
	s_nop 0
	v_fma_f32 v8, -v2, v7, 1.0
	v_fmac_f32_e32 v7, v8, v7
	v_mul_f32_e32 v9, v1, v7
	v_fma_f32 v10, -v2, v9, v1
	v_fmac_f32_e32 v9, v10, v7
	v_fma_f32 v6, -v2, v9, v1
	v_fma_f32 v6, v6, v7, v9
	v_div_fixup_f32 v2, v6, v2, v1
	v_pk_mul_f32 v[2:3], v[4:5], v[2:3]
	s_nop 0
	v_cvt_pk_bf16_f32 v1, v2, v3
	v_lshl_add_u64 v[2:3], v[20:21], 0, v[16:17]
	global_store_dwordx2 v[2:3], v[0:1], off

; DI size_t kblk(int row, int col, int nrows) { return ((size_t)(col >> 5) * nrows + row) * 32 + (col & 31); }
; #define MFMA16(a, b, c) __builtin_amdgcn_mfma_f32_16x16x32_bf16((a), (b), (c), 0, 0, 0)
; template <int MX, bool OUT>
; DI void rec_chunk(const Params& p, int l, int b, int h, int dir, int T0, unsigned char* smem, f32x4 (&St)[4], float& nst, float& dtot, int tid, const RecRaw& raw) {
;     ...
;     for (int ks = 0; ks < 2; ++ks) {
;       const bf16x8 fb = *(const bf16x8*)(smem + L_QS + swz(t, ks * 4 + g));
; #pragma unroll
;       for (int a = 0; a < 4; ++a) {
;         const bf16x8 fa = *(const bf16x8*)(smem + L_STT + swz(16 * a + col, ks * 4 + g));
;         O[a] = MFMA16(fa, fb, O[a]);
;       }
;     }
;     if (MX == 1) {
;       const float inv = 1.f / fmaxf(fabsf(den), 1.f);
; #pragma unroll
;       for (int a = 0; a < 4; ++a)
; #pragma unroll
;         for (int j = 0; j < 4; ++j) O[a][j] *= inv;
;     }
;     ...
;     } else {
;       float ss = 0.f;
; #pragma unroll
;       for (int a = 0; a < 4; ++a) {
;         const uint2 u = *(const uint2*)(MIX + kblk((int)orow, cb + 16 * a + 4 * g, ROWS));
;         O[a][0] += __uint_as_float(u.x << 16); O[a][1] += __uint_as_float(u.x & 0xffff0000u);
;         O[a][2] += __uint_as_float(u.y << 16); O[a][3] += __uint_as_float(u.y & 0xffff0000u);
.LBB0_928:
	s_or_b64 exec, exec, s[0:1]
	ds_read_b128 v[42:45], v242 offset:32768
	ds_read_b128 v[46:49], v240 offset:57344
	ds_read_b128 v[50:53], v240 offset:59392
	s_add_i32 s0, s54, -1
	v_mov_b32_e32 v40, s0
	v_cndmask_b32_e64 v40, v93, v40, s[40:41]
	s_waitcnt lgkmcnt(1)
	v_mfma_f32_16x16x32_bf16 v[46:49], v[46:49], v[42:45], v[56:59]
	v_lshlrev_b32_e32 v40, 6, v40
	v_add_u32_e32 v40, s49, v40
	v_mov_b32_e32 v41, v161
	ds_read_b128 v[54:57], v240 offset:61440
	s_waitcnt lgkmcnt(1)
	v_mfma_f32_16x16x32_bf16 v[50:53], v[50:53], v[42:45], v[60:63]
	v_lshl_add_u64 v[40:41], v[40:41], 0, v[84:85]
	s_nop 1
	ds_read_b128 v[58:61], v240 offset:63488
	s_waitcnt lgkmcnt(1)
	v_mfma_f32_16x16x32_bf16 v[54:57], v[54:57], v[42:45], v[64:67]
	s_waitcnt lgkmcnt(0)
	v_mfma_f32_16x16x32_bf16 v[42:45], v[58:61], v[42:45], v[72:75]
	ds_read_b128 v[58:61], v241 offset:32768
	ds_read_b128 v[62:65], v239 offset:57344
	s_waitcnt lgkmcnt(0)
	v_mfma_f32_16x16x32_bf16 v[46:49], v[62:65], v[58:61], v[46:49]
	ds_read_b128 v[62:65], v239 offset:59392
	s_waitcnt lgkmcnt(0)
	v_mfma_f32_16x16x32_bf16 v[50:53], v[62:65], v[58:61], v[50:53]
	ds_read_b128 v[62:65], v239 offset:61440
	s_waitcnt lgkmcnt(0)
	v_mfma_f32_16x16x32_bf16 v[62:65], v[62:65], v[58:61], v[54:57]
	s_nop 2
	ds_read_b128 v[54:57], v239 offset:63488
	s_waitcnt lgkmcnt(0)
	v_mfma_f32_16x16x32_bf16 v[42:45], v[54:57], v[58:61], v[42:45]
	v_add_f32_e32 v54, v95, v100
	v_max_f32_e64 v54, |v54|, 1.0
	v_rcp_f32_e32 v56, v54
	s_mov_b64 s[0:1], -1
	v_fma_f32 v57, -v54, v56, 1.0
	v_fmac_f32_e32 v56, v57, v56
	v_mov_b32_e64 v57, 1.0
	v_mul_f32_e32 v58, v57, v56
	v_fma_f32 v59, -v54, v58, v57
	v_fmac_f32_e32 v58, v59, v56
	v_fma_f32 v55, -v54, v58, v57
	v_fma_f32 v55, v55, v56, v58
	v_div_fixup_f32 v60, v55, v54, 1.0
	v_pk_mul_f32 v[54:55], v[60:61], v[46:47] op_sel_hi:[0,1]
	v_pk_mul_f32 v[46:47], v[60:61], v[42:43] op_sel_hi:[0,1]
	v_ashrrev_i32_e32 v43, 31, v40
	v_mov_b32_e32 v42, v40
	v_pk_mul_f32 v[58:59], v[60:61], v[48:49] op_sel_hi:[0,1]
	v_pk_mul_f32 v[50:51], v[60:61], v[50:51] op_sel_hi:[0,1]
	v_pk_mul_f32 v[56:57], v[60:61], v[52:53] op_sel_hi:[0,1]
	v_pk_mul_f32 v[48:49], v[60:61], v[62:63] op_sel_hi:[0,1]
	v_pk_mul_f32 v[52:53], v[60:61], v[64:65] op_sel_hi:[0,1]
	v_pk_mul_f32 v[44:45], v[60:61], v[44:45] op_sel_hi:[0,1]
	v_lshl_add_u64 v[60:61], v[42:43], 0, s[42:43]
	v_lshl_add_u64 v[62:63], v[42:43], 0, s[28:29]
	v_lshl_add_u64 v[42:43], v[42:43], 0, s[30:31]
	s_andn2_b64 vcc, exec, s[12:13]
	v_lshlrev_b64 v[64:65], 6, v[60:61]
	v_lshlrev_b64 v[62:63], 6, v[62:63]
	v_lshlrev_b64 v[60:61], 6, v[42:43]
	s_cbranch_vccnz .LBB0_930
	v_lshl_add_u64 v[102:103], v[90:91], 0, v[62:63]
	global_load_dwordx2 v[66:67], v[102:103], off
	v_mov_b64_e32 v[42:43], s[24:25]
	v_mad_u64_u32 v[42:43], s[0:1], v40, s33, v[42:43]
	v_mad_i32_i24 v43, v41, s33, v43
	s_mov_b64 s[0:1], 0x1a20
	v_mov_b32_e32 v93, v161
	v_lshl_add_u64 v[74:75], v[42:43], 0, s[0:1]
	v_lshl_add_u64 v[104:105], v[74:75], 0, s[2:3]
	v_lshl_add_u64 v[74:75], v[74:75], 0, v[92:93]
	v_lshl_add_u64 v[106:107], v[86:87], 0, v[64:65]
	v_lshl_add_u64 v[74:75], v[74:75], 0, s[2:3]
	global_load_dwordx2 v[40:41], v[106:107], off
	s_mov_b32 s21, s3
	v_lshl_add_u64 v[42:43], v[42:43], 0, s[20:21]
	v_lshl_add_u64 v[42:43], v[42:43], 0, v[92:93]
	s_mov_b64 s[0:1], 0x1820
	v_lshl_add_u64 v[104:105], v[104:105], 0, v[92:93]
	global_load_dwordx2 v[74:75], v[74:75], off
	s_waitcnt vmcnt(0) lgkmcnt(0)
	v_lshlrev_b32_e32 v100, 16, v66
	v_and_b32_e32 v101, 0xffff0000, v66
	v_lshlrev_b32_e32 v108, 16, v67
	v_and_b32_e32 v109, 0xffff0000, v67
	v_lshl_add_u64 v[66:67], s[22:23], 0, v[60:61]
	v_lshl_add_u64 v[72:73], v[66:67], 0, v[92:93]
	global_load_dwordx2 v[68:69], v[72:73], off
	v_lshlrev_b32_e32 v128, 16, v40
	v_and_b32_e32 v129, 0xffff0000, v40
	v_lshlrev_b32_e32 v40, 16, v41
	v_and_b32_e32 v41, 0xffff0000, v41
	v_pk_add_f32 v[128:129], v[54:55], v[128:129]
	v_lshlrev_b32_e32 v95, 16, v74
	v_and_b32_e32 v243, 0xffff0000, v74
	v_lshlrev_b32_e32 v130, 16, v75
	v_and_b32_e32 v131, 0xffff0000, v75
	v_lshl_add_u64 v[74:75], v[42:43], 0, s[0:1]
	v_add_co_u32_e32 v42, vcc, s16, v42
	v_mul_f32_e32 v120, 0xbfb8aa3b, v130
	s_nop 0
	v_addc_co_u32_e32 v43, vcc, 0, v43, vcc
	v_mul_f32_e32 v121, 0xbfb8aa3b, v131
	global_load_dwordx2 v[42:43], v[42:43], off offset:2080
	v_exp_f32_e32 v120, v120
	v_exp_f32_e32 v121, v121
	s_waitcnt vmcnt(0) lgkmcnt(0)
; DI size_t kblk(int row, int col, int nrows) { return ((size_t)(col >> 5) * nrows + row) * 32 + (col & 31); }
; DI unsigned pk2(float a, float b) { hwf32x2 f = {a, b}; hwbf16x2 r = __builtin_convertvector(f, hwbf16x2); return __builtin_bit_cast(unsigned, r); }
; DI float sigmoidf_(float z) { return 1.f / (1.f + __expf(-z)); }
; DI float siluf_(float z) { return z / (1.f + __expf(-z)); }
; template <int MX, bool OUT>
; DI void rec_chunk(const Params& p, int l, int b, int h, int dir, int T0, unsigned char* smem, f32x4 (&St)[4], float& nst, float& dtot, int tid, const RecRaw& raw) {
;     ...
;     } else {
;       float ss = 0.f;
; #pragma unroll
;       for (int a = 0; a < 4; ++a) {
;         const uint2 u = *(const uint2*)(MIX + kblk((int)orow, cb + 16 * a + 4 * g, ROWS));
;         O[a][0] += __uint_as_float(u.x << 16); O[a][1] += __uint_as_float(u.x & 0xffff0000u);
;         O[a][2] += __uint_as_float(u.y << 16); O[a][3] += __uint_as_float(u.y & 0xffff0000u);
; #pragma unroll
;         for (int j = 0; j < 4; ++j) ss += O[a][j] * O[a][j];
;       }
;       ss += __shfl_xor(ss, 16);
;       ss += __shfl_xor(ss, 32);
;       const float rstd = rsqrtf(ss * (1.f / 64.f) + EPS);
;       const float* gvec = (MX ? p.ml_g : p.hg_g) + l * 64;
; #pragma unroll
;       for (int a = 0; a < 4; ++a) {
;         const int v0 = 16 * a + 4 * g;
;         const uint2 gt = *(const uint2*)(prow + GATE + cb + v0);
;         const float4 gg = *(const float4*)(gvec + v0);
;         float y0 = O[a][0] * rstd * gg.x * siluf_(__uint_as_float(gt.x << 16));
;         float y1 = O[a][1] * rstd * gg.y * siluf_(__uint_as_float(gt.x & 0xffff0000u));
;         float y2 = O[a][2] * rstd * gg.z * siluf_(__uint_as_float(gt.y << 16));
;         float y3 = O[a][3] * rstd * gg.w * siluf_(__uint_as_float(gt.y & 0xffff0000u));
;         if (MX == 1) {
;           const uint2 og = *(const uint2*)(prow + D_OG + h * 64 + v0);
;           y0 *= sigmoidf_(__uint_as_float(og.x << 16)); y1 *= sigmoidf_(__uint_as_float(og.x & 0xffff0000u));
;           y2 *= sigmoidf_(__uint_as_float(og.y << 16)); y3 *= sigmoidf_(__uint_as_float(og.y & 0xffff0000u));
;         }
;         *(uint2*)(MIX + kblk((int)orow, cb + v0, ROWS)) = make_uint2(pk2(y0, y1), pk2(y2, y3));
	v_lshlrev_b32_e32 v110, 16, v68
	v_and_b32_e32 v111, 0xffff0000, v68
	v_pk_add_f32 v[120:121], v[120:121], 1.0 op_sel_hi:[1,0]
	v_lshlrev_b32_e32 v112, 16, v69
	v_rcp_f32_e32 v133, v121
	v_and_b32_e32 v113, 0xffff0000, v69
	global_load_dwordx2 v[68:69], v[72:73], off offset:32
	v_pk_add_f32 v[110:111], v[48:49], v[110:111]
	v_fma_f32 v244, -v121, v133, 1.0
	v_fmac_f32_e32 v133, v244, v133
	v_mul_f32_e32 v245, v131, v133
	v_fma_f32 v246, -v121, v245, v131
	v_fmac_f32_e32 v245, v246, v133
	v_fma_f32 v132, -v121, v245, v131
	v_fma_f32 v132, v132, v133, v245
	v_div_fixup_f32 v121, v132, v121, v131
	v_rcp_f32_e32 v132, v120
	v_pk_mul_f32 v[250:251], v[110:111], v[110:111]
	v_lshlrev_b32_e32 v118, 16, v42
	v_and_b32_e32 v42, 0xffff0000, v42
	v_fma_f32 v133, -v120, v132, 1.0
	v_fmac_f32_e32 v132, v133, v132
	v_mul_f32_e32 v244, v130, v132
	v_fma_f32 v245, -v120, v244, v130
	v_fmac_f32_e32 v244, v245, v132
	v_fma_f32 v131, -v120, v244, v130
	v_fma_f32 v131, v131, v132, v244
	v_mul_f32_e32 v132, 0xbfb8aa3b, v95
	v_mul_f32_e32 v133, 0xbfb8aa3b, v243
	v_exp_f32_e32 v132, v132
	v_exp_f32_e32 v133, v133
	v_div_fixup_f32 v120, v131, v120, v130
	v_pk_mul_f32 v[130:131], v[128:129], v[128:129]
	v_mul_f32_e32 v118, 0xbfb8aa3b, v118
	v_pk_add_f32 v[132:133], v[132:133], 1.0 op_sel_hi:[1,0]
	v_mul_f32_e32 v42, 0xbfb8aa3b, v42
	v_rcp_f32_e32 v245, v133
	v_add_f32_e32 v93, v130, v131
	v_exp_f32_e32 v126, v118
	v_exp_f32_e32 v127, v42
	v_fma_f32 v246, -v133, v245, 1.0
	v_fmac_f32_e32 v245, v246, v245
	v_mul_f32_e32 v247, v243, v245
	v_fma_f32 v248, -v133, v247, v243
	v_fmac_f32_e32 v247, v248, v245
	v_fma_f32 v244, -v133, v247, v243
	v_fma_f32 v244, v244, v245, v247
	v_div_fixup_f32 v133, v244, v133, v243
	v_rcp_f32_e32 v244, v132
	v_lshlrev_b32_e32 v42, 16, v43
	v_pk_add_f32 v[118:119], v[58:59], v[40:41]
	v_pk_add_f32 v[248:249], v[50:51], v[100:101]
	v_fma_f32 v245, -v132, v244, 1.0
	v_fmac_f32_e32 v244, v245, v244
	v_mul_f32_e32 v246, v95, v244
	v_fma_f32 v247, -v132, v246, v95
	v_fmac_f32_e32 v246, v247, v244
	v_fma_f32 v243, -v132, v246, v95
	v_fma_f32 v243, v243, v244, v246
	v_div_fixup_f32 v132, v243, v132, v95
	v_pk_mul_f32 v[100:101], v[248:249], v[248:249]
	v_mul_f32_e32 v42, 0xbfb8aa3b, v42
	v_pk_mul_f32 v[122:123], v[118:119], v[118:119]
	v_exp_f32_e32 v124, v42
	v_and_b32_e32 v42, 0xffff0000, v43
	v_add_f32_e32 v93, v93, v122
	v_mul_f32_e32 v42, 0xbfb8aa3b, v42
	v_add_f32_e32 v93, v123, v93
	v_pk_add_f32 v[126:127], v[126:127], 1.0 op_sel_hi:[1,0]
	v_exp_f32_e32 v125, v42
	global_load_dwordx4 v[40:43], v[88:89], off
	v_rcp_f32_e32 v243, v127
	v_pk_add_f32 v[124:125], v[124:125], 1.0 op_sel_hi:[1,0]
	v_add_f32_e32 v93, v100, v93
	v_add_f32_e32 v93, v101, v93
	v_fma_f32 v244, -v127, v243, 1.0
	v_fmac_f32_e32 v243, v244, v243
	v_mov_b32_e64 v244, 1.0
	v_mul_f32_e32 v245, v244, v243
	v_fma_f32 v246, -v127, v245, v244
	v_fmac_f32_e32 v245, v246, v243
	v_fma_f32 v95, -v127, v245, v244
	v_fma_f32 v95, v95, v243, v245
	v_div_fixup_f32 v127, v95, v127, 1.0
	v_rcp_f32_e32 v243, v126
	s_waitcnt vmcnt(0) lgkmcnt(0)
	v_lshlrev_b32_e32 v70, 16, v68
	v_and_b32_e32 v71, 0xffff0000, v68
	v_pk_add_f32 v[70:71], v[46:47], v[70:71]
	v_fma_f32 v244, -v126, v243, 1.0
	v_fmac_f32_e32 v243, v244, v243
	v_mov_b32_e64 v244, 1.0
	v_mul_f32_e32 v245, v244, v243
	v_fma_f32 v246, -v126, v245, v244
	v_fmac_f32_e32 v245, v246, v243
	v_fma_f32 v95, -v126, v245, v244
	v_fma_f32 v95, v95, v243, v245
	v_div_fixup_f32 v126, v95, v126, 1.0
	v_rcp_f32_e32 v243, v125
	v_lshlrev_b32_e32 v68, 16, v69
	v_and_b32_e32 v69, 0xffff0000, v69
	v_pk_mul_f32 v[114:115], v[70:71], v[70:71]
	v_fma_f32 v244, -v125, v243, 1.0
	v_fmac_f32_e32 v243, v244, v243
	v_mov_b32_e64 v244, 1.0
	v_mul_f32_e32 v245, v244, v243
	v_fma_f32 v246, -v125, v245, v244
	v_fmac_f32_e32 v245, v246, v243
	v_fma_f32 v95, -v125, v245, v244
	v_fma_f32 v95, v95, v243, v245
	v_div_fixup_f32 v125, v95, v125, 1.0
	v_rcp_f32_e32 v243, v124
	v_pk_add_f32 v[68:69], v[44:45], v[68:69]
	v_fma_f32 v244, -v124, v243, 1.0
	v_fmac_f32_e32 v243, v244, v243
	v_mov_b32_e64 v244, 1.0
	v_mul_f32_e32 v245, v244, v243
	v_fma_f32 v246, -v124, v245, v244
	v_fmac_f32_e32 v245, v246, v243
	v_fma_f32 v95, -v124, v245, v244
	v_fma_f32 v95, v95, v243, v245
	v_pk_add_f32 v[244:245], v[56:57], v[108:109]
	v_pk_add_f32 v[108:109], v[52:53], v[112:113]
	v_pk_mul_f32 v[246:247], v[244:245], v[244:245]
	v_pk_mul_f32 v[112:113], v[108:109], v[108:109]
	v_add_f32_e32 v93, v246, v93
	v_add_f32_e32 v93, v247, v93
	v_add_f32_e32 v93, v250, v93
	v_add_f32_e32 v93, v251, v93
	v_add_f32_e32 v93, v112, v93
	v_add_f32_e32 v93, v113, v93
	v_add_f32_e32 v93, v114, v93
	v_pk_mul_f32 v[116:117], v[68:69], v[68:69]
	v_add_f32_e32 v93, v115, v93
	v_add_f32_e32 v93, v116, v93
	v_add_f32_e32 v93, v117, v93
	v_div_fixup_f32 v124, v95, v124, 1.0
	ds_bpermute_b32 v95, v149, v93
	s_waitcnt lgkmcnt(0)
	v_add_f32_e32 v93, v93, v95
	ds_bpermute_b32 v95, v150, v93
	s_waitcnt lgkmcnt(0)
	v_add_f32_e32 v93, v93, v95
	v_fmamk_f32 v93, v93, 0x3c800000, v162
	v_cmp_gt_f32_e32 vcc, s38, v93
	v_mul_f32_e32 v95, 0x4b800000, v93
	s_nop 0
	v_cndmask_b32_e32 v93, v93, v95, vcc
	v_rsq_f32_e32 v93, v93
	s_nop 0
	v_mul_f32_e32 v95, 0x45800000, v93
	v_cndmask_b32_e32 v100, v93, v95, vcc
	v_pk_mul_f32 v[112:113], v[128:129], v[100:101] op_sel_hi:[1,0]
	s_nop 0
	v_pk_mul_f32 v[40:41], v[40:41], v[112:113]
	v_pk_mul_f32 v[112:113], v[118:119], v[100:101] op_sel_hi:[1,0]
	v_pk_mul_f32 v[40:41], v[132:133], v[40:41]
	v_pk_mul_f32 v[42:43], v[42:43], v[112:113]
	v_pk_mul_f32 v[40:41], v[126:127], v[40:41]
	v_pk_mul_f32 v[42:43], v[120:121], v[42:43]
	v_cvt_pk_bf16_f32 v40, v40, v41
	v_pk_mul_f32 v[42:43], v[124:125], v[42:43]
	s_nop 0
	v_cvt_pk_bf16_f32 v41, v42, v43
	global_store_dwordx2 v[106:107], v[40:41], off
	global_load_dwordx2 v[40:41], v[104:105], off offset:32
	s_nop 0
	global_load_dwordx4 v[112:115], v[88:89], off offset:64
	v_pk_mul_f32 v[106:107], v[248:249], v[100:101] op_sel_hi:[1,0]
	s_waitcnt vmcnt(0) lgkmcnt(0)
; DI size_t kblk(int row, int col, int nrows) { return ((size_t)(col >> 5) * nrows + row) * 32 + (col & 31); }
; DI unsigned pk2(float a, float b) { hwf32x2 f = {a, b}; hwbf16x2 r = __builtin_convertvector(f, hwbf16x2); return __builtin_bit_cast(unsigned, r); }
; DI float sigmoidf_(float z) { return 1.f / (1.f + __expf(-z)); }
; DI float siluf_(float z) { return z / (1.f + __expf(-z)); }
; template <int MX, bool OUT>
; DI void rec_chunk(const Params& p, int l, int b, int h, int dir, int T0, unsigned char* smem, f32x4 (&St)[4], float& nst, float& dtot, int tid, const RecRaw& raw) {
;     ...
;       for (int a = 0; a < 4; ++a) {
;         const int v0 = 16 * a + 4 * g;
;         const uint2 gt = *(const uint2*)(prow + GATE + cb + v0);
;         const float4 gg = *(const float4*)(gvec + v0);
;         float y0 = O[a][0] * rstd * gg.x * siluf_(__uint_as_float(gt.x << 16));
;         float y1 = O[a][1] * rstd * gg.y * siluf_(__uint_as_float(gt.x & 0xffff0000u));
;         float y2 = O[a][2] * rstd * gg.z * siluf_(__uint_as_float(gt.y << 16));
;         float y3 = O[a][3] * rstd * gg.w * siluf_(__uint_as_float(gt.y & 0xffff0000u));
;         if (MX == 1) {
;           const uint2 og = *(const uint2*)(prow + D_OG + h * 64 + v0);
;           y0 *= sigmoidf_(__uint_as_float(og.x << 16)); y1 *= sigmoidf_(__uint_as_float(og.x & 0xffff0000u));
;           y2 *= sigmoidf_(__uint_as_float(og.y << 16)); y3 *= sigmoidf_(__uint_as_float(og.y & 0xffff0000u));
;         }
;         *(uint2*)(MIX + kblk((int)orow, cb + v0, ROWS)) = make_uint2(pk2(y0, y1), pk2(y2, y3));
	v_lshlrev_b32_e32 v93, 16, v40
	v_and_b32_e32 v40, 0xffff0000, v40
	v_mul_f32_e32 v42, 0xbfb8aa3b, v93
	v_mul_f32_e32 v43, 0xbfb8aa3b, v40
	v_exp_f32_e32 v42, v42
	v_exp_f32_e32 v43, v43
	v_pk_mul_f32 v[106:107], v[112:113], v[106:107]
	v_pk_add_f32 v[42:43], v[42:43], 1.0 op_sel_hi:[1,0]
	s_nop 0
	v_rcp_f32_e32 v101, v43
	s_nop 0
	v_fma_f32 v112, -v43, v101, 1.0
	v_fmac_f32_e32 v101, v112, v101
	v_mul_f32_e32 v113, v40, v101
	v_fma_f32 v116, -v43, v113, v40
	v_fmac_f32_e32 v113, v116, v101
	v_fma_f32 v95, -v43, v113, v40
	v_fma_f32 v95, v95, v101, v113
	v_div_fixup_f32 v43, v95, v43, v40
	v_rcp_f32_e32 v95, v42
	s_nop 0
	v_fma_f32 v101, -v42, v95, 1.0
	v_fmac_f32_e32 v95, v101, v95
	v_mul_f32_e32 v112, v93, v95
	v_fma_f32 v113, -v42, v112, v93
	v_fmac_f32_e32 v112, v113, v95
	v_fma_f32 v40, -v42, v112, v93
	v_fma_f32 v40, v40, v95, v112
	v_div_fixup_f32 v42, v40, v42, v93
	v_lshlrev_b32_e32 v93, 16, v41
	v_and_b32_e32 v95, 0xffff0000, v41
	v_mul_f32_e32 v40, 0xbfb8aa3b, v93
	v_mul_f32_e32 v41, 0xbfb8aa3b, v95
	v_exp_f32_e32 v40, v40
	v_exp_f32_e32 v41, v41
	v_pk_mul_f32 v[42:43], v[42:43], v[106:107]
	v_pk_mul_f32 v[106:107], v[244:245], v[100:101] op_sel_hi:[1,0]
	v_pk_add_f32 v[40:41], v[40:41], 1.0 op_sel_hi:[1,0]
	s_nop 0
	v_rcp_f32_e32 v112, v41
	v_pk_mul_f32 v[106:107], v[114:115], v[106:107]
	v_fma_f32 v113, -v41, v112, 1.0
	v_fmac_f32_e32 v112, v113, v112
	v_mul_f32_e32 v114, v95, v112
	v_fma_f32 v115, -v41, v114, v95
	v_fmac_f32_e32 v114, v115, v112
	v_fma_f32 v101, -v41, v114, v95
	v_fma_f32 v101, v101, v112, v114
	v_div_fixup_f32 v41, v101, v41, v95
	v_rcp_f32_e32 v101, v40
	s_nop 0
	v_fma_f32 v112, -v40, v101, 1.0
	v_fmac_f32_e32 v101, v112, v101
	v_mul_f32_e32 v113, v93, v101
	v_fma_f32 v114, -v40, v113, v93
	v_fmac_f32_e32 v113, v114, v101
	v_fma_f32 v95, -v40, v113, v93
	v_fma_f32 v95, v95, v101, v113
	v_div_fixup_f32 v40, v95, v40, v93
	v_pk_mul_f32 v[40:41], v[40:41], v[106:107]
	global_load_dwordx2 v[106:107], v[74:75], off offset:32
	s_waitcnt vmcnt(0) lgkmcnt(0)
	v_lshlrev_b32_e32 v93, 16, v106
	v_mul_f32_e32 v93, 0xbfb8aa3b, v93
	v_exp_f32_e32 v112, v93
	v_and_b32_e32 v93, 0xffff0000, v106
	v_mul_f32_e32 v93, 0xbfb8aa3b, v93
	v_exp_f32_e32 v113, v93
	s_nop 0
	v_pk_add_f32 v[112:113], v[112:113], 1.0 op_sel_hi:[1,0]
	s_nop 0
	v_rcp_f32_e32 v95, v113
	s_nop 0
	v_fma_f32 v101, -v113, v95, 1.0
	v_fmac_f32_e32 v95, v101, v95
	v_mov_b32_e64 v101, 1.0
	v_mul_f32_e32 v106, v101, v95
	v_fma_f32 v114, -v113, v106, v101
	v_fmac_f32_e32 v106, v114, v95
	v_fma_f32 v93, -v113, v106, v101
	v_fma_f32 v93, v93, v95, v106
	v_div_fixup_f32 v113, v93, v113, 1.0
	v_rcp_f32_e32 v95, v112
	s_nop 0
	v_fma_f32 v101, -v112, v95, 1.0
	v_fmac_f32_e32 v95, v101, v95
	v_mov_b32_e64 v101, 1.0
	v_mul_f32_e32 v106, v101, v95
	v_fma_f32 v114, -v112, v106, v101
	v_fmac_f32_e32 v106, v114, v95
	v_fma_f32 v93, -v112, v106, v101
	v_fma_f32 v93, v93, v95, v106
	v_div_fixup_f32 v112, v93, v112, 1.0
	v_lshlrev_b32_e32 v93, 16, v107
	v_mul_f32_e32 v93, 0xbfb8aa3b, v93
	v_exp_f32_e32 v106, v93
	v_and_b32_e32 v93, 0xffff0000, v107
	v_mul_f32_e32 v93, 0xbfb8aa3b, v93
	v_exp_f32_e32 v107, v93
	v_pk_mul_f32 v[42:43], v[42:43], v[112:113]
	v_pk_add_f32 v[106:107], v[106:107], 1.0 op_sel_hi:[1,0]
	s_nop 0
	v_rcp_f32_e32 v95, v107
	v_cvt_pk_bf16_f32 v42, v42, v43
	v_fma_f32 v101, -v107, v95, 1.0
	v_fmac_f32_e32 v95, v101, v95
	v_mov_b32_e64 v101, 1.0
	v_mul_f32_e32 v112, v101, v95
	v_fma_f32 v113, -v107, v112, v101
	v_fmac_f32_e32 v112, v113, v95
	v_fma_f32 v93, -v107, v112, v101
	v_fma_f32 v93, v93, v95, v112
	v_div_fixup_f32 v107, v93, v107, 1.0
	v_rcp_f32_e32 v95, v106
	s_nop 0
	v_fma_f32 v101, -v106, v95, 1.0
	v_fmac_f32_e32 v95, v101, v95
	v_mov_b32_e64 v101, 1.0
	v_mul_f32_e32 v112, v101, v95
	v_fma_f32 v113, -v106, v112, v101
	v_fmac_f32_e32 v112, v113, v95
	v_fma_f32 v93, -v106, v112, v101
	v_fma_f32 v93, v93, v95, v112
	v_div_fixup_f32 v106, v93, v106, 1.0
	v_pk_mul_f32 v[40:41], v[40:41], v[106:107]
	s_nop 0
	v_cvt_pk_bf16_f32 v43, v40, v41
	global_store_dwordx2 v[102:103], v[42:43], off
	global_load_dwordx2 v[40:41], v[104:105], off offset:64
	global_load_dwordx4 v[112:115], v[88:89], off offset:128
	v_pk_mul_f32 v[102:103], v[110:111], v[100:101] op_sel_hi:[1,0]
	s_waitcnt vmcnt(0) lgkmcnt(0)
	v_lshlrev_b32_e32 v93, 16, v40
	v_and_b32_e32 v40, 0xffff0000, v40
	v_mul_f32_e32 v42, 0xbfb8aa3b, v93
	v_mul_f32_e32 v43, 0xbfb8aa3b, v40
	v_exp_f32_e32 v42, v42
	v_exp_f32_e32 v43, v43
	v_pk_mul_f32 v[102:103], v[102:103], v[112:113]
	v_pk_add_f32 v[42:43], v[42:43], 1.0 op_sel_hi:[1,0]
	s_nop 0
	v_rcp_f32_e32 v101, v43
	s_nop 0
	v_fma_f32 v106, -v43, v101, 1.0
	v_fmac_f32_e32 v101, v106, v101
	v_mul_f32_e32 v107, v40, v101
	v_fma_f32 v110, -v43, v107, v40
	v_fmac_f32_e32 v107, v110, v101
	v_fma_f32 v95, -v43, v107, v40
	v_fma_f32 v95, v95, v101, v107
	v_div_fixup_f32 v43, v95, v43, v40
	v_rcp_f32_e32 v95, v42
	s_nop 0
	v_fma_f32 v101, -v42, v95, 1.0
	v_fmac_f32_e32 v95, v101, v95
	v_mul_f32_e32 v106, v93, v95
	v_fma_f32 v107, -v42, v106, v93
	v_fmac_f32_e32 v106, v107, v95
	v_fma_f32 v40, -v42, v106, v93
	v_fma_f32 v40, v40, v95, v106
	v_div_fixup_f32 v42, v40, v42, v93
	v_lshlrev_b32_e32 v93, 16, v41
	v_and_b32_e32 v95, 0xffff0000, v41
	v_mul_f32_e32 v40, 0xbfb8aa3b, v93
	v_mul_f32_e32 v41, 0xbfb8aa3b, v95
	v_exp_f32_e32 v40, v40
	v_exp_f32_e32 v41, v41
	v_pk_mul_f32 v[42:43], v[102:103], v[42:43]
	v_pk_mul_f32 v[102:103], v[108:109], v[100:101] op_sel_hi:[1,0]
	v_pk_add_f32 v[40:41], v[40:41], 1.0 op_sel_hi:[1,0]
	s_nop 0
	v_rcp_f32_e32 v106, v41
	v_pk_mul_f32 v[102:103], v[102:103], v[114:115]
	v_fma_f32 v107, -v41, v106, 1.0
	v_fmac_f32_e32 v106, v107, v106
	v_mul_f32_e32 v108, v95, v106
	v_fma_f32 v109, -v41, v108, v95
	v_fmac_f32_e32 v108, v109, v106
	v_fma_f32 v101, -v41, v108, v95
	v_fma_f32 v101, v101, v106, v108
	v_div_fixup_f32 v41, v101, v41, v95
	v_rcp_f32_e32 v101, v40
	s_nop 0
	v_fma_f32 v106, -v40, v101, 1.0
	v_fmac_f32_e32 v101, v106, v101
	v_mul_f32_e32 v107, v93, v101
	v_fma_f32 v108, -v40, v107, v93
	v_fmac_f32_e32 v107, v108, v101
	v_fma_f32 v95, -v40, v107, v93
	v_fma_f32 v95, v95, v101, v107
	v_div_fixup_f32 v40, v95, v40, v93
	v_pk_mul_f32 v[40:41], v[102:103], v[40:41]
	global_load_dwordx2 v[102:103], v[74:75], off offset:64
	s_waitcnt vmcnt(0) lgkmcnt(0)
; DI size_t kblk(int row, int col, int nrows) { return ((size_t)(col >> 5) * nrows + row) * 32 + (col & 31); }
; DI unsigned pk2(float a, float b) { hwf32x2 f = {a, b}; hwbf16x2 r = __builtin_convertvector(f, hwbf16x2); return __builtin_bit_cast(unsigned, r); }
; DI float sigmoidf_(float z) { return 1.f / (1.f + __expf(-z)); }
; DI float siluf_(float z) { return z / (1.f + __expf(-z)); }
; template <int MX, bool OUT>
; DI void rec_chunk(const Params& p, int l, int b, int h, int dir, int T0, unsigned char* smem, f32x4 (&St)[4], float& nst, float& dtot, int tid, const RecRaw& raw) {
;     ...
;       for (int a = 0; a < 4; ++a) {
;         const int v0 = 16 * a + 4 * g;
;         const uint2 gt = *(const uint2*)(prow + GATE + cb + v0);
;         const float4 gg = *(const float4*)(gvec + v0);
;         float y0 = O[a][0] * rstd * gg.x * siluf_(__uint_as_float(gt.x << 16));
;         float y1 = O[a][1] * rstd * gg.y * siluf_(__uint_as_float(gt.x & 0xffff0000u));
;         float y2 = O[a][2] * rstd * gg.z * siluf_(__uint_as_float(gt.y << 16));
;         float y3 = O[a][3] * rstd * gg.w * siluf_(__uint_as_float(gt.y & 0xffff0000u));
;         if (MX == 1) {
;           const uint2 og = *(const uint2*)(prow + D_OG + h * 64 + v0);
;           y0 *= sigmoidf_(__uint_as_float(og.x << 16)); y1 *= sigmoidf_(__uint_as_float(og.x & 0xffff0000u));
;           y2 *= sigmoidf_(__uint_as_float(og.y << 16)); y3 *= sigmoidf_(__uint_as_float(og.y & 0xffff0000u));
;         }
;         *(uint2*)(MIX + kblk((int)orow, cb + v0, ROWS)) = make_uint2(pk2(y0, y1), pk2(y2, y3));
	v_lshlrev_b32_e32 v93, 16, v102
	v_mul_f32_e32 v93, 0xbfb8aa3b, v93
	v_exp_f32_e32 v106, v93
	v_and_b32_e32 v93, 0xffff0000, v102
	v_mul_f32_e32 v93, 0xbfb8aa3b, v93
	v_exp_f32_e32 v107, v93
	s_nop 0
	v_pk_add_f32 v[106:107], v[106:107], 1.0 op_sel_hi:[1,0]
	s_nop 0
	v_rcp_f32_e32 v95, v107
	s_nop 0
	v_fma_f32 v101, -v107, v95, 1.0
	v_fmac_f32_e32 v95, v101, v95
	v_mov_b32_e64 v101, 1.0
	v_mul_f32_e32 v102, v101, v95
	v_fma_f32 v108, -v107, v102, v101
	v_fmac_f32_e32 v102, v108, v95
	v_fma_f32 v93, -v107, v102, v101
	v_fma_f32 v93, v93, v95, v102
	v_div_fixup_f32 v107, v93, v107, 1.0
	v_rcp_f32_e32 v95, v106
	s_nop 0
	v_fma_f32 v101, -v106, v95, 1.0
	v_fmac_f32_e32 v95, v101, v95
	v_mov_b32_e64 v101, 1.0
	v_mul_f32_e32 v102, v101, v95
	v_fma_f32 v108, -v106, v102, v101
	v_fmac_f32_e32 v102, v108, v95
	v_fma_f32 v93, -v106, v102, v101
	v_fma_f32 v93, v93, v95, v102
	v_div_fixup_f32 v106, v93, v106, 1.0
	v_lshlrev_b32_e32 v93, 16, v103
	v_mul_f32_e32 v93, 0xbfb8aa3b, v93
	v_exp_f32_e32 v102, v93
	v_and_b32_e32 v93, 0xffff0000, v103
	v_mul_f32_e32 v93, 0xbfb8aa3b, v93
	v_exp_f32_e32 v103, v93
	v_pk_mul_f32 v[42:43], v[42:43], v[106:107]
	v_pk_add_f32 v[102:103], v[102:103], 1.0 op_sel_hi:[1,0]
	s_nop 0
	v_rcp_f32_e32 v95, v103
	v_cvt_pk_bf16_f32 v42, v42, v43
	v_fma_f32 v101, -v103, v95, 1.0
	v_fmac_f32_e32 v95, v101, v95
	v_mov_b32_e64 v101, 1.0
	v_mul_f32_e32 v106, v101, v95
	v_fma_f32 v107, -v103, v106, v101
	v_fmac_f32_e32 v106, v107, v95
	v_fma_f32 v93, -v103, v106, v101
	v_fma_f32 v93, v93, v95, v106
	v_div_fixup_f32 v103, v93, v103, 1.0
	v_rcp_f32_e32 v95, v102
	s_nop 0
	v_fma_f32 v101, -v102, v95, 1.0
	v_fmac_f32_e32 v95, v101, v95
	v_mov_b32_e64 v101, 1.0
	v_mul_f32_e32 v106, v101, v95
	v_fma_f32 v107, -v102, v106, v101
	v_fmac_f32_e32 v106, v107, v95
	v_fma_f32 v93, -v102, v106, v101
	v_fma_f32 v93, v93, v95, v106
	v_div_fixup_f32 v102, v93, v102, 1.0
	v_pk_mul_f32 v[40:41], v[40:41], v[102:103]
	s_nop 0
	v_cvt_pk_bf16_f32 v43, v40, v41
	global_store_dwordx2 v[72:73], v[42:43], off
	global_load_dwordx2 v[40:41], v[104:105], off offset:96
	s_nop 0
	global_load_dwordx2 v[74:75], v[74:75], off offset:96
	s_waitcnt vmcnt(0) lgkmcnt(0)
	v_lshlrev_b32_e32 v73, 16, v40
	v_and_b32_e32 v93, 0xffff0000, v40
	v_lshlrev_b32_e32 v40, 16, v41
	v_mul_f32_e32 v42, 0xbfb8aa3b, v40
	v_exp_f32_e32 v42, v42
	s_nop 0
	v_add_f32_e32 v42, 1.0, v42
	v_rcp_f32_e32 v72, v42
	s_nop 0
	v_fma_f32 v95, -v42, v72, 1.0
	v_fmac_f32_e32 v72, v95, v72
	v_mul_f32_e32 v101, v40, v72
	v_fma_f32 v102, -v42, v101, v40
	v_fmac_f32_e32 v101, v102, v72
	v_fma_f32 v43, -v42, v101, v40
	v_fma_f32 v43, v43, v72, v101
	v_and_b32_e32 v95, 0xffff0000, v41
	v_div_fixup_f32 v72, v43, v42, v40
	v_mul_f32_e32 v40, 0xbfb8aa3b, v95
	v_exp_f32_e32 v102, v40
	v_lshlrev_b32_e32 v40, 16, v74
	v_mul_f32_e32 v40, 0xbfb8aa3b, v40
	v_exp_f32_e32 v104, v40
	v_and_b32_e32 v40, 0xffff0000, v74
	v_mul_f32_e32 v40, 0xbfb8aa3b, v40
	v_exp_f32_e32 v105, v40
	global_load_dwordx4 v[40:43], v[88:89], off offset:192
	v_pk_mul_f32 v[70:71], v[70:71], v[100:101] op_sel_hi:[1,0]
	v_mul_f32_e32 v74, 0xbfb8aa3b, v73
	v_exp_f32_e32 v106, v74
	s_waitcnt vmcnt(0)
	v_pk_mul_f32 v[40:41], v[70:71], v[40:41]
	v_mul_f32_e32 v70, 0xbfb8aa3b, v93
	v_exp_f32_e32 v107, v70
	s_nop 0
	v_pk_add_f32 v[70:71], v[106:107], 1.0 op_sel_hi:[1,0]
	s_nop 0
	v_rcp_f32_e32 v101, v71
	s_nop 0
	v_fma_f32 v103, -v71, v101, 1.0
	v_fmac_f32_e32 v101, v103, v101
	v_mul_f32_e32 v106, v93, v101
	v_fma_f32 v107, -v71, v106, v93
	v_fmac_f32_e32 v106, v107, v101
	v_fma_f32 v74, -v71, v106, v93
	v_fma_f32 v74, v74, v101, v106
	v_div_fixup_f32 v71, v74, v71, v93
	v_rcp_f32_e32 v93, v70
	s_nop 0
	v_fma_f32 v101, -v70, v93, 1.0
	v_fmac_f32_e32 v93, v101, v93
	v_mul_f32_e32 v103, v73, v93
	v_fma_f32 v106, -v70, v103, v73
	v_fmac_f32_e32 v103, v106, v93
	v_fma_f32 v74, -v70, v103, v73
	v_fma_f32 v74, v74, v93, v103
	v_div_fixup_f32 v70, v74, v70, v73
	v_pk_mul_f32 v[40:41], v[40:41], v[70:71]
	v_pk_add_f32 v[70:71], v[104:105], 1.0 op_sel_hi:[1,0]
	s_nop 0
	v_rcp_f32_e32 v74, v71
	s_nop 0
	v_fma_f32 v93, -v71, v74, 1.0
	v_fmac_f32_e32 v74, v93, v74
	v_mov_b32_e64 v93, 1.0
	v_mul_f32_e32 v101, v93, v74
	v_fma_f32 v103, -v71, v101, v93
	v_fmac_f32_e32 v101, v103, v74
	v_fma_f32 v73, -v71, v101, v93
	v_fma_f32 v73, v73, v74, v101
	v_div_fixup_f32 v71, v73, v71, 1.0
	v_rcp_f32_e32 v74, v70
	s_nop 0
	v_fma_f32 v93, -v70, v74, 1.0
	v_fmac_f32_e32 v74, v93, v74
	v_mov_b32_e64 v93, 1.0
	v_mul_f32_e32 v101, v93, v74
	v_fma_f32 v103, -v70, v101, v93
	v_fmac_f32_e32 v101, v103, v74
	v_fma_f32 v73, -v70, v101, v93
	v_fma_f32 v73, v73, v74, v101
	v_div_fixup_f32 v70, v73, v70, 1.0
	v_pk_mul_f32 v[40:41], v[40:41], v[70:71]
	v_lshlrev_b32_e32 v70, 16, v75
	v_mul_f32_e32 v70, 0xbfb8aa3b, v70
	v_exp_f32_e32 v70, v70
	v_cvt_pk_bf16_f32 v40, v40, v41
	v_add_f32_e32 v70, 1.0, v70
	v_rcp_f32_e32 v73, v70
	s_nop 0
	v_fma_f32 v74, -v70, v73, 1.0
	v_fmac_f32_e32 v73, v74, v73
	v_mov_b32_e64 v74, 1.0
	v_mul_f32_e32 v93, v74, v73
	v_fma_f32 v101, -v70, v93, v74
	v_fmac_f32_e32 v93, v101, v73
	v_fma_f32 v71, -v70, v93, v74
	v_fma_f32 v71, v71, v73, v93
	v_div_fixup_f32 v70, v71, v70, 1.0
	v_and_b32_e32 v71, 0xffff0000, v75
	v_mul_f32_e32 v71, 0xbfb8aa3b, v71
	v_exp_f32_e32 v103, v71
	s_nop 0
	v_pk_add_f32 v[74:75], v[102:103], 1.0 op_sel_hi:[1,0]
	s_nop 0
	v_rcp_f32_e32 v73, v75
	s_nop 0
	v_fma_f32 v93, -v75, v73, 1.0
	v_fmac_f32_e32 v73, v93, v73
	v_mov_b32_e64 v93, 1.0
	v_mul_f32_e32 v101, v93, v73
	v_fma_f32 v102, -v75, v101, v93
	v_fmac_f32_e32 v101, v102, v73
	v_fma_f32 v71, -v75, v101, v93
	v_fma_f32 v71, v71, v73, v101
	v_div_fixup_f32 v71, v71, v75, 1.0
	v_rcp_f32_e32 v75, v74
	s_mov_b64 s[0:1], 0
	v_fma_f32 v93, -v74, v75, 1.0
	v_fmac_f32_e32 v75, v93, v75
	v_mul_f32_e32 v101, v95, v75
	v_fma_f32 v102, -v74, v101, v95
	v_fmac_f32_e32 v101, v102, v75
	v_fma_f32 v73, -v74, v101, v95
	v_fma_f32 v73, v73, v75, v101
	v_pk_mul_f32 v[68:69], v[68:69], v[100:101] op_sel_hi:[1,0]
	v_div_fixup_f32 v73, v73, v74, v95
	v_pk_mul_f32 v[42:43], v[68:69], v[42:43]
	v_mov_b32_e32 v95, v161
	v_pk_mul_f32 v[42:43], v[42:43], v[72:73]
	v_lshl_add_u64 v[66:67], v[66:67], 0, v[94:95]
	v_pk_mul_f32 v[42:43], v[42:43], v[70:71]
	global_store_dword v[66:67], v40, off

; DI float sigmoidf_(float z) { return 1.f / (1.f + __expf(-z)); }
; DI void rec_setup_lb(const Params& p, int l, int h, unsigned char* smem, int tid) {
;   float* LB = (float*)(smem + L_LB);
;   __syncthreads();
;   if (tid < 64) LB[tid] = (l == 1) ? sigmoidf_(p.hg_lb[256 + h * 64 + tid] - p.hg_lb[h * 64 + tid]) : 0.f;
;   __syncthreads();
; }
.LBB0_939:
	s_and_b64 vcc, exec, s[0:1]
	s_cbranch_vccz .LBB0_803
	v_readlane_b32 s0, v253, 39
	v_mbcnt_lo_u32_b32 v2, -1, 0
	v_mbcnt_hi_u32_b32 v2, -1, v2
	s_waitcnt lgkmcnt(0)
	s_barrier
	v_or_b32_e32 v0, s0, v2
	v_cmp_gt_i32_e32 vcc, 64, v0
	s_and_saveexec_b64 s[0:1], vcc
	s_cbranch_execz .LBB0_944
	v_readlane_b32 s4, v254, 19
	v_readlane_b32 s5, v254, 20
	v_mov_b32_e32 v1, 0
	s_andn2_b64 vcc, exec, s[4:5]
	s_cbranch_vccnz .LBB0_943
	s_lshl_b32 s2, s48, 6
	v_ashrrev_i32_e32 v1, 31, v0
	v_readlane_b32 s52, v253, 23
	v_lshl_add_u64 v[4:5], s[2:3], 0, v[0:1]
	v_readlane_b32 s58, v253, 29
	v_readlane_b32 s59, v253, 30
	v_readlane_b32 s53, v253, 24
	v_readlane_b32 s54, v253, 25
	v_lshl_add_u64 v[4:5], v[4:5], 2, s[58:59]
	global_load_dword v1, v[4:5], off offset:1024
	v_add_u32_e32 v4, s2, v0
	v_ashrrev_i32_e32 v5, 31, v4
	v_lshl_add_u64 v[4:5], v[4:5], 2, s[58:59]
	global_load_dword v3, v[4:5], off
	v_readlane_b32 s55, v253, 26
	v_readlane_b32 s56, v253, 27
	v_readlane_b32 s57, v253, 28
	v_readlane_b32 s60, v253, 31
	v_readlane_b32 s61, v253, 32
	v_readlane_b32 s62, v253, 33
	v_readlane_b32 s63, v253, 34
	v_readlane_b32 s64, v253, 35
	v_readlane_b32 s65, v253, 36
	v_readlane_b32 s66, v253, 37
	v_readlane_b32 s67, v253, 38
	s_waitcnt vmcnt(0)
	v_sub_f32_e32 v1, v1, v3
	v_mul_f32_e32 v1, 0xbfb8aa3b, v1
	v_exp_f32_e32 v1, v1
	s_nop 0
	v_add_f32_e32 v1, 1.0, v1
	v_rcp_f32_e32 v4, v1
	s_nop 0
	v_fma_f32 v5, -v1, v4, 1.0
	v_fmac_f32_e32 v4, v5, v4
	v_mov_b32_e64 v5, 1.0
	v_mul_f32_e32 v6, v5, v4
	v_fma_f32 v7, -v1, v6, v5
	v_fmac_f32_e32 v6, v7, v4
	v_fma_f32 v3, -v1, v6, v5
	v_fma_f32 v3, v3, v4, v6
	v_div_fixup_f32 v1, v3, v1, 1.0

; template <int MX>
; DI RecRaw rec_load(const Params& p, int b, int h, int dir, int T0, int tid) {
;     ...
;   if (MX == 0) {
;     const int fcol = (dir ? B_FB : B_FF) + h * 64 + k0;
;     w.a0 = *(const uint4*)(rp + fcol); w.a1 = *(const uint4*)(rp + fcol + 8);
;     w.b0 = *(const uint4*)(rp + B_Q + h * 64 + k0); w.b1 = *(const uint4*)(rp + B_Q + h * 64 + k0 + 8);
;     w.c0 = *(const uint4*)(rp + B_I + h * 64 + k0); w.c1 = *(const uint4*)(rp + B_I + h * 64 + k0 + 8);
; template <int MX, bool OUT>
; DI void rec_chunk(const Params& p, int l, int b, int h, int dir, int T0, unsigned char* smem, f32x4 (&St)[4], float& nst, float& dtot, int tid, const RecRaw& raw) {
;     ...
;     if (MX == 0) {
; #pragma unroll
;       for (int i = 0; i < 8; ++i) {
; #pragma unroll
;         for (int hh = 0; hh < 2; ++hh) {
;           const int k = 2 * i + hh;
;           float z = __uint_as_float(hh ? (au[i] & 0xffff0000u) : (au[i] << 16));
;           z = fminf(fmaxf(z, -30.f), 30.f);
;           const float e = __expf(-z);
;           const float sg = 1.f / (1.f + e);
;           const float lb = LB[k0 + k];
;           lf[k] = __log2f(lb + (1.f - lb) * sg);
;           kin[k] = (1.f - lb) * (e * sg);
;           qv[k] = __uint_as_float(hh ? (bu[i] & 0xffff0000u) : (bu[i] << 16)) * 0.125f;
;           vv[k] = __uint_as_float(hh ? (cu[i] & 0xffff0000u) : (cu[i] << 16));
;         }
;       }
.LBB0_950:
	v_add_co_u32_e64 v95, s[26:27], s84, 1
	s_and_b64 s[26:27], s[26:27], exec
	s_cselect_b32 s34, 3, s83
	s_cselect_b32 s35, 0, s84
	s_and_b64 s[26:27], s[8:9], exec
	s_cselect_b32 s26, s34, s35
	s_lshl_b32 s26, s26, 6
	s_add_i32 s26, s26, s80
	s_ashr_i32 s27, s26, 31
	v_lshl_add_u64 v[16:17], v[82:83], 0, s[26:27]
	v_mov_b64_e32 v[18:19], s[4:5]
	v_mad_u64_u32 v[24:25], s[26:27], v16, s33, v[18:19]
	s_waitcnt vmcnt(0) lgkmcnt(0)
	v_lshlrev_b32_e32 v18, 16, v60
	v_max_f32_e32 v18, v18, v18
	v_med3_f32 v18, v18, s17, v190
	v_mul_f32_e32 v18, 0xbfb8aa3b, v18
	v_exp_f32_e32 v207, v18
	v_and_b32_e32 v60, 0xffff0000, v60
	v_max_f32_e32 v60, v60, v60
	v_med3_f32 v60, v60, s17, v190
	v_add_f32_e32 v64, 1.0, v207
	v_mul_f32_e32 v60, 0xbfb8aa3b, v60
	v_exp_f32_e32 v210, v60
	v_rcp_f32_e32 v66, v64
	v_mad_i32_i24 v25, v17, s33, v25
	v_lshl_add_u64 v[16:17], v[24:25], 0, v[160:161]
	v_add_f32_e32 v60, 1.0, v210
	v_fma_f32 v67, -v64, v66, 1.0
	v_fmac_f32_e32 v66, v67, v66
	v_mov_b32_e64 v67, 1.0
	v_rcp_f32_e32 v104, v60
	v_mul_f32_e32 v68, v67, v66
	v_fma_f32 v69, -v64, v68, v67
	v_fmac_f32_e32 v68, v69, v66
	v_fma_f32 v65, -v64, v68, v67
	v_fma_f32 v105, -v60, v104, 1.0
	v_fma_f32 v65, v65, v66, v68
	v_fmac_f32_e32 v104, v105, v104
	v_mov_b32_e64 v105, 1.0
	v_mul_f32_e32 v106, v105, v104
	v_fma_f32 v107, -v60, v106, v105
	v_fmac_f32_e32 v106, v107, v104
	v_fma_f32 v97, -v60, v106, v105
	v_lshlrev_b32_e32 v105, 16, v61
	v_max_f32_e32 v105, v105, v105
	v_med3_f32 v105, v105, s17, v190
	v_mul_f32_e32 v105, 0xbfb8aa3b, v105
	v_exp_f32_e32 v206, v105
	v_fma_f32 v97, v97, v104, v106
	v_div_fixup_f32 v213, v97, v60, 1.0
	v_and_b32_e32 v61, 0xffff0000, v61
	v_add_f32_e32 v60, 1.0, v206
	v_rcp_f32_e32 v104, v60
	v_max_f32_e32 v61, v61, v61
	v_med3_f32 v61, v61, s17, v190
	v_mul_f32_e32 v61, 0xbfb8aa3b, v61
	v_fma_f32 v105, -v60, v104, 1.0
	v_fmac_f32_e32 v104, v105, v104
	v_mov_b32_e64 v105, 1.0
	v_mul_f32_e32 v106, v105, v104
	v_fma_f32 v107, -v60, v106, v105
	v_exp_f32_e32 v203, v61
	v_fmac_f32_e32 v106, v107, v104
	v_fma_f32 v97, -v60, v106, v105
	v_fma_f32 v61, v97, v104, v106
	v_div_fixup_f32 v208, v61, v60, 1.0
	v_add_f32_e32 v60, 1.0, v203
	v_rcp_f32_e32 v97, v60
	v_lshl_add_u64 v[24:25], v[24:25], 0, s[20:21]
	v_lshl_add_u64 v[24:25], v[24:25], 0, v[98:99]
	global_load_dwordx4 v[20:23], v[16:17], off
	s_nop 0
	global_load_dwordx4 v[16:19], v[16:17], off offset:16
	v_fma_f32 v104, -v60, v97, 1.0
	v_fmac_f32_e32 v97, v104, v97
	v_mov_b32_e64 v104, 1.0
	v_mul_f32_e32 v105, v104, v97
	v_fma_f32 v106, -v60, v105, v104
	v_fmac_f32_e32 v105, v106, v97
	v_fma_f32 v61, -v60, v105, v104
	v_lshlrev_b32_e32 v104, 16, v62
	v_max_f32_e32 v104, v104, v104
	v_med3_f32 v104, v104, s17, v190
	v_mul_f32_e32 v104, 0xbfb8aa3b, v104
	v_exp_f32_e32 v200, v104
	v_fma_f32 v61, v61, v97, v105
	v_div_fixup_f32 v204, v61, v60, 1.0
	v_and_b32_e32 v62, 0xffff0000, v62
	v_add_f32_e32 v60, 1.0, v200
	v_rcp_f32_e32 v97, v60
	v_max_f32_e32 v62, v62, v62
	v_med3_f32 v62, v62, s17, v190
	v_mul_f32_e32 v62, 0xbfb8aa3b, v62
	v_fma_f32 v104, -v60, v97, 1.0
	v_fmac_f32_e32 v97, v104, v97
	v_mov_b32_e64 v104, 1.0
	v_mul_f32_e32 v105, v104, v97
	v_fma_f32 v106, -v60, v105, v104
	v_exp_f32_e32 v119, v62
	v_fmac_f32_e32 v105, v106, v97
	v_fma_f32 v61, -v60, v105, v104
	v_fma_f32 v61, v61, v97, v105
	v_div_fixup_f32 v201, v61, v60, 1.0
	v_add_f32_e32 v61, 1.0, v119
	global_load_dwordx4 v[36:39], v[24:25], off offset:1536
	global_load_dwordx4 v[32:35], v[24:25], off offset:1552
	global_load_dwordx4 v[28:31], v[24:25], off offset:3072
	s_nop 0
	global_load_dwordx4 v[24:27], v[24:25], off offset:3088
	v_div_fixup_f32 v211, v65, v64, 1.0
	ds_read_b128 v[68:71], v81
	ds_read_b128 v[100:103], v81 offset:16
	ds_read_b128 v[72:75], v81 offset:32
	ds_read_b128 v[64:67], v81 offset:48
	v_rcp_f32_e32 v97, v61
	s_waitcnt lgkmcnt(0)
	v_sub_f32_e32 v212, 1.0, v68
	v_sub_f32_e32 v202, 1.0, v100
	v_fma_f32 v60, v201, v202, v100
	v_fma_f32 v100, -v61, v97, 1.0
	v_fmac_f32_e32 v97, v100, v97
	v_mov_b32_e64 v100, 1.0
	v_mul_f32_e32 v104, v100, v97
	v_fma_f32 v105, -v61, v104, v100
	v_fmac_f32_e32 v104, v105, v97
	v_fma_f32 v62, -v61, v104, v100
	v_lshlrev_b32_e32 v100, 16, v63
	v_max_f32_e32 v100, v100, v100
	v_med3_f32 v100, v100, s17, v190
	v_mul_f32_e32 v100, 0xbfb8aa3b, v100
	v_exp_f32_e32 v116, v100
	v_fma_f32 v62, v62, v97, v104
	v_div_fixup_f32 v120, v62, v61, 1.0
	v_sub_f32_e32 v121, 1.0, v101
	v_add_f32_e32 v62, 1.0, v116
	v_rcp_f32_e32 v100, v62
	v_and_b32_e32 v63, 0xffff0000, v63
	v_fma_f32 v61, v120, v121, v101
	v_max_f32_e32 v63, v63, v63
	v_fma_f32 v101, -v62, v100, 1.0
	v_fmac_f32_e32 v100, v101, v100
	v_mov_b32_e64 v101, 1.0
	v_med3_f32 v63, v63, s17, v190
	v_mul_f32_e32 v104, v101, v100
	v_mul_f32_e32 v63, 0xbfb8aa3b, v63
	v_fma_f32 v105, -v62, v104, v101
	v_exp_f32_e32 v113, v63
	v_fmac_f32_e32 v104, v105, v100
	v_fma_f32 v97, -v62, v104, v101
	v_fma_f32 v63, v97, v100, v104
	v_div_fixup_f32 v117, v63, v62, 1.0
	v_add_f32_e32 v63, 1.0, v113
	v_rcp_f32_e32 v100, v63
	v_sub_f32_e32 v118, 1.0, v102
	v_fma_f32 v62, v117, v118, v102
	v_sub_f32_e32 v115, 1.0, v103
	v_fma_f32 v101, -v63, v100, 1.0
	v_fmac_f32_e32 v100, v101, v100
	v_mov_b32_e64 v101, 1.0
	v_mul_f32_e32 v102, v101, v100
	v_fma_f32 v104, -v63, v102, v101
	v_fmac_f32_e32 v102, v104, v100
	v_fma_f32 v97, -v63, v102, v101
	v_lshlrev_b32_e32 v101, 16, v56
	v_max_f32_e32 v101, v101, v101
	v_med3_f32 v101, v101, s17, v190
	v_mul_f32_e32 v101, 0xbfb8aa3b, v101
	v_exp_f32_e32 v110, v101
	v_fma_f32 v97, v97, v100, v102
	v_div_fixup_f32 v114, v97, v63, 1.0
	v_and_b32_e32 v56, 0xffff0000, v56
	v_add_f32_e32 v97, 1.0, v110
	v_rcp_f32_e32 v101, v97
; template <int MX, bool OUT>
; DI void rec_chunk(const Params& p, int l, int b, int h, int dir, int T0, unsigned char* smem, f32x4 (&St)[4], float& nst, float& dtot, int tid, const RecRaw& raw) {
;     ...
;     if (MX == 0) {
; #pragma unroll
;       for (int i = 0; i < 8; ++i) {
; #pragma unroll
;         for (int hh = 0; hh < 2; ++hh) {
;           const int k = 2 * i + hh;
;           float z = __uint_as_float(hh ? (au[i] & 0xffff0000u) : (au[i] << 16));
;           z = fminf(fmaxf(z, -30.f), 30.f);
;           const float e = __expf(-z);
;           const float sg = 1.f / (1.f + e);
;           const float lb = LB[k0 + k];
;           lf[k] = __log2f(lb + (1.f - lb) * sg);
;           kin[k] = (1.f - lb) * (e * sg);
;           qv[k] = __uint_as_float(hh ? (bu[i] & 0xffff0000u) : (bu[i] << 16)) * 0.125f;
;           vv[k] = __uint_as_float(hh ? (cu[i] & 0xffff0000u) : (cu[i] << 16));
;         }
;       }
;     ...
;     const int k = tid & 63, part = tid >> 6;
;     float x[16];
;     float acc = 0.f;
;     if (dir == 0) {
; #pragma unroll
;       for (int i = 0; i < 16; ++i) { acc += CUM[(part * 16 + i) * 64 + k]; x[i] = acc; }
;     } else {
; #pragma unroll
;       for (int i = 15; i >= 0; --i) { acc += CUM[(part * 16 + i) * 64 + k]; x[i] = acc; }
;     }
	v_max_f32_e32 v56, v56, v56
	v_fmac_f32_e32 v103, v114, v115
	v_med3_f32 v56, v56, s17, v190
	v_fma_f32 v102, -v97, v101, 1.0
	v_fmac_f32_e32 v101, v102, v101
	v_mov_b32_e64 v102, 1.0
	v_log_f32_e32 v63, v103
	v_mul_f32_e32 v103, v102, v101
	v_mul_f32_e32 v56, 0xbfb8aa3b, v56
	v_fma_f32 v104, -v97, v103, v102
	v_exp_f32_e32 v107, v56
	v_fmac_f32_e32 v103, v104, v101
	v_fma_f32 v100, -v97, v103, v102
	v_fma_f32 v56, v100, v101, v103
	v_div_fixup_f32 v111, v56, v97, 1.0
	v_add_f32_e32 v56, 1.0, v107
	v_rcp_f32_e32 v100, v56
	v_sub_f32_e32 v112, 1.0, v72
	v_fma_f32 v72, v111, v112, v72
	v_log_f32_e32 v216, v72
	v_fma_f32 v72, -v56, v100, 1.0
	v_fmac_f32_e32 v100, v72, v100
	v_mov_b32_e64 v72, 1.0
	v_mul_f32_e32 v101, v72, v100
	v_fma_f32 v102, -v56, v101, v72
	v_fmac_f32_e32 v101, v102, v100
	v_fma_f32 v72, -v56, v101, v72
	v_lshlrev_b32_e32 v97, 16, v57
	v_max_f32_e32 v97, v97, v97
	v_med3_f32 v97, v97, s17, v190
	v_mul_f32_e32 v97, 0xbfb8aa3b, v97
	v_exp_f32_e32 v104, v97
	v_fma_f32 v72, v72, v100, v101
	v_div_fixup_f32 v108, v72, v56, 1.0
	v_sub_f32_e32 v109, 1.0, v73
	v_add_f32_e32 v56, 1.0, v104
	v_rcp_f32_e32 v97, v56
	v_fma_f32 v73, v108, v109, v73
	v_log_f32_e32 v217, v73
	v_and_b32_e32 v57, 0xffff0000, v57
	v_fma_f32 v73, -v56, v97, 1.0
	v_fmac_f32_e32 v97, v73, v97
	v_mov_b32_e64 v73, 1.0
	v_max_f32_e32 v57, v57, v57
	v_mul_f32_e32 v100, v73, v97
	v_med3_f32 v57, v57, s17, v190
	v_fma_f32 v101, -v56, v100, v73
	v_mul_f32_e32 v57, 0xbfb8aa3b, v57
	v_fmac_f32_e32 v100, v101, v97
	v_exp_f32_e32 v101, v57
	v_fma_f32 v72, -v56, v100, v73
	v_fma_f32 v57, v72, v97, v100
	v_div_fixup_f32 v105, v57, v56, 1.0
	v_add_f32_e32 v56, 1.0, v101
	v_rcp_f32_e32 v72, v56
	v_sub_f32_e32 v106, 1.0, v74
	v_fma_f32 v73, v105, v106, v74
	v_log_f32_e32 v218, v73
	v_fma_f32 v73, -v56, v72, 1.0
	v_fmac_f32_e32 v72, v73, v72
	v_mov_b32_e64 v73, 1.0
	v_mul_f32_e32 v74, v73, v72
	v_fma_f32 v97, -v56, v74, v73
	v_fmac_f32_e32 v74, v97, v72
	v_fma_f32 v57, -v56, v74, v73
	v_lshlrev_b32_e32 v73, 16, v58
	v_max_f32_e32 v73, v73, v73
	v_med3_f32 v73, v73, s17, v190
	v_mul_f32_e32 v73, 0xbfb8aa3b, v73
	v_exp_f32_e32 v97, v73
	v_fma_f32 v57, v57, v72, v74
	v_div_fixup_f32 v102, v57, v56, 1.0
	v_sub_f32_e32 v103, 1.0, v75
	v_add_f32_e32 v56, 1.0, v97
	v_rcp_f32_e32 v73, v56
	v_and_b32_e32 v58, 0xffff0000, v58
	v_fmac_f32_e32 v75, v102, v103
	v_max_f32_e32 v58, v58, v58
	v_fma_f32 v72, -v56, v73, 1.0
	v_fmac_f32_e32 v73, v72, v73
	v_mov_b32_e64 v72, 1.0
	v_mul_f32_e32 v74, v72, v73
	v_log_f32_e32 v219, v75
	v_fma_f32 v75, -v56, v74, v72
	v_med3_f32 v58, v58, s17, v190
	v_fmac_f32_e32 v74, v75, v73
	v_mul_f32_e32 v58, 0xbfb8aa3b, v58
	v_fma_f32 v57, -v56, v74, v72
	v_exp_f32_e32 v72, v58
	v_fma_f32 v57, v57, v73, v74
	v_div_fixup_f32 v75, v57, v56, 1.0
	v_sub_f32_e32 v100, 1.0, v64
	v_add_f32_e32 v56, 1.0, v72
	v_rcp_f32_e32 v58, v56
	v_fma_f32 v64, v75, v100, v64
	v_log_f32_e32 v220, v64
	v_sub_f32_e32 v214, 1.0, v69
	v_fma_f32 v64, -v56, v58, 1.0
	v_fmac_f32_e32 v58, v64, v58
	v_mov_b32_e64 v64, 1.0
	v_mul_f32_e32 v73, v64, v58
	v_fma_f32 v74, -v56, v73, v64
	v_fmac_f32_e32 v73, v74, v58
	v_fma_f32 v57, -v56, v73, v64
	v_lshlrev_b32_e32 v64, 16, v59
	v_max_f32_e32 v64, v64, v64
	v_med3_f32 v64, v64, s17, v190
	v_mul_f32_e32 v64, 0xbfb8aa3b, v64
	v_exp_f32_e32 v64, v64
	v_fma_f32 v57, v57, v58, v73
	v_div_fixup_f32 v73, v57, v56, 1.0
	v_sub_f32_e32 v74, 1.0, v65
	v_add_f32_e32 v57, 1.0, v64
	v_rcp_f32_e32 v58, v57
	v_fma_f32 v65, v73, v74, v65
	v_log_f32_e32 v221, v65
	v_sub_f32_e32 v209, 1.0, v70
	v_fma_f32 v65, -v57, v58, 1.0
	v_fmac_f32_e32 v58, v65, v58
	v_mov_b32_e64 v65, 1.0
	v_mul_f32_e32 v215, v65, v58
	v_fma_f32 v222, -v57, v215, v65
	v_fmac_f32_e32 v215, v222, v58
	v_fma_f32 v65, -v57, v215, v65
	v_and_b32_e32 v56, 0xffff0000, v59
	v_max_f32_e32 v56, v56, v56
	v_med3_f32 v56, v56, s17, v190
	v_mul_f32_e32 v56, 0xbfb8aa3b, v56
	v_exp_f32_e32 v56, v56
	v_fma_f32 v58, v65, v58, v215
	v_div_fixup_f32 v59, v58, v57, 1.0
	v_sub_f32_e32 v65, 1.0, v66
	v_add_f32_e32 v57, 1.0, v56
	v_rcp_f32_e32 v215, v57
	v_fma_f32 v66, v59, v65, v66
	v_log_f32_e32 v222, v66
	v_sub_f32_e32 v205, 1.0, v71
	v_fma_f32 v66, -v57, v215, 1.0
	v_fmac_f32_e32 v215, v66, v215
	v_mov_b32_e64 v66, 1.0
	v_mul_f32_e32 v223, v66, v215
	v_fma_f32 v224, -v57, v223, v66
	v_fmac_f32_e32 v223, v224, v215
	v_fma_f32 v68, v211, v212, v68
	v_fma_f32 v69, v213, v214, v69
	v_fma_f32 v70, v208, v209, v70
	v_fmac_f32_e32 v71, v204, v205
	v_fma_f32 v58, -v57, v223, v66
	v_log_f32_e32 v68, v68
	v_log_f32_e32 v69, v69
	v_log_f32_e32 v70, v70
	v_log_f32_e32 v71, v71
	v_fma_f32 v58, v58, v215, v223
	v_log_f32_e32 v60, v60
	v_log_f32_e32 v61, v61
	v_log_f32_e32 v62, v62
	v_div_fixup_f32 v57, v58, v57, 1.0
	v_sub_f32_e32 v58, 1.0, v67
	v_fmac_f32_e32 v67, v57, v58
	v_log_f32_e32 v223, v67
	ds_write_b128 v122, v[68:71]
	ds_write_b128 v122, v[60:63] offset:16
	ds_write_b128 v122, v[216:219] offset:32
	ds_write_b128 v122, v[220:223] offset:48
	v_cndmask_b32_e64 v60, 0, 1, s[10:11]
	v_cmp_ne_u32_e64 s[78:79], 1, v60
	s_andn2_b64 vcc, exec, s[10:11]
	s_mov_b64 s[26:27], -1
	s_waitcnt lgkmcnt(0)
	s_barrier
	s_cbranch_vccnz .LBB0_952
	ds_read2st64_b32 v[60:61], v123 offset0:14 offset1:15
	s_mov_b64 s[26:27], 0
	ds_read2st64_b32 v[62:63], v123 offset0:8 offset1:9
	ds_read2st64_b32 v[216:217], v123 offset0:6 offset1:7
	ds_read2st64_b32 v[218:219], v123 offset0:2 offset1:3
	ds_read2st64_b32 v[220:221], v123 offset1:1
	s_waitcnt lgkmcnt(0)
	v_add_f32_e32 v70, 0, v61
	v_add_f32_e32 v71, v70, v60
	ds_read2st64_b32 v[60:61], v123 offset0:12 offset1:13
	s_waitcnt lgkmcnt(0)
	v_add_f32_e32 v66, v71, v61
	v_add_f32_e32 v67, v66, v60
	ds_read2st64_b32 v[60:61], v123 offset0:10 offset1:11
	s_waitcnt lgkmcnt(0)
	v_add_f32_e32 v68, v67, v61
	v_add_f32_e32 v69, v68, v60
	v_add_f32_e32 v60, v69, v63
	v_add_f32_e32 v61, v60, v62
	v_add_f32_e32 v62, v61, v217
	v_add_f32_e32 v63, v62, v216
	ds_read2st64_b32 v[216:217], v123 offset0:4 offset1:5
	s_waitcnt lgkmcnt(0)
	v_add_f32_e32 v215, v63, v217
	v_add_f32_e32 v216, v215, v216
	v_add_f32_e32 v217, v216, v219
	v_add_f32_e32 v218, v217, v218
	v_add_f32_e32 v219, v218, v221
	v_add_f32_e32 v220, v219, v220

; DI size_t kblk(int row, int col, int nrows) { return ((size_t)(col >> 5) * nrows + row) * 32 + (col & 31); }
; DI float siluf_(float z) { return z / (1.f + __expf(-z)); }
; #define MFMA16(a, b, c) __builtin_amdgcn_mfma_f32_16x16x32_bf16((a), (b), (c), 0, 0, 0)
; template <int MX, bool OUT>
; DI void rec_chunk(const Params& p, int l, int b, int h, int dir, int T0, unsigned char* smem, f32x4 (&St)[4], float& nst, float& dtot, int tid, const RecRaw& raw) {
;     ...
; #pragma unroll
;     for (int ks = 0; ks < 2; ++ks) {
;       const bf16x8 fb = *(const bf16x8*)(smem + L_QS + swz(t, ks * 4 + g));
; #pragma unroll
;       for (int a = 0; a < 4; ++a) {
;         const bf16x8 fa = *(const bf16x8*)(smem + L_STT + swz(16 * a + col, ks * 4 + g));
;         O[a] = MFMA16(fa, fb, O[a]);
;       }
;     }
;     ...
;     } else {
;       float ss = 0.f;
; #pragma unroll
;       for (int a = 0; a < 4; ++a) {
;         const uint2 u = *(const uint2*)(MIX + kblk((int)orow, cb + 16 * a + 4 * g, ROWS));
;         O[a][0] += __uint_as_float(u.x << 16); O[a][1] += __uint_as_float(u.x & 0xffff0000u);
;         O[a][2] += __uint_as_float(u.y << 16); O[a][3] += __uint_as_float(u.y & 0xffff0000u);
; #pragma unroll
;         for (int j = 0; j < 4; ++j) ss += O[a][j] * O[a][j];
;       }
;       ss += __shfl_xor(ss, 16);
;       ss += __shfl_xor(ss, 32);
;       const float rstd = rsqrtf(ss * (1.f / 64.f) + EPS);
;       const float* gvec = (MX ? p.ml_g : p.hg_g) + l * 64;
; #pragma unroll
;       for (int a = 0; a < 4; ++a) {
;         const int v0 = 16 * a + 4 * g;
;         const uint2 gt = *(const uint2*)(prow + GATE + cb + v0);
;         const float4 gg = *(const float4*)(gvec + v0);
;         float y0 = O[a][0] * rstd * gg.x * siluf_(__uint_as_float(gt.x << 16));
;         float y1 = O[a][1] * rstd * gg.y * siluf_(__uint_as_float(gt.x & 0xffff0000u));
;         float y2 = O[a][2] * rstd * gg.z * siluf_(__uint_as_float(gt.y << 16));
;         float y3 = O[a][3] * rstd * gg.w * siluf_(__uint_as_float(gt.y & 0xffff0000u));
.LBB0_1014:
	s_or_b64 exec, exec, s[26:27]
	s_add_i32 s26, s83, -1
	v_mov_b32_e32 v40, s26
	v_cndmask_b32_e64 v40, v95, v40, s[8:9]
	v_lshlrev_b32_e32 v40, 6, v40
	v_add_u32_e32 v40, s81, v40
	v_mov_b32_e32 v41, v161
	v_lshl_add_u64 v[68:69], v[40:41], 0, v[84:85]
	ds_read_b128 v[40:43], v203 offset:32768
	ds_read_b128 v[44:47], v201 offset:57344
	ds_read_b128 v[48:51], v201 offset:59392
	ds_read_b128 v[52:55], v201 offset:61440
	s_waitcnt lgkmcnt(0)
	v_mfma_f32_16x16x32_bf16 v[44:47], v[44:47], v[40:43], v[56:59]
	s_mov_b64 s[26:27], -1
	s_nop 1
	ds_read_b128 v[56:59], v201 offset:63488
	s_and_b64 vcc, exec, s[78:79]
	v_mfma_f32_16x16x32_bf16 v[48:51], v[48:51], v[40:43], v[60:63]
	v_ashrrev_i32_e32 v204, 31, v68
	v_mfma_f32_16x16x32_bf16 v[52:55], v[52:55], v[40:43], v[64:67]
	s_waitcnt lgkmcnt(0)
	v_mfma_f32_16x16x32_bf16 v[56:59], v[56:59], v[40:43], v[72:75]
	ds_read_b128 v[60:63], v202 offset:32768
	ds_read_b128 v[40:43], v200 offset:57344
	s_waitcnt lgkmcnt(0)
	v_mfma_f32_16x16x32_bf16 v[40:43], v[40:43], v[60:63], v[44:47]
	s_nop 2
	ds_read_b128 v[44:47], v200 offset:59392
	s_waitcnt lgkmcnt(0)
	v_mfma_f32_16x16x32_bf16 v[48:51], v[44:47], v[60:63], v[48:51]
	ds_read_b128 v[44:47], v200 offset:61440
	s_waitcnt lgkmcnt(0)
	v_mfma_f32_16x16x32_bf16 v[52:55], v[44:47], v[60:63], v[52:55]
	ds_read_b128 v[44:47], v200 offset:63488
	s_waitcnt lgkmcnt(0)
	v_mfma_f32_16x16x32_bf16 v[44:47], v[44:47], v[60:63], v[56:59]
	s_cbranch_vccnz .LBB0_1016
	s_nop 1
	v_mov_b64_e32 v[56:57], s[14:15]
	v_mad_u64_u32 v[56:57], s[26:27], v68, s33, v[56:57]
	v_mad_i32_i24 v57, v69, s33, v57
	v_mov_b32_e32 v69, v204
	v_lshl_add_u64 v[60:61], v[68:69], 0, s[30:31]
	v_lshlrev_b64 v[60:61], 6, v[60:61]
	v_lshl_add_u64 v[70:71], v[90:91], 0, v[60:61]
	global_load_dwordx2 v[60:61], v[70:71], off
	v_lshl_add_u64 v[58:59], v[68:69], 0, s[28:29]
	v_lshlrev_b64 v[58:59], 6, v[58:59]
	v_mov_b32_e32 v95, v161
	v_lshl_add_u64 v[100:101], v[86:87], 0, v[58:59]
	global_load_dwordx2 v[58:59], v[100:101], off
	s_mov_b64 s[26:27], 0x41c7a20
	v_lshl_add_u64 v[56:57], v[56:57], 0, s[26:27]
	v_lshl_add_u64 v[72:73], v[56:57], 0, s[2:3]
	v_lshl_add_u64 v[56:57], v[56:57], 0, v[94:95]
	v_lshl_add_u64 v[56:57], v[56:57], 0, s[2:3]
	v_cmp_lt_i32_e32 vcc, v183, v178
	v_lshl_add_u64 v[72:73], v[72:73], 0, v[94:95]
	global_load_dwordx2 v[56:57], v[56:57], off
	s_waitcnt vmcnt(0) lgkmcnt(0)
	v_lshlrev_b32_e32 v74, 16, v60
	v_and_b32_e32 v75, 0xffff0000, v60
	v_lshlrev_b32_e32 v102, 16, v61
	v_and_b32_e32 v103, 0xffff0000, v61
	v_lshl_add_u64 v[60:61], v[68:69], 0, s[42:43]
	v_lshlrev_b64 v[60:61], 6, v[60:61]
	v_lshl_add_u64 v[60:61], s[6:7], 0, v[60:61]
	v_lshl_add_u64 v[66:67], v[60:61], 0, v[94:95]
	global_load_dwordx2 v[62:63], v[66:67], off
	v_cndmask_b32_e32 v69, v177, v183, vcc
	v_cmp_lt_i32_e32 vcc, v184, v178
	v_lshlrev_b32_e32 v97, 2, v69
	v_lshlrev_b32_e32 v116, 16, v58
	v_cndmask_b32_e32 v69, v177, v184, vcc
	v_and_b32_e32 v117, 0xffff0000, v58
	v_lshlrev_b32_e32 v58, 16, v59
	v_and_b32_e32 v59, 0xffff0000, v59
	v_pk_add_f32 v[112:113], v[42:43], v[58:59]
	v_pk_add_f32 v[116:117], v[40:41], v[116:117]
	v_pk_mul_f32 v[114:115], v[112:113], v[112:113]
	v_pk_mul_f32 v[120:121], v[116:117], v[116:117]
	v_lshlrev_b32_e32 v69, 2, v69
	v_add_f32_e32 v95, v120, v121
	v_add_f32_e32 v95, v95, v114
	v_add_f32_e32 v95, v115, v95
	v_lshlrev_b32_e32 v205, 16, v56
	v_and_b32_e32 v206, 0xffff0000, v56
	v_lshlrev_b32_e32 v208, 16, v57
	v_and_b32_e32 v209, 0xffff0000, v57
	global_load_dwordx4 v[56:59], v[88:89], off
	v_mul_f32_e32 v118, 0xbfb8aa3b, v205
	v_mul_f32_e32 v119, 0xbfb8aa3b, v206
	v_exp_f32_e32 v118, v118
	v_exp_f32_e32 v119, v119
	s_waitcnt vmcnt(0) lgkmcnt(0)
	v_lshlrev_b32_e32 v108, 16, v62
	v_and_b32_e32 v109, 0xffff0000, v62
	v_lshlrev_b32_e32 v110, 16, v63
	v_and_b32_e32 v111, 0xffff0000, v63
	global_load_dwordx2 v[62:63], v[66:67], off offset:32
	v_pk_add_f32 v[118:119], v[118:119], 1.0 op_sel_hi:[1,0]
	v_pk_add_f32 v[108:109], v[52:53], v[108:109]
	v_rcp_f32_e32 v210, v119
	v_pk_mul_f32 v[214:215], v[108:109], v[108:109]
	v_fma_f32 v211, -v119, v210, 1.0
	v_fmac_f32_e32 v210, v211, v210
	v_mul_f32_e32 v212, v206, v210
	v_fma_f32 v213, -v119, v212, v206
	v_fmac_f32_e32 v212, v213, v210
	v_fma_f32 v207, -v119, v212, v206
	v_fma_f32 v207, v207, v210, v212
	v_div_fixup_f32 v119, v207, v119, v206
	v_rcp_f32_e32 v207, v118
	s_waitcnt vmcnt(0) lgkmcnt(0)
	v_lshlrev_b32_e32 v64, 16, v62
	v_fma_f32 v210, -v118, v207, 1.0
	v_fmac_f32_e32 v207, v210, v207
	v_mul_f32_e32 v211, v205, v207
	v_fma_f32 v212, -v118, v211, v205
	v_fmac_f32_e32 v211, v212, v207
	v_fma_f32 v206, -v118, v211, v205
	v_fma_f32 v206, v206, v207, v211
	v_div_fixup_f32 v118, v206, v118, v205
	v_mul_f32_e32 v205, 0xbfb8aa3b, v208
	v_exp_f32_e32 v206, v205
	v_mul_f32_e32 v205, 0xbfb8aa3b, v209
	v_exp_f32_e32 v207, v205
	v_and_b32_e32 v65, 0xffff0000, v62
	v_pk_add_f32 v[64:65], v[44:45], v[64:65]
	v_lshlrev_b32_e32 v62, 16, v63
	v_pk_add_f32 v[206:207], v[206:207], 1.0 op_sel_hi:[1,0]
	v_and_b32_e32 v63, 0xffff0000, v63
	v_rcp_f32_e32 v210, v207
	v_pk_mul_f32 v[104:105], v[64:65], v[64:65]
	v_pk_add_f32 v[62:63], v[46:47], v[62:63]
	v_fma_f32 v211, -v207, v210, 1.0
	v_fmac_f32_e32 v210, v211, v210
	v_mul_f32_e32 v212, v209, v210
	v_fma_f32 v213, -v207, v212, v209
	v_fmac_f32_e32 v212, v213, v210
	v_fma_f32 v205, -v207, v212, v209
	v_fma_f32 v205, v205, v210, v212
	v_div_fixup_f32 v207, v205, v207, v209
	v_rcp_f32_e32 v209, v206
	v_pk_mul_f32 v[106:107], v[62:63], v[62:63]
	v_fma_f32 v210, -v206, v209, 1.0
	v_fmac_f32_e32 v209, v210, v209
	v_mul_f32_e32 v211, v208, v209
	v_fma_f32 v212, -v206, v211, v208
	v_fmac_f32_e32 v211, v212, v209
	v_fma_f32 v205, -v206, v211, v208
	v_pk_add_f32 v[212:213], v[48:49], v[74:75]
	v_fma_f32 v205, v205, v209, v211
	v_pk_mul_f32 v[74:75], v[212:213], v[212:213]
	v_div_fixup_f32 v206, v205, v206, v208
	v_pk_add_f32 v[208:209], v[50:51], v[102:103]
	v_add_f32_e32 v74, v74, v95
	v_pk_mul_f32 v[210:211], v[208:209], v[208:209]
	v_add_f32_e32 v74, v75, v74
	v_add_f32_e32 v74, v210, v74
	v_add_f32_e32 v74, v211, v74
	v_pk_add_f32 v[102:103], v[54:55], v[110:111]
	v_add_f32_e32 v74, v214, v74
	v_pk_mul_f32 v[110:111], v[102:103], v[102:103]
	v_add_f32_e32 v74, v215, v74
	v_add_f32_e32 v74, v110, v74
	v_add_f32_e32 v74, v111, v74
	v_add_f32_e32 v74, v104, v74
	v_add_f32_e32 v74, v105, v74
	v_add_f32_e32 v74, v106, v74
	v_add_f32_e32 v74, v107, v74
	ds_bpermute_b32 v75, v97, v74
	s_waitcnt lgkmcnt(0)
; DI size_t kblk(int row, int col, int nrows) { return ((size_t)(col >> 5) * nrows + row) * 32 + (col & 31); }
; DI unsigned pk2(float a, float b) { hwf32x2 f = {a, b}; hwbf16x2 r = __builtin_convertvector(f, hwbf16x2); return __builtin_bit_cast(unsigned, r); }
; DI float sigmoidf_(float z) { return 1.f / (1.f + __expf(-z)); }
; DI float siluf_(float z) { return z / (1.f + __expf(-z)); }
; template <int MX, bool OUT>
; DI void rec_chunk(const Params& p, int l, int b, int h, int dir, int T0, unsigned char* smem, f32x4 (&St)[4], float& nst, float& dtot, int tid, const RecRaw& raw) {
;     ...
;       ss += __shfl_xor(ss, 16);
;       ss += __shfl_xor(ss, 32);
;       const float rstd = rsqrtf(ss * (1.f / 64.f) + EPS);
;       const float* gvec = (MX ? p.ml_g : p.hg_g) + l * 64;
; #pragma unroll
;       for (int a = 0; a < 4; ++a) {
;         const int v0 = 16 * a + 4 * g;
;         const uint2 gt = *(const uint2*)(prow + GATE + cb + v0);
;         const float4 gg = *(const float4*)(gvec + v0);
;         float y0 = O[a][0] * rstd * gg.x * siluf_(__uint_as_float(gt.x << 16));
;         float y1 = O[a][1] * rstd * gg.y * siluf_(__uint_as_float(gt.x & 0xffff0000u));
;         float y2 = O[a][2] * rstd * gg.z * siluf_(__uint_as_float(gt.y << 16));
;         float y3 = O[a][3] * rstd * gg.w * siluf_(__uint_as_float(gt.y & 0xffff0000u));
;         if (MX == 1) {
;           const uint2 og = *(const uint2*)(prow + D_OG + h * 64 + v0);
;           y0 *= sigmoidf_(__uint_as_float(og.x << 16)); y1 *= sigmoidf_(__uint_as_float(og.x & 0xffff0000u));
;           y2 *= sigmoidf_(__uint_as_float(og.y << 16)); y3 *= sigmoidf_(__uint_as_float(og.y & 0xffff0000u));
;         }
;         *(uint2*)(MIX + kblk((int)orow, cb + v0, ROWS)) = make_uint2(pk2(y0, y1), pk2(y2, y3));
	v_add_f32_e32 v74, v74, v75
	ds_bpermute_b32 v69, v69, v74
	s_waitcnt lgkmcnt(0)
	v_add_f32_e32 v69, v74, v69
	v_fmamk_f32 v69, v69, 0x3c800000, v162
	v_cmp_gt_f32_e32 vcc, s38, v69
	v_mul_f32_e32 v74, 0x4b800000, v69
	s_nop 0
	v_cndmask_b32_e32 v69, v69, v74, vcc
	v_rsq_f32_e32 v69, v69
	s_nop 0
	v_mul_f32_e32 v74, 0x45800000, v69
	v_cndmask_b32_e32 v74, v69, v74, vcc
	v_pk_mul_f32 v[104:105], v[116:117], v[74:75] op_sel_hi:[1,0]
	s_nop 0
	v_pk_mul_f32 v[56:57], v[56:57], v[104:105]
	v_pk_mul_f32 v[104:105], v[112:113], v[74:75] op_sel_hi:[1,0]
	v_pk_mul_f32 v[56:57], v[118:119], v[56:57]
	v_pk_mul_f32 v[58:59], v[58:59], v[104:105]
	v_cvt_pk_bf16_f32 v56, v56, v57
	v_pk_mul_f32 v[58:59], v[206:207], v[58:59]
	s_nop 0
	v_cvt_pk_bf16_f32 v57, v58, v59
	global_store_dwordx2 v[100:101], v[56:57], off
	global_load_dwordx2 v[100:101], v[72:73], off offset:32
	s_nop 0
	global_load_dwordx4 v[56:59], v[88:89], off offset:64
	s_waitcnt vmcnt(0) lgkmcnt(0)
	v_lshlrev_b32_e32 v69, 16, v100
	v_and_b32_e32 v75, 0xffff0000, v100
	v_mul_f32_e32 v95, 0xbfb8aa3b, v69
	v_exp_f32_e32 v104, v95
	v_mul_f32_e32 v95, 0xbfb8aa3b, v75
	v_exp_f32_e32 v105, v95
	v_pk_mul_f32 v[106:107], v[212:213], v[74:75] op_sel_hi:[1,0]
	v_pk_add_f32 v[104:105], v[104:105], 1.0 op_sel_hi:[1,0]
	s_nop 0
	v_rcp_f32_e32 v97, v105
	v_pk_mul_f32 v[56:57], v[56:57], v[106:107]
	v_fma_f32 v100, -v105, v97, 1.0
	v_fmac_f32_e32 v97, v100, v97
	v_mul_f32_e32 v106, v75, v97
	v_fma_f32 v107, -v105, v106, v75
	v_fmac_f32_e32 v106, v107, v97
	v_fma_f32 v95, -v105, v106, v75
	v_fma_f32 v95, v95, v97, v106
	v_div_fixup_f32 v105, v95, v105, v75
	v_rcp_f32_e32 v95, v104
	s_nop 0
	v_fma_f32 v97, -v104, v95, 1.0
	v_fmac_f32_e32 v95, v97, v95
	v_mul_f32_e32 v100, v69, v95
	v_fma_f32 v106, -v104, v100, v69
	v_fmac_f32_e32 v100, v106, v95
	v_fma_f32 v75, -v104, v100, v69
	v_fma_f32 v75, v75, v95, v100
	v_div_fixup_f32 v104, v75, v104, v69
	v_lshlrev_b32_e32 v69, 16, v101
	v_and_b32_e32 v75, 0xffff0000, v101
	v_mul_f32_e32 v95, 0xbfb8aa3b, v69
	v_exp_f32_e32 v100, v95
	v_mul_f32_e32 v95, 0xbfb8aa3b, v75
	v_exp_f32_e32 v101, v95
	v_pk_mul_f32 v[56:57], v[104:105], v[56:57]
	v_pk_mul_f32 v[104:105], v[208:209], v[74:75] op_sel_hi:[1,0]
	v_cvt_pk_bf16_f32 v56, v56, v57
	v_pk_add_f32 v[100:101], v[100:101], 1.0 op_sel_hi:[1,0]
	v_pk_mul_f32 v[58:59], v[58:59], v[104:105]
	v_rcp_f32_e32 v97, v101
	s_nop 0
	v_fma_f32 v104, -v101, v97, 1.0
	v_fmac_f32_e32 v97, v104, v97
	v_mul_f32_e32 v105, v75, v97
	v_fma_f32 v106, -v101, v105, v75
	v_fmac_f32_e32 v105, v106, v97
	v_fma_f32 v95, -v101, v105, v75
	v_fma_f32 v95, v95, v97, v105
	v_div_fixup_f32 v101, v95, v101, v75
	v_rcp_f32_e32 v95, v100
	s_nop 0
	v_fma_f32 v97, -v100, v95, 1.0
	v_fmac_f32_e32 v95, v97, v95
	v_mul_f32_e32 v104, v69, v95
	v_fma_f32 v105, -v100, v104, v69
	v_fmac_f32_e32 v104, v105, v95
	v_fma_f32 v75, -v100, v104, v69
	v_fma_f32 v75, v75, v95, v104
	v_div_fixup_f32 v100, v75, v100, v69
	v_pk_mul_f32 v[58:59], v[100:101], v[58:59]
	s_nop 0
	v_cvt_pk_bf16_f32 v57, v58, v59
	global_store_dwordx2 v[70:71], v[56:57], off
	global_load_dwordx2 v[70:71], v[72:73], off offset:64
	s_nop 0
	global_load_dwordx4 v[56:59], v[88:89], off offset:128
	s_waitcnt vmcnt(0) lgkmcnt(0)
; DI size_t kblk(int row, int col, int nrows) { return ((size_t)(col >> 5) * nrows + row) * 32 + (col & 31); }
; DI float bf2f(bf16_t v) { return __uint_as_float(((unsigned)v) << 16); }
; DI unsigned pk2(float a, float b) { hwf32x2 f = {a, b}; hwbf16x2 r = __builtin_convertvector(f, hwbf16x2); return __builtin_bit_cast(unsigned, r); }
; DI float siluf_(float z) { return z / (1.f + __expf(-z)); }
; template <int MODE>
; DI void attn_mfma(const Params& p, int l, int b, int hd, int qb, unsigned char* smem) {
;     ...
; #pragma unroll
;       for (int vt = 0; vt < 2; ++vt)
; #pragma unroll
;         for (int g4 = 0; g4 < 4; ++g4) {
;           const int v0 = vt * 32 + 8 * g4 + 4 * h2;
;           const ushort4 gt = *(const ushort4*)(P + qrow * PW + GATE + hd * 64 + v0);
;           const float4 gg = *(const float4*)(p.diff_g + l * 64 + v0);
;           uint2 o;
;           o.x = pk2(O[vt][4 * g4 + 0] * rstd * gg.x * siluf_(bf2f(gt.x)), O[vt][4 * g4 + 1] * rstd * gg.y * siluf_(bf2f(gt.y)));
;           o.y = pk2(O[vt][4 * g4 + 2] * rstd * gg.z * siluf_(bf2f(gt.z)), O[vt][4 * g4 + 3] * rstd * gg.w * siluf_(bf2f(gt.w)));
;           *(uint2*)(MIX + kblk((int)qrow, hd * 64 + v0, ROWS)) = o;
;         }
	v_lshlrev_b32_e32 v69, 16, v70
	v_and_b32_e32 v70, 0xffff0000, v70
	v_mul_f32_e32 v75, 0xbfb8aa3b, v69
	v_exp_f32_e32 v100, v75
	v_pk_mul_f32 v[104:105], v[108:109], v[74:75] op_sel_hi:[1,0]
	v_mul_f32_e32 v75, 0xbfb8aa3b, v70
	v_exp_f32_e32 v101, v75
	v_pk_mul_f32 v[56:57], v[104:105], v[56:57]
	v_pk_add_f32 v[100:101], v[100:101], 1.0 op_sel_hi:[1,0]
	s_nop 0
	v_rcp_f32_e32 v95, v101
	s_nop 0
	v_fma_f32 v97, -v101, v95, 1.0
	v_fmac_f32_e32 v95, v97, v95
	v_mul_f32_e32 v104, v70, v95
	v_fma_f32 v105, -v101, v104, v70
	v_fmac_f32_e32 v104, v105, v95
	v_fma_f32 v75, -v101, v104, v70
	v_fma_f32 v75, v75, v95, v104
	v_div_fixup_f32 v101, v75, v101, v70
	v_rcp_f32_e32 v75, v100
	s_nop 0
	v_fma_f32 v95, -v100, v75, 1.0
	v_fmac_f32_e32 v75, v95, v75
	v_mul_f32_e32 v97, v69, v75
	v_fma_f32 v104, -v100, v97, v69
	v_fmac_f32_e32 v97, v104, v75
	v_fma_f32 v70, -v100, v97, v69
	v_fma_f32 v70, v70, v75, v97
	v_div_fixup_f32 v100, v70, v100, v69
	v_lshlrev_b32_e32 v69, 16, v71
	v_and_b32_e32 v75, 0xffff0000, v71
	v_mul_f32_e32 v70, 0xbfb8aa3b, v69
	v_mul_f32_e32 v71, 0xbfb8aa3b, v75
	v_exp_f32_e32 v70, v70
	v_exp_f32_e32 v71, v71
	v_pk_mul_f32 v[56:57], v[56:57], v[100:101]
	v_pk_mul_f32 v[100:101], v[102:103], v[74:75] op_sel_hi:[1,0]
	v_cvt_pk_bf16_f32 v56, v56, v57
	v_pk_add_f32 v[70:71], v[70:71], 1.0 op_sel_hi:[1,0]
	v_pk_mul_f32 v[58:59], v[100:101], v[58:59]
	v_rcp_f32_e32 v97, v71
	s_nop 0
	v_fma_f32 v100, -v71, v97, 1.0
	v_fmac_f32_e32 v97, v100, v97
	v_mul_f32_e32 v101, v75, v97
	v_fma_f32 v102, -v71, v101, v75
	v_fmac_f32_e32 v101, v102, v97
	v_fma_f32 v95, -v71, v101, v75
	v_fma_f32 v95, v95, v97, v101
	v_div_fixup_f32 v71, v95, v71, v75
	v_rcp_f32_e32 v95, v70
	s_nop 0
	v_fma_f32 v97, -v70, v95, 1.0
	v_fmac_f32_e32 v95, v97, v95
	v_mul_f32_e32 v100, v69, v95
	v_fma_f32 v101, -v70, v100, v69
	v_fmac_f32_e32 v100, v101, v95
	v_fma_f32 v75, -v70, v100, v69
	v_fma_f32 v75, v75, v95, v100
	v_div_fixup_f32 v70, v75, v70, v69
	v_pk_mul_f32 v[58:59], v[58:59], v[70:71]
	v_pk_mul_f32 v[64:65], v[64:65], v[74:75] op_sel_hi:[1,0]
	v_cvt_pk_bf16_f32 v57, v58, v59
	global_store_dwordx2 v[66:67], v[56:57], off
	global_load_dwordx2 v[66:67], v[72:73], off offset:96
	v_mov_b32_e32 v97, v161
	global_load_dwordx4 v[56:59], v[88:89], off offset:192
	s_waitcnt vmcnt(0) lgkmcnt(0)
	v_lshlrev_b32_e32 v69, 16, v66
	v_and_b32_e32 v66, 0xffff0000, v66
	v_mul_f32_e32 v70, 0xbfb8aa3b, v69
	v_pk_mul_f32 v[56:57], v[64:65], v[56:57]
	v_mul_f32_e32 v64, 0xbfb8aa3b, v66
	v_exp_f32_e32 v70, v70
	v_exp_f32_e32 v71, v64
	s_nop 0
	v_pk_add_f32 v[64:65], v[70:71], 1.0 op_sel_hi:[1,0]
	s_nop 0
	v_rcp_f32_e32 v71, v65
	s_nop 0
	v_fma_f32 v72, -v65, v71, 1.0
	v_fmac_f32_e32 v71, v72, v71
	v_mul_f32_e32 v73, v66, v71
	v_fma_f32 v75, -v65, v73, v66
	v_fmac_f32_e32 v73, v75, v71
	v_fma_f32 v70, -v65, v73, v66
	v_fma_f32 v70, v70, v71, v73
	v_div_fixup_f32 v65, v70, v65, v66
	v_rcp_f32_e32 v70, v64
	v_pk_mul_f32 v[62:63], v[62:63], v[74:75] op_sel_hi:[1,0]
	v_fma_f32 v71, -v64, v70, 1.0
	v_fmac_f32_e32 v70, v71, v70
	v_mul_f32_e32 v72, v69, v70
	v_fma_f32 v73, -v64, v72, v69
	v_fmac_f32_e32 v72, v73, v70
	v_fma_f32 v66, -v64, v72, v69
	v_fma_f32 v66, v66, v70, v72
	v_div_fixup_f32 v64, v66, v64, v69
	v_lshlrev_b32_e32 v66, 16, v67
	v_and_b32_e32 v67, 0xffff0000, v67
	v_pk_mul_f32 v[64:65], v[56:57], v[64:65]
	v_mul_f32_e32 v56, 0xbfb8aa3b, v66
	v_mul_f32_e32 v57, 0xbfb8aa3b, v67
	v_exp_f32_e32 v56, v56
	v_exp_f32_e32 v57, v57
	v_pk_mul_f32 v[58:59], v[62:63], v[58:59]
	v_pk_add_f32 v[56:57], v[56:57], 1.0 op_sel_hi:[1,0]
	s_nop 0
	v_rcp_f32_e32 v63, v57
	s_nop 0
	v_fma_f32 v69, -v57, v63, 1.0
	v_fmac_f32_e32 v63, v69, v63
	v_mul_f32_e32 v70, v67, v63
	v_fma_f32 v71, -v57, v70, v67
	v_fmac_f32_e32 v70, v71, v63
	v_fma_f32 v62, -v57, v70, v67
	v_fma_f32 v62, v62, v63, v70
	v_div_fixup_f32 v57, v62, v57, v67
	v_rcp_f32_e32 v63, v56
	s_mov_b64 s[26:27], 0
	v_fma_f32 v67, -v56, v63, 1.0
	v_fmac_f32_e32 v63, v67, v63
	v_mul_f32_e32 v69, v66, v63
	v_fma_f32 v70, -v56, v69, v66
	v_fmac_f32_e32 v69, v70, v63
	v_fma_f32 v62, -v56, v69, v66
	v_fma_f32 v62, v62, v63, v69
	v_div_fixup_f32 v56, v62, v56, v66
	v_pk_mul_f32 v[56:57], v[58:59], v[56:57]
	v_cvt_pk_bf16_f32 v62, v64, v65
	v_lshl_add_u64 v[58:59], v[60:61], 0, v[96:97]
	global_store_dword v[58:59], v62, off
